# v29 + attention FAST units: P fed to PV MFMAs in lane-native key order with V tile rows placed in matching order (bits 2,3 of key index swapped in the DMA source row); 8 v_permlane32_swap per step rem
# speedup vs baseline: 1.0080x; 1.0067x over previous
.LBB0_891:
	s_lshr_b32 s16, s19, 6
	s_and_b64 s[12:13], s[12:13], exec
	s_cselect_b32 s12, s19, s16
	s_and_b32 s17, s12, 7
	s_mul_i32 s12, s9, 0xc00
	s_mul_hi_u32 s13, s8, 0xc00
	s_add_i32 s13, s13, s12
	s_mul_i32 s12, s8, 0xc00
	v_readlane_b32 s20, v242, 21
	v_readlane_b32 s21, v242, 22
	s_add_u32 s12, s20, s12
	s_addc_u32 s13, s21, s13
	s_mul_i32 s16, s17, 0x180
	s_add_u32 s28, s12, s16
	s_addc_u32 s29, s13, 0
	s_mul_i32 s12, s1, 0xc00
	s_mul_hi_u32 s13, s0, 0xc00
	s_add_i32 s13, s13, s12
	s_mul_i32 s12, s0, 0xc00
	s_add_u32 s12, s27, s12
	s_addc_u32 s13, s30, s13
	s_add_u32 s12, s12, s16
	s_mul_i32 s20, s15, 0x3000000
	s_mul_hi_u32 s21, s14, 0x3000000
	s_addc_u32 s13, s13, 0
	s_add_i32 s21, s21, s20
	s_mul_i32 s20, s14, 0x3000000
	s_add_u32 s20, s27, s20
	s_addc_u32 s21, s30, s21
	s_add_u32 s22, s20, s16
	s_addc_u32 s23, s21, 0
	s_lshl_b64 s[0:1], s[0:1], 12
	s_add_u32 s0, s31, s0
	s_addc_u32 s1, s34, s1
	s_lshl_b32 s16, s17, 9
	s_add_u32 s0, s0, s16
	s_addc_u32 s1, s1, 0
	s_add_u32 s24, s0, 0x100
	s_addc_u32 s25, s1, 0
	s_lshl_b64 s[14:15], s[14:15], 26
	s_add_u32 s14, s31, s14
	s_addc_u32 s15, s34, s15
	s_add_u32 s14, s14, s16
	s_addc_u32 s15, s15, 0
	s_add_u32 s33, s14, 0x100
	v_readfirstlane_b32 s68, v0
	s_addc_u32 s35, s15, 0
	s_lshr_b32 s20, s68, 6
	s_lshl_b32 s16, s20, 5
	v_or_b32_e32 v4, s16, v1
	v_mov_b64_e32 v[2:3], s[28:29]
	s_movk_i32 s14, 0xc00
	v_mad_u64_u32 v[2:3], s[14:15], v4, s14, v[2:3]
	s_andn2_b32 s68, s68, 63
	v_lshl_add_u64 v[2:3], v[2:3], 0, v[148:149]
	global_load_dwordx4 v[142:145], v[2:3], off
	global_load_dwordx4 v[138:141], v[2:3], off offset:32
	global_load_dwordx4 v[134:137], v[2:3], off offset:64
	global_load_dwordx4 v[130:133], v[2:3], off offset:96
	global_load_dwordx4 v[126:129], v[2:3], off offset:128
	global_load_dwordx4 v[122:125], v[2:3], off offset:160
	global_load_dwordx4 v[118:121], v[2:3], off offset:192
	global_load_dwordx4 v[114:117], v[2:3], off offset:224
	global_load_dwordx4 v[110:113], v[2:3], off offset:256
	global_load_dwordx4 v[106:109], v[2:3], off offset:288
	global_load_dwordx4 v[102:105], v[2:3], off offset:320
	global_load_dwordx4 v[98:101], v[2:3], off offset:352
	v_or_b32_e32 v2, s68, v166
	v_mul_hi_i32 v3, v2, s11
	v_lshrrev_b32_e32 v4, 31, v3
	v_ashrrev_i32_e32 v3, 2, v3
	v_add_u32_e32 v3, v3, v4
	v_mul_lo_u32 v4, v3, 24
	v_sub_u32_e32 v4, v2, v4
	v_mul_lo_u32 v5, v3, s18
	v_lshrrev_b32_e32 v3, 1, v3
	v_bitop3_b32 v3, v3, v4, 7 bitop3:0x6c
	v_lshl_add_u32 v160, v3, 3, v5
	v_add_u32_e32 v3, 0x200, v2
	v_mul_hi_i32 v4, v3, s11
	v_lshrrev_b32_e32 v5, 31, v4
	v_ashrrev_i32_e32 v4, 2, v4
	v_add_u32_e32 v4, v4, v5
	v_mul_lo_u32 v5, v4, 24
	v_sub_u32_e32 v3, v3, v5
	v_mul_lo_u32 v5, v4, s18
	v_lshrrev_b32_e32 v4, 1, v4
	v_bitop3_b32 v3, v4, v3, 7 bitop3:0x6c
	v_lshl_add_u32 v162, v3, 3, v5
	v_add_u32_e32 v3, 0x400, v2
	v_mul_hi_i32 v4, v3, s11
	v_lshrrev_b32_e32 v5, 31, v4
	v_ashrrev_i32_e32 v4, 2, v4
	v_add_u32_e32 v4, v4, v5
	s_ashr_i32 s14, s68, 4
	v_mul_lo_u32 v5, v4, 24
	s_and_b32 s15, s14, 0x1ffff0
	s_lshr_b32 s14, s14, 1
	v_sub_u32_e32 v3, v3, v5
	v_mul_lo_u32 v5, v4, s18
	v_lshrrev_b32_e32 v4, 1, v4
	s_and_b32 s14, s14, 4
	v_bitop3_b32 v3, v4, v3, 7 bitop3:0x6c
	s_or_b32 s14, s15, s14
	v_lshl_add_u32 v170, v3, 3, v5
	v_or_b32_e32 v3, s14, v169
	v_lshrrev_b32_e32 v173, 1, v3
	v_xor_b32_e32 v173, v173, v3
	v_and_b32_e32 v173, 4, v173
	v_lshl_or_b32 v173, v173, 1, v173
	v_xor_b32_e32 v3, v3, v173
	s_add_i32 s14, s68, 0x200
	s_ashr_i32 s14, s14, 4
	s_and_b32 s15, s14, 0x1ffff0
	s_lshr_b32 s14, s14, 1
	s_and_b32 s14, s14, 4
	v_and_or_b32 v2, v2, s10, v165
	s_or_b32 s14, s15, s14
	v_lshl_or_b32 v172, v3, 11, v2
	v_or_b32_e32 v3, s14, v169
	v_lshrrev_b32_e32 v175, 1, v3
	v_xor_b32_e32 v175, v175, v3
	v_and_b32_e32 v175, 4, v175
	v_lshl_or_b32 v175, v175, 1, v175
	v_xor_b32_e32 v3, v3, v175
	s_lshl_b32 s14, s20, 10
	s_add_i32 s69, s14, 0
	v_ashrrev_i32_e32 v161, 31, v160
	v_lshl_or_b32 v174, v3, 11, v2
	s_add_i32 m0, s69, 0x8000
	v_lshl_add_u64 v[2:3], v[160:161], 1, s[12:13]
	v_ashrrev_i32_e32 v163, 31, v162
	global_load_lds_dwordx4 v[2:3], off
	v_lshl_add_u64 v[2:3], v[162:163], 1, s[12:13]
	s_add_i32 m0, s69, 0xa000
	v_ashrrev_i32_e32 v171, 31, v170
	global_load_lds_dwordx4 v[2:3], off
	v_lshl_add_u64 v[2:3], v[170:171], 1, s[12:13]
	s_add_i32 m0, s69, 0xc000
	v_ashrrev_i32_e32 v173, 31, v172
	global_load_lds_dwordx4 v[2:3], off
	v_lshl_add_u64 v[2:3], v[172:173], 1, s[0:1]
	v_lshl_add_u64 v[2:3], v[2:3], 0, s[6:7]
	s_mov_b32 m0, s69
	v_ashrrev_i32_e32 v175, 31, v174
	global_load_lds_dwordx4 v[2:3], off
	v_lshl_add_u64 v[2:3], v[174:175], 1, s[0:1]
	v_lshl_add_u64 v[2:3], v[2:3], 0, s[6:7]
	s_add_i32 m0, s69, 0x2000
	v_mov_b32_e32 v151, 0
	global_load_lds_dwordx4 v[2:3], off
	s_waitcnt vmcnt(0)
	s_add_i32 s0, s4, 1
	s_mov_b32 s4, 0
	s_mov_b64 s[14:15], 64
	v_mov_b32_e32 v2, 0
	v_mov_b32_e32 v3, v151
	v_mov_b32_e32 v4, v151
	v_mov_b32_e32 v5, v151
	v_mov_b32_e32 v6, v151
	v_mov_b32_e32 v7, v151
	v_mov_b32_e32 v8, v151
	v_mov_b32_e32 v9, v151
	v_mov_b32_e32 v10, v151
	v_mov_b32_e32 v11, v151
	v_mov_b32_e32 v12, v151
	v_mov_b32_e32 v13, v151
	v_mov_b32_e32 v14, v151
	v_mov_b32_e32 v15, v151
	v_mov_b32_e32 v16, v151
	v_mov_b32_e32 v17, v151
	v_mov_b32_e32 v18, 0
	v_mov_b32_e32 v19, v151
	v_mov_b32_e32 v20, v151
	v_mov_b32_e32 v21, v151
	v_mov_b32_e32 v22, v151
	v_mov_b32_e32 v23, v151
	v_mov_b32_e32 v24, v151
	v_mov_b32_e32 v25, v151
	v_mov_b32_e32 v26, v151
	v_mov_b32_e32 v27, v151
	v_mov_b32_e32 v28, v151
	v_mov_b32_e32 v29, v151
	v_mov_b32_e32 v30, v151
	v_mov_b32_e32 v31, v151
	v_mov_b32_e32 v32, v151
	v_mov_b32_e32 v33, v151
	v_mov_b32_e32 v34, 0
	v_mov_b32_e32 v35, v151
	v_mov_b32_e32 v36, v151
	v_mov_b32_e32 v37, v151
	v_mov_b32_e32 v38, v151
	v_mov_b32_e32 v39, v151
	v_mov_b32_e32 v40, v151
	v_mov_b32_e32 v41, v151
	v_mov_b32_e32 v42, v151
	v_mov_b32_e32 v43, v151
	v_mov_b32_e32 v44, v151
	v_mov_b32_e32 v45, v151
	v_mov_b32_e32 v46, v151
	v_mov_b32_e32 v47, v151
	v_mov_b32_e32 v48, v151
	v_mov_b32_e32 v49, v151
	v_mov_b32_e32 v50, 0
	v_mov_b32_e32 v51, v151
	v_mov_b32_e32 v52, v151
	v_mov_b32_e32 v53, v151
	v_mov_b32_e32 v54, v151
	v_mov_b32_e32 v55, v151
	v_mov_b32_e32 v56, v151
	v_mov_b32_e32 v57, v151
	v_mov_b32_e32 v58, v151
	v_mov_b32_e32 v59, v151
	v_mov_b32_e32 v60, v151
	v_mov_b32_e32 v61, v151
	v_mov_b32_e32 v62, v151
	v_mov_b32_e32 v63, v151
	v_mov_b32_e32 v64, v151
	v_mov_b32_e32 v65, v151
	s_waitcnt vmcnt(0) lgkmcnt(0)
	s_barrier
.LBB0_892:
	v_sub_co_u32_e64 v66, s[28:29], s4, 3
	s_and_b32 s21, s4, 1
	s_add_i32 s1, s4, 1
	v_readfirstlane_b32 s4, v66
	s_lshl_b64 s[36:37], s[4:5], 6
	s_and_b64 s[38:39], s[28:29], exec
	s_cselect_b32 s37, s15, s37
	s_cselect_b32 s36, s14, s36
	s_mul_i32 s39, s37, 0xc00
	s_mul_hi_u32 s40, s36, 0xc00
	s_cselect_b32 s4, s13, s23
	s_cselect_b32 s38, s12, s22
	s_add_i32 s40, s40, s39
	s_mul_i32 s39, s36, 0xc00
	s_add_u32 s38, s38, s39
	s_addc_u32 s39, s4, s40
	s_xor_b32 s4, s21, 1
	s_mulk_i32 s4, 0x6000
	s_add_i32 s4, s69, s4
	s_add_i32 m0, s4, 0x8000
	v_lshl_add_u64 v[66:67], v[160:161], 1, s[38:39]
	global_load_lds_dwordx4 v[66:67], off
	v_lshl_add_u64 v[66:67], v[162:163], 1, s[38:39]
	s_add_i32 m0, s4, 0xa000
	s_lshl_b64 s[36:37], s[36:37], 12
	global_load_lds_dwordx4 v[66:67], off
	s_add_i32 m0, s4, 0xc000
	s_and_b64 s[28:29], s[28:29], exec
	s_cselect_b32 s28, s24, s33
	s_cselect_b32 s4, s25, s35
	s_add_u32 s28, s28, s36
	s_addc_u32 s29, s4, s37
	s_lshl_b32 s4, s21, 14
	s_xor_b32 s36, s4, 0x4000
	v_lshl_add_u64 v[66:67], v[170:171], 1, s[38:39]
	s_add_i32 s36, s69, s36
	global_load_lds_dwordx4 v[66:67], off
	v_lshl_add_u64 v[66:67], v[172:173], 1, s[28:29]
	s_mov_b32 m0, s36
	s_mulk_i32 s21, 0x6000
	global_load_lds_dwordx4 v[66:67], off
	v_lshl_add_u64 v[66:67], v[174:175], 1, s[28:29]
	s_add_i32 m0, s36, 0x2000
	s_nop 0
	global_load_lds_dwordx4 v[66:67], off
	v_add_u32_e32 v70, s21, v179
	v_add_u32_e32 v71, v70, v178
	ds_read_b128 v[66:69], v71 offset:32768
	v_add_u32_e32 v153, v70, v180
	v_add_u32_e32 v155, v70, v181
	v_add_u32_e32 v157, v70, v182
	v_add_u32_e32 v159, v70, v183
	v_add_u32_e32 v193, v70, v184
	v_add_u32_e32 v198, v70, v185
	v_add_u32_e32 v199, v70, v186
	v_add_u32_e32 v200, v70, v187
	s_waitcnt lgkmcnt(0)
	v_mfma_f32_32x32x16_bf16 v[82:97], v[66:69], v[142:145], 0
	ds_read_b128 v[66:69], v153 offset:32768
	v_add_u32_e32 v201, v70, v188
	v_add_u32_e32 v202, v70, v189
	v_add_u32_e32 v203, v70, v190
	s_waitcnt lgkmcnt(0)
	v_mfma_f32_32x32x16_bf16 v[82:97], v[66:69], v[138:141], v[82:97]
	ds_read_b128 v[66:69], v155 offset:32768
	s_waitcnt lgkmcnt(0)
	v_mfma_f32_32x32x16_bf16 v[82:97], v[66:69], v[134:137], v[82:97]
	ds_read_b128 v[66:69], v157 offset:32768
	s_waitcnt lgkmcnt(0)
	v_mfma_f32_32x32x16_bf16 v[82:97], v[66:69], v[130:133], v[82:97]
	ds_read_b128 v[66:69], v159 offset:32768
	s_waitcnt lgkmcnt(0)
	v_mfma_f32_32x32x16_bf16 v[82:97], v[66:69], v[126:129], v[82:97]
	ds_read_b128 v[66:69], v193 offset:32768
	s_waitcnt lgkmcnt(0)
	v_mfma_f32_32x32x16_bf16 v[82:97], v[66:69], v[122:125], v[82:97]
	ds_read_b128 v[66:69], v198 offset:32768
	s_waitcnt lgkmcnt(0)
	v_mfma_f32_32x32x16_bf16 v[82:97], v[66:69], v[118:121], v[82:97]
	ds_read_b128 v[66:69], v199 offset:32768
	s_waitcnt lgkmcnt(0)
	v_mfma_f32_32x32x16_bf16 v[82:97], v[66:69], v[114:117], v[82:97]
	ds_read_b128 v[66:69], v200 offset:32768
	s_waitcnt lgkmcnt(0)
	v_mfma_f32_32x32x16_bf16 v[82:97], v[66:69], v[110:113], v[82:97]
	ds_read_b128 v[66:69], v201 offset:32768
	s_waitcnt lgkmcnt(0)
	v_mfma_f32_32x32x16_bf16 v[82:97], v[66:69], v[106:109], v[82:97]
	ds_read_b128 v[66:69], v202 offset:32768
	s_waitcnt lgkmcnt(0)
	v_mfma_f32_32x32x16_bf16 v[82:97], v[66:69], v[102:105], v[82:97]
	ds_read_b128 v[66:69], v203 offset:32768
	s_waitcnt lgkmcnt(0)
	v_mfma_f32_32x32x16_bf16 v[82:97], v[66:69], v[98:101], v[82:97]
	ds_read_b128 v[66:69], v71 offset:45056
	ds_read_b128 v[194:197], v153 offset:45056
	s_nop 9
	v_exp_f32_e32 v204, v88
	v_exp_f32_e32 v205, v89
	v_exp_f32_e32 v206, v90
	v_exp_f32_e32 v207, v91
	v_exp_f32_e32 v208, v92
	v_exp_f32_e32 v209, v93
	v_exp_f32_e32 v210, v94
	s_waitcnt lgkmcnt(0)
	v_mfma_f32_32x32x16_bf16 v[66:81], v[66:69], v[142:145], 0
	v_exp_f32_e32 v211, v95
	v_exp_f32_e32 v212, v96
	v_exp_f32_e32 v213, v97
	v_add_u32_e32 v153, s4, v176
	v_cvt_pk_bf16_f32 v88, v210, v211
	v_cvt_pk_bf16_f32 v89, v212, v213
	v_mfma_f32_32x32x16_bf16 v[66:81], v[194:197], v[138:141], v[66:81]
	ds_read_b128 v[194:197], v155 offset:45056
	v_exp_f32_e32 v155, v82
	s_waitcnt lgkmcnt(0)
	v_mfma_f32_32x32x16_bf16 v[66:81], v[194:197], v[134:137], v[66:81]
	ds_read_b128 v[194:197], v157 offset:45056
	v_exp_f32_e32 v157, v83
	s_nop 0
	v_cvt_pk_bf16_f32 v82, v155, v157
	s_waitcnt lgkmcnt(0)
	v_mfma_f32_32x32x16_bf16 v[66:81], v[194:197], v[130:133], v[66:81]
	ds_read_b128 v[194:197], v159 offset:45056
	v_exp_f32_e32 v159, v84
	s_waitcnt lgkmcnt(0)
	v_mfma_f32_32x32x16_bf16 v[66:81], v[194:197], v[126:129], v[66:81]
	ds_read_b128 v[194:197], v193 offset:45056
	v_exp_f32_e32 v193, v85
	v_cvt_pk_bf16_f32 v85, v204, v205
	v_cvt_pk_bf16_f32 v83, v159, v193
	s_nop 1
	s_waitcnt lgkmcnt(0)
	v_mfma_f32_32x32x16_bf16 v[66:81], v[194:197], v[122:125], v[66:81]
	ds_read_b128 v[194:197], v198 offset:45056
	s_waitcnt lgkmcnt(0)
	v_mfma_f32_32x32x16_bf16 v[66:81], v[194:197], v[118:121], v[66:81]
	ds_read_b128 v[194:197], v199 offset:45056
	s_waitcnt lgkmcnt(0)
	v_mfma_f32_32x32x16_bf16 v[66:81], v[194:197], v[114:117], v[66:81]
	ds_read_b128 v[194:197], v200 offset:45056
	s_waitcnt lgkmcnt(0)
	v_mfma_f32_32x32x16_bf16 v[66:81], v[194:197], v[110:113], v[66:81]
	ds_read_b128 v[194:197], v201 offset:45056
	s_waitcnt lgkmcnt(0)
	v_mfma_f32_32x32x16_bf16 v[66:81], v[194:197], v[106:109], v[66:81]
	ds_read_b128 v[194:197], v202 offset:45056
	v_exp_f32_e32 v202, v86
	v_cvt_pk_bf16_f32 v86, v206, v207
	s_nop 1
	s_waitcnt lgkmcnt(0)
	v_mfma_f32_32x32x16_bf16 v[66:81], v[194:197], v[102:105], v[66:81]
	ds_read_b128 v[194:197], v203 offset:45056
	v_exp_f32_e32 v203, v87
	v_cvt_pk_bf16_f32 v87, v208, v209
	s_nop 1
	v_cvt_pk_bf16_f32 v84, v202, v203
	s_nop 1
	s_waitcnt lgkmcnt(0)
	v_mfma_f32_32x32x16_bf16 v[66:81], v[194:197], v[98:101], v[66:81]
	ds_read_b64_tr_b16 v[90:91], v153 offset:0
	ds_read_b64_tr_b16 v[92:93], v153 offset:0x800
	ds_read_b64_tr_b16 v[94:95], v153 offset:0x1000
	ds_read_b64_tr_b16 v[96:97], v153 offset:0x1800
	ds_read_b64_tr_b16 v[194:195], v153 offset:0x200
	ds_read_b64_tr_b16 v[196:197], v153 offset:0xa00
	ds_read_b64_tr_b16 v[198:199], v153 offset:0x1200
	ds_read_b64_tr_b16 v[200:201], v153 offset:0x1a00
	s_waitcnt lgkmcnt(4)
	s_nop 0
	v_mfma_f32_32x32x16_bf16 v[2:17], v[82:85], v[90:93], v[2:17]
	s_nop 9
	v_exp_f32_e32 v214, v66
	v_exp_f32_e32 v215, v67
	v_exp_f32_e32 v216, v68
	v_exp_f32_e32 v217, v69
	v_mfma_f32_32x32x16_bf16 v[2:17], v[86:89], v[94:97], v[2:17]
	ds_read_b64_tr_b16 v[66:67], v153 offset:0x400
	ds_read_b64_tr_b16 v[68:69], v153 offset:0xc00
	ds_read_b64_tr_b16 v[90:91], v153 offset:0x1400
	ds_read_b64_tr_b16 v[92:93], v153 offset:0x1c00
	s_waitcnt lgkmcnt(4)
	v_mfma_f32_32x32x16_bf16 v[18:33], v[82:85], v[194:197], v[18:33]
	v_exp_f32_e32 v194, v70
	v_exp_f32_e32 v195, v71
	v_exp_f32_e32 v196, v72
	v_exp_f32_e32 v197, v73
	v_mfma_f32_32x32x16_bf16 v[18:33], v[86:89], v[198:201], v[18:33]
	ds_read_b64_tr_b16 v[70:71], v153 offset:0x600
	ds_read_b64_tr_b16 v[72:73], v153 offset:0xe00
	ds_read_b64_tr_b16 v[94:95], v153 offset:0x1600
	ds_read_b64_tr_b16 v[96:97], v153 offset:0x1e00
	s_waitcnt lgkmcnt(4)
	v_mfma_f32_32x32x16_bf16 v[34:49], v[82:85], v[66:69], v[34:49]
	v_exp_f32_e32 v198, v74
	v_exp_f32_e32 v199, v75
	v_exp_f32_e32 v200, v76
	v_exp_f32_e32 v201, v77
	v_mfma_f32_32x32x16_bf16 v[34:49], v[86:89], v[90:93], v[34:49]
	ds_read_b64_tr_b16 v[66:67], v153 offset:0x2000
	ds_read_b64_tr_b16 v[68:69], v153 offset:0x2800
	ds_read_b64_tr_b16 v[74:75], v153 offset:0x3000
	ds_read_b64_tr_b16 v[76:77], v153 offset:0x3800
	s_waitcnt lgkmcnt(4)
	v_mfma_f32_32x32x16_bf16 v[50:65], v[82:85], v[70:73], v[50:65]
	v_exp_f32_e32 v249, v78
	v_exp_f32_e32 v250, v79
	v_cvt_pk_bf16_f32 v72, v194, v195
	v_cvt_pk_bf16_f32 v73, v196, v197
	v_mfma_f32_32x32x16_bf16 v[50:65], v[86:89], v[94:97], v[50:65]
	v_exp_f32_e32 v251, v80
	v_exp_f32_e32 v248, v81
	v_cvt_pk_bf16_f32 v78, v198, v199
	v_cvt_pk_bf16_f32 v79, v200, v201
	v_cvt_pk_bf16_f32 v80, v249, v250
	v_cvt_pk_bf16_f32 v70, v214, v215
	v_cvt_pk_bf16_f32 v71, v216, v217
	v_cvt_pk_bf16_f32 v81, v251, v248
	s_nop 0
	ds_read_b64_tr_b16 v[82:83], v153 offset:0x2200
	ds_read_b64_tr_b16 v[84:85], v153 offset:0x2a00
	ds_read_b64_tr_b16 v[86:87], v153 offset:0x3200
	ds_read_b64_tr_b16 v[88:89], v153 offset:0x3a00
	s_waitcnt lgkmcnt(4)
	s_nop 0
	v_mfma_f32_32x32x16_bf16 v[2:17], v[70:73], v[66:69], v[2:17]
	v_add_f32_e32 v246, v155, v157
	v_add_f32_e32 v247, v214, v215
	v_add_f32_e32 v246, v246, v159
	v_add_f32_e32 v247, v247, v216
	v_mfma_f32_32x32x16_bf16 v[2:17], v[78:81], v[74:77], v[2:17]
	v_add_f32_e32 v246, v246, v193
	v_add_f32_e32 v247, v247, v217
	v_add_f32_e32 v246, v246, v202
	v_add_f32_e32 v247, v247, v194
	ds_read_b64_tr_b16 v[66:67], v153 offset:0x2400
	ds_read_b64_tr_b16 v[68:69], v153 offset:0x2c00
	ds_read_b64_tr_b16 v[74:75], v153 offset:0x3400
	ds_read_b64_tr_b16 v[76:77], v153 offset:0x3c00
	s_waitcnt lgkmcnt(4)
	v_mfma_f32_32x32x16_bf16 v[18:33], v[70:73], v[82:85], v[18:33]
	v_add_f32_e32 v246, v246, v203
	v_add_f32_e32 v247, v247, v195
	v_add_f32_e32 v246, v246, v204
	v_add_f32_e32 v247, v247, v196
	v_mfma_f32_32x32x16_bf16 v[18:33], v[78:81], v[86:89], v[18:33]
	v_add_f32_e32 v246, v246, v205
	v_add_f32_e32 v247, v247, v197
	v_add_f32_e32 v246, v246, v206
	v_add_f32_e32 v247, v247, v198
	ds_read_b64_tr_b16 v[82:83], v153 offset:0x2600
	ds_read_b64_tr_b16 v[84:85], v153 offset:0x2e00
	ds_read_b64_tr_b16 v[86:87], v153 offset:0x3600
	ds_read_b64_tr_b16 v[88:89], v153 offset:0x3e00
	s_waitcnt lgkmcnt(4)
	v_mfma_f32_32x32x16_bf16 v[34:49], v[70:73], v[66:69], v[34:49]
	v_add_f32_e32 v246, v246, v207
	v_add_f32_e32 v247, v247, v199
	v_add_f32_e32 v246, v246, v208
	v_add_f32_e32 v247, v247, v200
	v_mfma_f32_32x32x16_bf16 v[34:49], v[78:81], v[74:77], v[34:49]
	v_add_f32_e32 v246, v246, v209
	v_add_f32_e32 v247, v247, v201
	v_add_f32_e32 v246, v246, v210
	v_add_f32_e32 v247, v247, v249
	s_waitcnt lgkmcnt(0)
	v_mfma_f32_32x32x16_bf16 v[50:65], v[70:73], v[82:85], v[50:65]
	v_add_f32_e32 v246, v246, v211
	v_add_f32_e32 v247, v247, v250
	v_add_f32_e32 v246, v246, v212
	v_add_f32_e32 v247, v247, v251
	v_add_f32_e32 v246, v246, v213
	v_add_f32_e32 v247, v247, v248
	v_add_f32_e32 v246, v246, v247
	v_mov_b32_e32 v247, v246
	s_nop 1
	v_permlane32_swap_b32_e32 v246, v247
	v_add_f32_e32 v246, v246, v247
	v_add_f32_e32 v151, v151, v246
	s_waitcnt vmcnt(0)
	s_add_u32 s14, s14, 64
	s_addc_u32 s15, s15, 0
	s_cmp_eq_u32 s0, s1
	s_mov_b32 s4, s1
	s_waitcnt vmcnt(0)
	s_barrier
	v_mfma_f32_32x32x16_bf16 v[50:65], v[78:81], v[86:89], v[50:65]
	s_cbranch_scc0 .LBB0_892
	s_lshl_b32 s1, s68, 2
	s_add_i32 s4, s1, 0
	s_and_b32 s0, s0, 1
	s_add_i32 s4, s4, 0x1e000
	s_mul_i32 s1, s0, 0x6000
	v_add_u32_e32 v70, s1, v179
	v_add_u32_e32 v71, v70, v178
	ds_read_b128 v[66:69], v71 offset:32768
	v_add_u32_e32 v153, v70, v180
	v_add_u32_e32 v155, v70, v181
	v_add_u32_e32 v157, v70, v182
	v_add_u32_e32 v159, v70, v183
	v_add_u32_e32 v160, v70, v184
	v_add_u32_e32 v161, v70, v185
	v_add_u32_e32 v162, v70, v186
	v_add_u32_e32 v163, v70, v187
	s_waitcnt lgkmcnt(0)
	v_mfma_f32_32x32x16_bf16 v[82:97], v[66:69], v[142:145], 0
	ds_read_b128 v[66:69], v153 offset:32768
	v_add_u32_e32 v170, v70, v188
	v_add_u32_e32 v171, v70, v189
	v_add_u32_e32 v172, v70, v190
	s_waitcnt lgkmcnt(0)
	v_mfma_f32_32x32x16_bf16 v[82:97], v[66:69], v[138:141], v[82:97]
	ds_read_b128 v[66:69], v155 offset:32768
	s_waitcnt lgkmcnt(0)
	v_mfma_f32_32x32x16_bf16 v[82:97], v[66:69], v[134:137], v[82:97]
	ds_read_b128 v[66:69], v157 offset:32768
	s_waitcnt lgkmcnt(0)
	v_mfma_f32_32x32x16_bf16 v[82:97], v[66:69], v[130:133], v[82:97]
	ds_read_b128 v[66:69], v159 offset:32768
	s_waitcnt lgkmcnt(0)
	v_mfma_f32_32x32x16_bf16 v[82:97], v[66:69], v[126:129], v[82:97]
	ds_read_b128 v[66:69], v160 offset:32768
	s_waitcnt lgkmcnt(0)
	v_mfma_f32_32x32x16_bf16 v[82:97], v[66:69], v[122:125], v[82:97]
	ds_read_b128 v[66:69], v161 offset:32768
	s_waitcnt lgkmcnt(0)
	v_mfma_f32_32x32x16_bf16 v[82:97], v[66:69], v[118:121], v[82:97]
	ds_read_b128 v[66:69], v162 offset:32768
	s_waitcnt lgkmcnt(0)
	v_mfma_f32_32x32x16_bf16 v[82:97], v[66:69], v[114:117], v[82:97]
	ds_read_b128 v[66:69], v163 offset:32768
	s_waitcnt lgkmcnt(0)
	v_mfma_f32_32x32x16_bf16 v[82:97], v[66:69], v[110:113], v[82:97]
	ds_read_b128 v[66:69], v170 offset:32768
	s_waitcnt lgkmcnt(0)
	v_mfma_f32_32x32x16_bf16 v[82:97], v[66:69], v[106:109], v[82:97]
	ds_read_b128 v[66:69], v171 offset:32768
	s_waitcnt lgkmcnt(0)
	v_mfma_f32_32x32x16_bf16 v[82:97], v[66:69], v[102:105], v[82:97]
	ds_read_b128 v[66:69], v172 offset:32768
	s_waitcnt lgkmcnt(0)
	v_mfma_f32_32x32x16_bf16 v[82:97], v[66:69], v[98:101], v[82:97]
	ds_read_b128 v[66:69], v71 offset:45056
	s_waitcnt lgkmcnt(0)
	v_mfma_f32_32x32x16_bf16 v[66:81], v[66:69], v[142:145], 0
	ds_read_b128 v[142:145], v153 offset:45056
	s_waitcnt lgkmcnt(0)
	v_mfma_f32_32x32x16_bf16 v[66:81], v[142:145], v[138:141], v[66:81]
	ds_read_b128 v[138:141], v155 offset:45056
	s_waitcnt lgkmcnt(0)
	v_mfma_f32_32x32x16_bf16 v[66:81], v[138:141], v[134:137], v[66:81]
	ds_read_b128 v[134:137], v157 offset:45056
	s_waitcnt lgkmcnt(0)
	v_mfma_f32_32x32x16_bf16 v[66:81], v[134:137], v[130:133], v[66:81]
	ds_read_b128 v[130:133], v159 offset:45056
	s_waitcnt lgkmcnt(0)
	v_mfma_f32_32x32x16_bf16 v[66:81], v[130:133], v[126:129], v[66:81]
	ds_read_b128 v[126:129], v160 offset:45056
	s_waitcnt lgkmcnt(0)
	v_mfma_f32_32x32x16_bf16 v[66:81], v[126:129], v[122:125], v[66:81]
	ds_read_b128 v[122:125], v161 offset:45056
	s_waitcnt lgkmcnt(0)
	v_mfma_f32_32x32x16_bf16 v[66:81], v[122:125], v[118:121], v[66:81]
	ds_read_b128 v[118:121], v162 offset:45056
	v_exp_f32_e32 v122, v97
	s_waitcnt lgkmcnt(0)
	v_mfma_f32_32x32x16_bf16 v[66:81], v[118:121], v[114:117], v[66:81]
	ds_read_b128 v[114:117], v163 offset:45056
	v_exp_f32_e32 v118, v93
	v_exp_f32_e32 v119, v94
	v_exp_f32_e32 v120, v95
	v_exp_f32_e32 v121, v96
	s_waitcnt lgkmcnt(0)
	v_mfma_f32_32x32x16_bf16 v[66:81], v[114:117], v[110:113], v[66:81]
	ds_read_b128 v[110:113], v170 offset:45056
	v_exp_f32_e32 v114, v89
	v_exp_f32_e32 v115, v90
	v_exp_f32_e32 v116, v91
	v_exp_f32_e32 v117, v92
	v_cvt_pk_bf16_f32 v89, v121, v122
	s_waitcnt lgkmcnt(0)
	v_mfma_f32_32x32x16_bf16 v[66:81], v[110:113], v[106:109], v[66:81]
	ds_read_b128 v[106:109], v171 offset:45056
	v_exp_f32_e32 v110, v85
	v_exp_f32_e32 v111, v86
	v_exp_f32_e32 v112, v87
	v_exp_f32_e32 v113, v88
	v_cvt_pk_bf16_f32 v86, v115, v116
	v_cvt_pk_bf16_f32 v87, v117, v118
	s_waitcnt lgkmcnt(0)
	v_mfma_f32_32x32x16_bf16 v[66:81], v[106:109], v[102:105], v[66:81]
	ds_read_b128 v[102:105], v172 offset:45056
	v_exp_f32_e32 v107, v82
	v_exp_f32_e32 v108, v83
	v_exp_f32_e32 v109, v84
	v_cvt_pk_bf16_f32 v84, v111, v112
	v_cvt_pk_bf16_f32 v85, v113, v114
	v_cvt_pk_bf16_f32 v82, v107, v108
	s_waitcnt lgkmcnt(0)
	v_mfma_f32_32x32x16_bf16 v[66:81], v[102:105], v[98:101], v[66:81]
	v_cvt_pk_bf16_f32 v83, v109, v110
	v_cvt_pk_bf16_f32 v88, v119, v120
	v_lshl_add_u32 v106, s0, 14, v176
	ds_read_b64_tr_b16 v[90:91], v106 offset:0
	ds_read_b64_tr_b16 v[92:93], v106 offset:0x800
	ds_read_b64_tr_b16 v[94:95], v106 offset:0x1000
	ds_read_b64_tr_b16 v[96:97], v106 offset:0x1800
	ds_read_b64_tr_b16 v[98:99], v106 offset:0x200
	ds_read_b64_tr_b16 v[100:101], v106 offset:0xa00
	ds_read_b64_tr_b16 v[102:103], v106 offset:0x1200
	ds_read_b64_tr_b16 v[104:105], v106 offset:0x1a00
	s_waitcnt lgkmcnt(4)
	s_nop 0
	v_mfma_f32_32x32x16_bf16 v[2:17], v[82:85], v[90:93], v[2:17]
	s_nop 2
	v_exp_f32_e32 v123, v66
	v_exp_f32_e32 v124, v67
	v_exp_f32_e32 v125, v68
	v_exp_f32_e32 v126, v69
	v_mfma_f32_32x32x16_bf16 v[2:17], v[86:89], v[94:97], v[2:17]
	ds_read_b64_tr_b16 v[66:67], v106 offset:0x400
	ds_read_b64_tr_b16 v[68:69], v106 offset:0xc00
	ds_read_b64_tr_b16 v[90:91], v106 offset:0x1400
	ds_read_b64_tr_b16 v[92:93], v106 offset:0x1c00
	s_waitcnt lgkmcnt(4)
	v_mfma_f32_32x32x16_bf16 v[18:33], v[82:85], v[98:101], v[18:33]
	v_exp_f32_e32 v98, v70
	v_exp_f32_e32 v99, v71
	v_exp_f32_e32 v100, v72
	v_exp_f32_e32 v101, v73
	v_mfma_f32_32x32x16_bf16 v[18:33], v[86:89], v[102:105], v[18:33]
	ds_read_b64_tr_b16 v[70:71], v106 offset:0x600
	ds_read_b64_tr_b16 v[72:73], v106 offset:0xe00
	ds_read_b64_tr_b16 v[94:95], v106 offset:0x1600
	ds_read_b64_tr_b16 v[96:97], v106 offset:0x1e00
	s_waitcnt lgkmcnt(4)
	v_mfma_f32_32x32x16_bf16 v[34:49], v[82:85], v[66:69], v[34:49]
	v_exp_f32_e32 v102, v74
	v_exp_f32_e32 v103, v75
	v_exp_f32_e32 v104, v76
	v_exp_f32_e32 v105, v77
	v_mfma_f32_32x32x16_bf16 v[34:49], v[86:89], v[90:93], v[34:49]
	ds_read_b64_tr_b16 v[74:75], v106 offset:0x2000
	ds_read_b64_tr_b16 v[76:77], v106 offset:0x2800
	ds_read_b64_tr_b16 v[90:91], v106 offset:0x3000
	ds_read_b64_tr_b16 v[92:93], v106 offset:0x3800
	s_waitcnt lgkmcnt(4)
	v_add_f32_e32 v66, v107, v108
	v_add_f32_e32 v67, v123, v124
	v_mfma_f32_32x32x16_bf16 v[50:65], v[82:85], v[70:73], v[50:65]
	v_add_f32_e32 v66, v66, v109
	v_add_f32_e32 v67, v67, v125
	v_exp_f32_e32 v127, v78
	v_add_f32_e32 v66, v66, v110
	v_add_f32_e32 v67, v67, v126
	v_exp_f32_e32 v128, v79
	v_add_f32_e32 v66, v66, v111
	v_add_f32_e32 v67, v67, v98
	v_mfma_f32_32x32x16_bf16 v[50:65], v[86:89], v[94:97], v[50:65]
	v_add_f32_e32 v66, v66, v112
	v_add_f32_e32 v67, v67, v99
	v_exp_f32_e32 v129, v80
	v_add_f32_e32 v66, v66, v113
	v_add_f32_e32 v67, v67, v100
	v_exp_f32_e32 v81, v81
	v_add_f32_e32 v66, v66, v114
	v_add_f32_e32 v67, v67, v101
	v_cvt_pk_bf16_f32 v68, v123, v124
	v_add_f32_e32 v66, v66, v115
	v_add_f32_e32 v67, v67, v102
	v_cvt_pk_bf16_f32 v69, v125, v126
	v_add_f32_e32 v66, v66, v116
	v_add_f32_e32 v67, v67, v103
	v_cvt_pk_bf16_f32 v70, v98, v99
	v_add_f32_e32 v66, v66, v117
	v_add_f32_e32 v67, v67, v104
	v_cvt_pk_bf16_f32 v71, v100, v101
	v_add_f32_e32 v66, v66, v118
	v_add_f32_e32 v67, v67, v105
	v_cvt_pk_bf16_f32 v78, v102, v103
	v_add_f32_e32 v66, v66, v119
	v_add_f32_e32 v67, v67, v127
	v_cvt_pk_bf16_f32 v79, v104, v105
	v_add_f32_e32 v66, v66, v120
	v_add_f32_e32 v67, v67, v128
	v_cvt_pk_bf16_f32 v80, v127, v128
	v_add_f32_e32 v66, v66, v121
	v_add_f32_e32 v67, v67, v129
	v_add_f32_e32 v66, v66, v122
	v_add_f32_e32 v67, v67, v81
	v_cvt_pk_bf16_f32 v81, v129, v81
	v_add_f32_e32 v66, v66, v67
	v_mov_b32_e32 v67, v66
	s_nop 1
	v_permlane32_swap_b32_e32 v66, v67
	ds_read_b64_tr_b16 v[82:83], v106 offset:0x2200
	ds_read_b64_tr_b16 v[84:85], v106 offset:0x2a00
	ds_read_b64_tr_b16 v[86:87], v106 offset:0x3200
	ds_read_b64_tr_b16 v[88:89], v106 offset:0x3a00
	s_waitcnt lgkmcnt(4)
	v_mfma_f32_32x32x16_bf16 v[2:17], v[68:71], v[74:77], v[2:17]
	s_nop 0
	v_mfma_f32_32x32x16_bf16 v[2:17], v[78:81], v[90:93], v[2:17]
	ds_read_b64_tr_b16 v[72:73], v106 offset:0x2400
	ds_read_b64_tr_b16 v[74:75], v106 offset:0x2c00
	ds_read_b64_tr_b16 v[90:91], v106 offset:0x3400
	ds_read_b64_tr_b16 v[92:93], v106 offset:0x3c00
	s_waitcnt lgkmcnt(4)
	v_mfma_f32_32x32x16_bf16 v[18:33], v[68:71], v[82:85], v[18:33]
	v_mfma_f32_32x32x16_bf16 v[18:33], v[78:81], v[86:89], v[18:33]
	ds_read_b64_tr_b16 v[82:83], v106 offset:0x2600
	ds_read_b64_tr_b16 v[84:85], v106 offset:0x2e00
	ds_read_b64_tr_b16 v[86:87], v106 offset:0x3600
	ds_read_b64_tr_b16 v[88:89], v106 offset:0x3e00
	s_waitcnt lgkmcnt(4)
	v_mfma_f32_32x32x16_bf16 v[34:49], v[68:71], v[72:75], v[34:49]
	v_mfma_f32_32x32x16_bf16 v[34:49], v[78:81], v[90:93], v[34:49]
	s_waitcnt lgkmcnt(0)
	v_mfma_f32_32x32x16_bf16 v[50:65], v[68:71], v[82:85], v[50:65]
	s_waitcnt vmcnt(0)
	s_barrier
	v_mfma_f32_32x32x16_bf16 v[50:65], v[78:81], v[86:89], v[50:65]
	s_and_saveexec_b64 s[0:1], s[2:3]
	s_cbranch_execz .LBB0_886
	v_add_f32_e32 v66, v66, v67
	v_lshl_add_u32 v68, v1, 2, s4
	v_add_f32_e32 v66, v151, v66
	ds_write_b32 v68, v66
	s_branch .LBB0_886

.LBB0_902:
	s_lshr_b32 s6, s26, 6
	s_and_b64 s[18:19], s[16:17], exec
	s_cselect_b32 s6, s6, s26
	s_mul_i32 s10, s15, 0x3000
	s_mul_hi_u32 s18, s14, 0x3000
	s_and_b32 s23, s6, 15
	s_add_i32 s18, s18, s10
	s_mul_i32 s10, s14, 0x3000
	v_readlane_b32 s30, v242, 17
	v_readlane_b32 s31, v242, 18
	s_add_u32 s10, s30, s10
	s_addc_u32 s18, s31, s18
	s_lshl_b32 s25, s23, 7
	s_add_u32 s10, s10, s25
	s_addc_u32 s18, s18, 0
	s_add_u32 s28, s10, 0x1000
	s_mulk_i32 s5, 0x3000
	s_mul_hi_u32 s10, s4, 0x3000
	s_addc_u32 s29, s18, 0
	s_add_i32 s10, s10, s5
	s_mulk_i32 s4, 0x3000
	s_add_u32 s18, s30, s4
	s_addc_u32 s10, s31, s10
	s_add_u32 s4, s18, s25
	s_addc_u32 s5, s10, 0
	s_mul_i32 s1, s1, 0xc000000
	s_mul_hi_u32 s87, s0, 0xc000000
	s_mul_i32 s88, s0, 0xc000000
	s_lshl_b32 s0, s6, 7
	s_add_i32 s87, s87, s1
	s_and_b32 s24, s0, 0x700
	s_add_u32 s0, s18, s24
	s_addc_u32 s1, s10, 0
	s_add_u32 s18, s0, 0x18002000
	v_readfirstlane_b32 s10, v0
	s_addc_u32 s19, s1, 0
	s_lshr_b32 s27, s10, 6
	s_lshl_b32 s6, s27, 5
	v_or_b32_e32 v1, s6, v165
	v_mov_b64_e32 v[2:3], s[28:29]
	s_movk_i32 s21, 0x3000
	v_mad_u64_u32 v[2:3], s[28:29], v1, s21, v[2:3]
	v_lshl_add_u64 v[2:3], v[2:3], 0, v[146:147]
	global_load_dwordx4 v[128:131], v[2:3], off
	global_load_dwordx4 v[132:135], v[2:3], off offset:32
	global_load_dwordx4 v[136:139], v[2:3], off offset:64
	global_load_dwordx4 v[140:143], v[2:3], off offset:96
	s_andn2_b32 s10, s10, 63
	v_or_b32_e32 v1, s10, v166
	v_ashrrev_i32_e32 v2, 31, v1
	v_lshrrev_b32_e32 v2, 29, v2
	s_ashr_i32 s21, s10, 4
	v_add_u32_e32 v2, v1, v2
	s_and_b32 s91, s21, -16
	s_lshr_b32 s21, s21, 1
	v_ashrrev_i32_e32 v3, 3, v2
	v_and_b32_e32 v2, 0x1ffffff8, v2
	s_and_b32 s92, s21, 4
	v_sub_u32_e32 v2, v1, v2
	v_lshrrev_b32_e32 v4, 1, v3
	s_or_b32 s21, s91, s92
	v_bitop3_b32 v2, v4, v2, 7 bitop3:0x6c
	v_or_b32_e32 v4, s21, v182
	v_lshrrev_b32_e32 v73, 1, v4
	v_xor_b32_e32 v73, v73, v4
	v_and_b32_e32 v73, 4, v73
	v_lshl_or_b32 v73, v73, 1, v73
	v_xor_b32_e32 v4, v4, v73
	s_add_i32 s21, s10, 0x200
	s_ashr_i32 s21, s21, 4
	s_and_b32 s89, s21, -16
	s_lshr_b32 s21, s21, 1
	s_and_b32 s90, s21, 4
	v_and_or_b32 v1, v1, s20, v169
	v_mul_lo_u32 v4, v4, s22
	s_or_b32 s21, s89, s90
	v_or_b32_e32 v72, v4, v1
	v_or_b32_e32 v4, s21, v182
	v_lshrrev_b32_e32 v71, 1, v4
	v_xor_b32_e32 v71, v71, v4
	v_and_b32_e32 v71, 4, v71
	v_lshl_or_b32 v71, v71, 1, v71
	v_xor_b32_e32 v4, v4, v71
	v_mul_lo_u32 v4, v4, s22
	v_or_b32_e32 v70, v4, v1
	v_mul_lo_u32 v1, v3, s22
	v_lshl_add_u32 v114, v2, 3, v1
	v_ashrrev_i32_e32 v115, 31, v114
	v_lshl_add_u64 v[74:75], v[114:115], 1, s[4:5]
	s_mov_b64 s[4:5], 0x18001800
	v_lshl_add_u64 v[2:3], v[74:75], 0, s[4:5]
	s_lshl_b32 s4, s27, 10
	s_add_i32 s30, s4, 0
	s_add_i32 s31, s30, 0x8000
	v_ashrrev_i32_e32 v73, 31, v72
	s_mov_b32 m0, s31
	v_lshlrev_b64 v[76:77], 1, v[72:73]
	v_ashrrev_i32_e32 v71, 31, v70
	global_load_lds_dwordx4 v[2:3], off
	v_lshl_add_u64 v[2:3], s[18:19], 0, v[76:77]
	s_mov_b32 m0, s30
	v_lshlrev_b64 v[78:79], 1, v[70:71]
	s_add_i32 s33, s30, 0x2000
	global_load_lds_dwordx4 v[2:3], off
	v_lshl_add_u64 v[2:3], s[18:19], 0, v[78:79]
	s_mov_b32 m0, s33
	s_mov_b64 s[4:5], 0x180c1800
	s_add_i32 s34, s30, 0xa000
	global_load_lds_dwordx4 v[2:3], off
	v_lshl_add_u64 v[2:3], v[74:75], 0, s[4:5]
	s_mov_b32 m0, s34
	s_waitcnt vmcnt(0)
	s_waitcnt vmcnt(0) lgkmcnt(0)
	s_barrier
	global_load_lds_dwordx4 v[2:3], off
	ds_read_b128 v[2:5], v188 offset:32768
	ds_read_b128 v[26:29], v188 offset:36864
	s_waitcnt lgkmcnt(0)
	v_mfma_f32_32x32x16_bf16 v[2:17], v[2:5], v[128:131], 0
	ds_read_b128 v[18:21], v189 offset:32768
	ds_read_b128 v[30:33], v189 offset:36864
	s_mov_b64 s[4:5], 0x18181800
	s_mov_b32 m0, s31
	s_waitcnt lgkmcnt(0)
	v_mfma_f32_32x32x16_bf16 v[2:17], v[18:21], v[132:135], v[2:17]
	ds_read_b128 v[18:21], v190 offset:32768
	ds_read_b128 v[22:25], v190 offset:36864
	s_waitcnt lgkmcnt(0)
	v_mfma_f32_32x32x16_bf16 v[2:17], v[18:21], v[136:139], v[2:17]
	ds_read_b128 v[34:37], v191 offset:32768
	ds_read_b128 v[18:21], v191 offset:36864
	s_waitcnt vmcnt(0)
	s_waitcnt vmcnt(0) lgkmcnt(0)
	s_barrier
	v_mfma_f32_32x32x16_bf16 v[2:17], v[34:37], v[140:143], v[2:17]
	s_nop 11
	v_exp_f32_e32 v80, v2
	v_exp_f32_e32 v81, v3
	v_lshl_add_u64 v[2:3], v[74:75], 0, s[4:5]
	s_add_u32 s4, s0, 0x180c2000
	s_addc_u32 s5, s1, 0
	s_add_i32 s35, s30, 0x4000
	global_load_lds_dwordx4 v[2:3], off
	v_lshl_add_u64 v[2:3], s[4:5], 0, v[76:77]
	s_mov_b32 m0, s35
	s_add_i32 s86, s30, 0x6000
	global_load_lds_dwordx4 v[2:3], off
	v_lshl_add_u64 v[2:3], s[4:5], 0, v[78:79]
	s_mov_b32 m0, s86
	v_exp_f32_e32 v99, v4
	global_load_lds_dwordx4 v[2:3], off
	v_exp_f32_e32 v100, v5
	v_exp_f32_e32 v101, v6
	v_exp_f32_e32 v102, v7
	v_exp_f32_e32 v103, v8
	v_exp_f32_e32 v104, v9
	v_exp_f32_e32 v105, v10
	v_exp_f32_e32 v106, v11
	v_exp_f32_e32 v107, v12
	v_exp_f32_e32 v108, v13
	v_exp_f32_e32 v109, v14
	v_exp_f32_e32 v110, v15
	v_exp_f32_e32 v111, v16
	v_exp_f32_e32 v112, v17
	v_mfma_f32_32x32x16_bf16 v[2:17], v[26:29], v[128:131], 0
	v_mfma_f32_32x32x16_bf16 v[2:17], v[30:33], v[132:135], v[2:17]
	v_mfma_f32_32x32x16_bf16 v[2:17], v[22:25], v[136:139], v[2:17]
	ds_read_b128 v[22:25], v188 offset:40960
	ds_read_b128 v[26:29], v188 offset:45056
	ds_read_b128 v[30:33], v189 offset:40960
	ds_read_b128 v[34:37], v189 offset:45056
	ds_read_b128 v[38:41], v190 offset:40960
	ds_read_b128 v[42:45], v190 offset:45056
	ds_read_b128 v[46:49], v191 offset:40960
	ds_read_b128 v[50:53], v191 offset:45056
	v_mfma_f32_32x32x16_bf16 v[2:17], v[18:21], v[140:143], v[2:17]
	s_waitcnt lgkmcnt(0)
	v_mfma_f32_32x32x16_bf16 v[54:69], v[22:25], v[128:131], 0
	s_nop 9
	v_exp_f32_e32 v2, v2
	v_exp_f32_e32 v3, v3
	v_exp_f32_e32 v4, v4
	v_exp_f32_e32 v5, v5
	v_exp_f32_e32 v6, v6
	v_exp_f32_e32 v7, v7
	v_exp_f32_e32 v8, v8
	v_mfma_f32_32x32x16_bf16 v[82:97], v[26:29], v[128:131], 0
	v_exp_f32_e32 v9, v9
	v_mfma_f32_32x32x16_bf16 v[54:69], v[30:33], v[132:135], v[54:69]
	v_exp_f32_e32 v10, v10
	v_exp_f32_e32 v11, v11
	v_exp_f32_e32 v12, v12
	v_exp_f32_e32 v13, v13
	v_exp_f32_e32 v14, v14
	v_exp_f32_e32 v15, v15
	v_exp_f32_e32 v16, v16
	v_mfma_f32_32x32x16_bf16 v[82:97], v[34:37], v[132:135], v[82:97]
	v_exp_f32_e32 v17, v17
	v_add_f32_e32 v1, v80, v81
	v_add_f32_e32 v18, v2, v3
	v_mfma_f32_32x32x16_bf16 v[54:69], v[38:41], v[136:139], v[54:69]
	v_add_f32_e32 v1, v1, v99
	v_add_f32_e32 v18, v18, v4
	v_cvt_pk_bf16_f32 v98, v80, v81
	v_add_f32_e32 v1, v1, v100
	v_add_f32_e32 v18, v18, v5
	v_cvt_pk_bf16_f32 v99, v99, v100
	v_add_f32_e32 v1, v1, v101
	v_add_f32_e32 v18, v18, v6
	v_mfma_f32_32x32x16_bf16 v[82:97], v[42:45], v[136:139], v[82:97]
	v_add_f32_e32 v1, v1, v102
	v_add_f32_e32 v18, v18, v7
	v_cvt_pk_bf16_f32 v100, v101, v102
	v_add_f32_e32 v1, v1, v103
	v_add_f32_e32 v18, v18, v8
	v_cvt_pk_bf16_f32 v101, v103, v104
	v_add_f32_e32 v1, v1, v104
	v_add_f32_e32 v18, v18, v9
	s_nop 0
	v_add_f32_e32 v1, v1, v105
	v_add_f32_e32 v18, v18, v10
	v_add_f32_e32 v1, v1, v106
	v_add_f32_e32 v18, v18, v11
	s_nop 0
	v_add_f32_e32 v1, v1, v107
	v_add_f32_e32 v18, v18, v12
	s_nop 0
	v_add_f32_e32 v1, v1, v108
	v_add_f32_e32 v18, v18, v13
	s_nop 0
	v_add_f32_e32 v1, v1, v109
	v_add_f32_e32 v18, v18, v14
	s_nop 0
	v_add_f32_e32 v1, v1, v110
	v_add_f32_e32 v18, v18, v15
	s_nop 0
	v_add_f32_e32 v1, v1, v111
	v_add_f32_e32 v18, v18, v16
	s_nop 0
	v_add_f32_e32 v1, v1, v112
	v_add_f32_e32 v18, v18, v17
	s_nop 0
	v_add_f32_e32 v1, v1, v18
	v_mov_b32_e32 v116, v1
	s_nop 1
	v_permlane32_swap_b32_e32 v1, v116
	v_mfma_f32_32x32x16_bf16 v[54:69], v[46:49], v[140:143], v[54:69]
	v_cvt_pk_bf16_f32 v102, v105, v106
	v_cvt_pk_bf16_f32 v103, v107, v108
	v_cvt_pk_bf16_f32 v104, v109, v110
	v_cvt_pk_bf16_f32 v105, v111, v112
	v_cvt_pk_bf16_f32 v106, v2, v3
	v_cvt_pk_bf16_f32 v107, v4, v5
	v_cvt_pk_bf16_f32 v108, v6, v7
	v_mfma_f32_32x32x16_bf16 v[82:97], v[50:53], v[140:143], v[82:97]
	v_cvt_pk_bf16_f32 v109, v8, v9
	v_cvt_pk_bf16_f32 v110, v10, v11
	v_cvt_pk_bf16_f32 v111, v12, v13
	v_cvt_pk_bf16_f32 v112, v14, v15
	v_cvt_pk_bf16_f32 v113, v16, v17
	ds_read_b64_tr_b16 v[2:3], v184 offset:0
	ds_read_b64_tr_b16 v[4:5], v184 offset:0x800
	ds_read_b64_tr_b16 v[18:19], v184 offset:0x1000
	ds_read_b64_tr_b16 v[20:21], v184 offset:0x1800
	ds_read_b64_tr_b16 v[22:23], v184 offset:0x2000
	ds_read_b64_tr_b16 v[24:25], v184 offset:0x2800
	ds_read_b64_tr_b16 v[26:27], v184 offset:0x3000
	ds_read_b64_tr_b16 v[28:29], v184 offset:0x3800
	ds_read_b64_tr_b16 v[30:31], v184 offset:0x200
	ds_read_b64_tr_b16 v[32:33], v184 offset:0xa00
	ds_read_b64_tr_b16 v[34:35], v184 offset:0x1200
	ds_read_b64_tr_b16 v[36:37], v184 offset:0x1a00
	ds_read_b64_tr_b16 v[38:39], v184 offset:0x2200
	ds_read_b64_tr_b16 v[40:41], v184 offset:0x2a00
	ds_read_b64_tr_b16 v[42:43], v184 offset:0x3200
	ds_read_b64_tr_b16 v[44:45], v184 offset:0x3a00
	s_waitcnt lgkmcnt(8)
	s_nop 0
	v_mfma_f32_32x32x16_bf16 v[2:17], v[98:101], v[2:5], 0
	v_exp_f32_e32 v117, v54
	v_exp_f32_e32 v126, v55
	v_exp_f32_e32 v127, v56
	v_exp_f32_e32 v149, v57
	v_mfma_f32_32x32x16_bf16 v[2:17], v[102:105], v[18:21], v[2:17]
	v_mfma_f32_32x32x16_bf16 v[2:17], v[106:109], v[22:25], v[2:17]
	v_mfma_f32_32x32x16_bf16 v[2:17], v[110:113], v[26:29], v[2:17]
	ds_read_b64_tr_b16 v[46:47], v184 offset:0x400
	ds_read_b64_tr_b16 v[48:49], v184 offset:0xc00
	ds_read_b64_tr_b16 v[50:51], v184 offset:0x1400
	ds_read_b64_tr_b16 v[52:53], v184 offset:0x1c00
	ds_read_b64_tr_b16 v[54:55], v184 offset:0x2400
	ds_read_b64_tr_b16 v[56:57], v184 offset:0x2c00
	ds_read_b64_tr_b16 v[118:119], v184 offset:0x3400
	ds_read_b64_tr_b16 v[120:121], v184 offset:0x3c00
	s_waitcnt lgkmcnt(8)
	v_mfma_f32_32x32x16_bf16 v[18:33], v[98:101], v[30:33], 0
	v_exp_f32_e32 v151, v58
	v_exp_f32_e32 v153, v59
	v_exp_f32_e32 v155, v60
	v_exp_f32_e32 v157, v61
	v_mfma_f32_32x32x16_bf16 v[18:33], v[102:105], v[34:37], v[18:33]
	v_mfma_f32_32x32x16_bf16 v[18:33], v[106:109], v[38:41], v[18:33]
	v_mfma_f32_32x32x16_bf16 v[18:33], v[110:113], v[42:45], v[18:33]
	ds_read_b64_tr_b16 v[58:59], v184 offset:0x600
	ds_read_b64_tr_b16 v[60:61], v184 offset:0xe00
	ds_read_b64_tr_b16 v[122:123], v184 offset:0x1600
	ds_read_b64_tr_b16 v[124:125], v184 offset:0x1e00
	ds_read_b64_tr_b16 v[170:171], v184 offset:0x2600
	ds_read_b64_tr_b16 v[172:173], v184 offset:0x2e00
	ds_read_b64_tr_b16 v[174:175], v184 offset:0x3600
	ds_read_b64_tr_b16 v[176:177], v184 offset:0x3e00
	s_waitcnt lgkmcnt(8)
	v_mfma_f32_32x32x16_bf16 v[34:49], v[98:101], v[46:49], 0
	v_exp_f32_e32 v159, v62
	v_exp_f32_e32 v161, v63
	v_exp_f32_e32 v163, v64
	v_exp_f32_e32 v196, v65
	v_mfma_f32_32x32x16_bf16 v[34:49], v[102:105], v[50:53], v[34:49]
	v_mfma_f32_32x32x16_bf16 v[34:49], v[106:109], v[54:57], v[34:49]
	v_mfma_f32_32x32x16_bf16 v[34:49], v[110:113], v[118:121], v[34:49]
	s_waitcnt lgkmcnt(0)
	v_mfma_f32_32x32x16_bf16 v[50:65], v[98:101], v[58:61], 0
	v_exp_f32_e32 v197, v66
	v_exp_f32_e32 v198, v67
	v_exp_f32_e32 v199, v68
	v_exp_f32_e32 v200, v69
	v_mfma_f32_32x32x16_bf16 v[50:65], v[102:105], v[122:125], v[50:65]
	v_mfma_f32_32x32x16_bf16 v[50:65], v[106:109], v[170:173], v[50:65]
	v_mfma_f32_32x32x16_bf16 v[50:65], v[110:113], v[174:177], v[50:65]
	s_mov_b64 s[4:5], 0x18241800
	s_add_u32 s0, s0, 0x18182000
	s_mov_b32 m0, s34
	v_lshl_add_u64 v[66:67], v[74:75], 0, s[4:5]
	s_addc_u32 s1, s1, 0
	s_waitcnt vmcnt(0)
	s_waitcnt vmcnt(0)
	s_barrier
	global_load_lds_dwordx4 v[66:67], off
	v_lshl_add_u64 v[66:67], s[0:1], 0, v[76:77]
	s_mov_b32 m0, s30
	s_nop 0
	global_load_lds_dwordx4 v[66:67], off
	v_lshl_add_u64 v[66:67], s[0:1], 0, v[78:79]
	s_mov_b32 m0, s33
	s_nop 0
	global_load_lds_dwordx4 v[66:67], off
	ds_read_b128 v[66:69], v188 offset:32768
	ds_read_b128 v[74:77], v188 offset:36864
	ds_read_b128 v[118:121], v189 offset:32768
	ds_read_b128 v[122:125], v189 offset:36864
	ds_read_b128 v[170:173], v190 offset:32768
	ds_read_b128 v[174:177], v190 offset:36864
	ds_read_b128 v[178:181], v191 offset:32768
	ds_read_b128 v[192:195], v191 offset:36864
	s_waitcnt lgkmcnt(0)
	v_mfma_f32_32x32x16_bf16 v[98:113], v[66:69], v[128:131], 0
	v_exp_f32_e32 v68, v82
	v_exp_f32_e32 v69, v83
	v_exp_f32_e32 v201, v84
	v_exp_f32_e32 v202, v85
	v_exp_f32_e32 v203, v86
	v_exp_f32_e32 v204, v87
	v_exp_f32_e32 v205, v88
	v_exp_f32_e32 v206, v89
	v_mfma_f32_32x32x16_bf16 v[74:89], v[74:77], v[128:131], 0
	v_mfma_f32_32x32x16_bf16 v[98:113], v[118:121], v[132:135], v[98:113]
	v_exp_f32_e32 v207, v90
	v_exp_f32_e32 v208, v91
	v_exp_f32_e32 v209, v92
	v_exp_f32_e32 v210, v93
	v_exp_f32_e32 v211, v94
	v_exp_f32_e32 v212, v95
	v_exp_f32_e32 v213, v96
	v_mfma_f32_32x32x16_bf16 v[74:89], v[122:125], v[132:135], v[74:89]
	v_exp_f32_e32 v214, v97
	v_add_f32_e32 v66, v117, v126
	v_add_f32_e32 v67, v68, v69
	v_mfma_f32_32x32x16_bf16 v[98:113], v[170:173], v[136:139], v[98:113]
	v_add_f32_e32 v66, v66, v127
	v_add_f32_e32 v67, v67, v201
	v_cvt_pk_bf16_f32 v90, v117, v126
	v_add_f32_e32 v66, v66, v149
	v_add_f32_e32 v67, v67, v202
	v_cvt_pk_bf16_f32 v91, v127, v149
	v_add_f32_e32 v66, v66, v151
	v_add_f32_e32 v67, v67, v203
	v_mfma_f32_32x32x16_bf16 v[74:89], v[174:177], v[136:139], v[74:89]
	v_add_f32_e32 v66, v66, v153
	v_add_f32_e32 v67, v67, v204
	v_cvt_pk_bf16_f32 v92, v151, v153
	v_add_f32_e32 v66, v66, v155
	v_add_f32_e32 v67, v67, v205
	v_cvt_pk_bf16_f32 v93, v155, v157
	v_add_f32_e32 v66, v66, v157
	v_add_f32_e32 v67, v67, v206
	s_nop 0
	v_add_f32_e32 v66, v66, v159
	v_add_f32_e32 v67, v67, v207
	v_add_f32_e32 v66, v66, v161
	v_add_f32_e32 v67, v67, v208
	s_nop 0
	v_add_f32_e32 v66, v66, v163
	v_add_f32_e32 v67, v67, v209
	s_nop 0
	v_add_f32_e32 v66, v66, v196
	v_add_f32_e32 v67, v67, v210
	s_nop 0
	v_add_f32_e32 v66, v66, v197
	v_add_f32_e32 v67, v67, v211
	s_nop 0
	v_add_f32_e32 v66, v66, v198
	v_add_f32_e32 v67, v67, v212
	s_nop 0
	v_add_f32_e32 v66, v66, v199
	v_add_f32_e32 v67, v67, v213
	s_nop 0
	v_add_f32_e32 v66, v66, v200
	v_add_f32_e32 v67, v67, v214
	s_nop 0
	v_add_f32_e32 v66, v66, v67
	v_mov_b32_e32 v67, v66
	s_nop 1
	v_permlane32_swap_b32_e32 v66, v67
	v_mfma_f32_32x32x16_bf16 v[98:113], v[178:181], v[140:143], v[98:113]
	v_cvt_pk_bf16_f32 v94, v159, v161
	v_cvt_pk_bf16_f32 v95, v163, v196
	v_cvt_pk_bf16_f32 v96, v197, v198
	v_cvt_pk_bf16_f32 v97, v199, v200
	v_cvt_pk_bf16_f32 v118, v68, v69
	v_cvt_pk_bf16_f32 v119, v201, v202
	v_cvt_pk_bf16_f32 v120, v203, v204
	v_mfma_f32_32x32x16_bf16 v[74:89], v[192:195], v[140:143], v[74:89]
	v_cvt_pk_bf16_f32 v121, v205, v206
	v_cvt_pk_bf16_f32 v122, v207, v208
	v_cvt_pk_bf16_f32 v123, v209, v210
	v_cvt_pk_bf16_f32 v124, v211, v212
	v_cvt_pk_bf16_f32 v125, v213, v214
	ds_read_b64_tr_b16 v[170:171], v185 offset:0
	ds_read_b64_tr_b16 v[172:173], v185 offset:0x800
	ds_read_b64_tr_b16 v[174:175], v185 offset:0x1000
	ds_read_b64_tr_b16 v[176:177], v185 offset:0x1800
	ds_read_b64_tr_b16 v[178:179], v185 offset:0x2000
	ds_read_b64_tr_b16 v[180:181], v185 offset:0x2800
	ds_read_b64_tr_b16 v[192:193], v185 offset:0x3000
	ds_read_b64_tr_b16 v[194:195], v185 offset:0x3800
	ds_read_b64_tr_b16 v[196:197], v185 offset:0x200
	ds_read_b64_tr_b16 v[198:199], v185 offset:0xa00
	ds_read_b64_tr_b16 v[200:201], v185 offset:0x1200
	ds_read_b64_tr_b16 v[202:203], v185 offset:0x1a00
	ds_read_b64_tr_b16 v[204:205], v185 offset:0x2200
	ds_read_b64_tr_b16 v[206:207], v185 offset:0x2a00
	ds_read_b64_tr_b16 v[208:209], v185 offset:0x3200
	ds_read_b64_tr_b16 v[210:211], v185 offset:0x3a00
	s_waitcnt lgkmcnt(8)
	s_nop 0
	v_mfma_f32_32x32x16_bf16 v[2:17], v[90:93], v[170:173], v[2:17]
	v_mfma_f32_32x32x16_bf16 v[2:17], v[94:97], v[174:177], v[2:17]
	v_mfma_f32_32x32x16_bf16 v[2:17], v[118:121], v[178:181], v[2:17]
	v_mfma_f32_32x32x16_bf16 v[2:17], v[122:125], v[192:195], v[2:17]
	ds_read_b64_tr_b16 v[170:171], v185 offset:0x400
	ds_read_b64_tr_b16 v[172:173], v185 offset:0xc00
	ds_read_b64_tr_b16 v[174:175], v185 offset:0x1400
	ds_read_b64_tr_b16 v[176:177], v185 offset:0x1c00
	ds_read_b64_tr_b16 v[178:179], v185 offset:0x2400
	ds_read_b64_tr_b16 v[180:181], v185 offset:0x2c00
	ds_read_b64_tr_b16 v[192:193], v185 offset:0x3400
	ds_read_b64_tr_b16 v[194:195], v185 offset:0x3c00
	s_waitcnt lgkmcnt(8)
	v_mfma_f32_32x32x16_bf16 v[18:33], v[90:93], v[196:199], v[18:33]
	v_mfma_f32_32x32x16_bf16 v[18:33], v[94:97], v[200:203], v[18:33]
	v_mfma_f32_32x32x16_bf16 v[18:33], v[118:121], v[204:207], v[18:33]
	v_mfma_f32_32x32x16_bf16 v[18:33], v[122:125], v[208:211], v[18:33]
	ds_read_b64_tr_b16 v[196:197], v185 offset:0x600
	ds_read_b64_tr_b16 v[198:199], v185 offset:0xe00
	ds_read_b64_tr_b16 v[200:201], v185 offset:0x1600
	ds_read_b64_tr_b16 v[202:203], v185 offset:0x1e00
	ds_read_b64_tr_b16 v[204:205], v185 offset:0x2600
	ds_read_b64_tr_b16 v[206:207], v185 offset:0x2e00
	ds_read_b64_tr_b16 v[208:209], v185 offset:0x3600
	ds_read_b64_tr_b16 v[210:211], v185 offset:0x3e00
	s_waitcnt lgkmcnt(8)
	v_mfma_f32_32x32x16_bf16 v[34:49], v[90:93], v[170:173], v[34:49]
	v_mfma_f32_32x32x16_bf16 v[34:49], v[94:97], v[174:177], v[34:49]
	v_mfma_f32_32x32x16_bf16 v[34:49], v[118:121], v[178:181], v[34:49]
	v_mfma_f32_32x32x16_bf16 v[34:49], v[122:125], v[192:195], v[34:49]
	s_waitcnt lgkmcnt(0)
	v_mfma_f32_32x32x16_bf16 v[50:65], v[90:93], v[196:199], v[50:65]
	v_mfma_f32_32x32x16_bf16 v[50:65], v[94:97], v[200:203], v[50:65]
	v_mfma_f32_32x32x16_bf16 v[50:65], v[118:121], v[204:207], v[50:65]
	v_mfma_f32_32x32x16_bf16 v[50:65], v[122:125], v[208:211], v[50:65]
	s_waitcnt vmcnt(0)
	v_cndmask_b32_e64 v68, 0, 1, s[16:17]
	v_cmp_ne_u32_e64 s[4:5], 1, v68
	s_andn2_b64 vcc, exec, s[16:17]
	s_waitcnt vmcnt(0)
	s_barrier
	s_cbranch_vccnz .LBB0_904
	s_lshl_b32 s0, s23, 6
	v_readlane_b32 s16, v242, 17
	v_readlane_b32 s17, v242, 18
	s_add_u32 s1, s16, s88
	s_addc_u32 s16, s17, s87
	s_lshl_b32 s0, s0, 1
	s_add_u32 s0, s1, s0
	s_addc_u32 s1, s16, 0
	v_lshl_add_u64 v[68:69], v[114:115], 1, s[0:1]
	s_mov_b64 s[0:1], 0x1800
	v_lshl_add_u64 v[68:69], v[68:69], 0, s[0:1]
	s_mov_b32 m0, s31
	s_nop 0
	global_load_lds_dwordx4 v[68:69], off
.LBB0_904:
	v_add_f32_e32 v1, v1, v116
	s_add_u32 s0, s18, 0x240000
	v_add_f32_e32 v1, 0, v1
	v_add_f32_e32 v66, v66, v67
	s_addc_u32 s1, s19, 0
	v_add_f32_e32 v1, v1, v66
	v_lshl_add_u64 v[66:67], v[72:73], 1, s[0:1]
	s_mov_b32 m0, s35
	v_exp_f32_e32 v175, v106
	global_load_lds_dwordx4 v[66:67], off
	v_lshl_add_u64 v[66:67], v[70:71], 1, s[0:1]
	s_mov_b32 m0, s86
	v_exp_f32_e32 v176, v107
	global_load_lds_dwordx4 v[66:67], off
	v_exp_f32_e32 v177, v108
	v_exp_f32_e32 v178, v109
	v_exp_f32_e32 v179, v110
	v_exp_f32_e32 v180, v111
	v_exp_f32_e32 v181, v112
	v_exp_f32_e32 v192, v113
	ds_read_b128 v[66:69], v188 offset:40960
	ds_read_b128 v[70:73], v188 offset:45056
	ds_read_b128 v[106:109], v189 offset:40960
	ds_read_b128 v[110:113], v189 offset:45056
	ds_read_b128 v[116:119], v190 offset:40960
	ds_read_b128 v[120:123], v190 offset:45056
	ds_read_b128 v[124:127], v191 offset:40960
	ds_read_b128 v[170:173], v191 offset:45056
	v_exp_f32_e32 v151, v98
	v_exp_f32_e32 v153, v99
	v_exp_f32_e32 v155, v100
	v_exp_f32_e32 v157, v101
	v_exp_f32_e32 v159, v102
	v_exp_f32_e32 v161, v103
	v_exp_f32_e32 v163, v104
	v_exp_f32_e32 v174, v105
	s_waitcnt lgkmcnt(0)
	v_mfma_f32_32x32x16_bf16 v[90:105], v[66:69], v[128:131], 0
	v_exp_f32_e32 v193, v74
	v_exp_f32_e32 v194, v75
	v_exp_f32_e32 v195, v76
	v_exp_f32_e32 v196, v77
	v_exp_f32_e32 v197, v78
	v_exp_f32_e32 v198, v79
	v_exp_f32_e32 v199, v80
	v_exp_f32_e32 v200, v81
	v_mfma_f32_32x32x16_bf16 v[66:81], v[70:73], v[128:131], 0
	v_mfma_f32_32x32x16_bf16 v[90:105], v[106:109], v[132:135], v[90:105]
	v_exp_f32_e32 v82, v82
	v_exp_f32_e32 v83, v83
	v_exp_f32_e32 v84, v84
	v_exp_f32_e32 v85, v85
	v_exp_f32_e32 v86, v86
	v_exp_f32_e32 v87, v87
	v_exp_f32_e32 v88, v88
	v_mfma_f32_32x32x16_bf16 v[66:81], v[110:113], v[132:135], v[66:81]
	v_exp_f32_e32 v89, v89
	v_add_f32_e32 v106, v151, v153
	v_add_f32_e32 v107, v193, v194
	v_mfma_f32_32x32x16_bf16 v[90:105], v[116:119], v[136:139], v[90:105]
	v_add_f32_e32 v106, v106, v155
	v_add_f32_e32 v107, v107, v195
	v_cvt_pk_bf16_f32 v108, v159, v161
	v_add_f32_e32 v106, v106, v157
	v_add_f32_e32 v107, v107, v196
	v_cvt_pk_bf16_f32 v109, v163, v174
	v_add_f32_e32 v106, v106, v159
	v_add_f32_e32 v107, v107, v197
	v_mfma_f32_32x32x16_bf16 v[66:81], v[120:123], v[136:139], v[66:81]
	v_add_f32_e32 v106, v106, v161
	v_add_f32_e32 v107, v107, v198
	s_nop 0
	v_add_f32_e32 v106, v106, v163
	v_add_f32_e32 v107, v107, v199
	s_nop 0
	v_add_f32_e32 v106, v106, v174
	v_add_f32_e32 v107, v107, v200
	s_nop 0
	v_add_f32_e32 v106, v106, v175
	v_add_f32_e32 v107, v107, v82
	s_nop 0
	v_add_f32_e32 v106, v106, v176
	v_add_f32_e32 v107, v107, v83
	s_nop 0
	v_add_f32_e32 v106, v106, v177
	v_add_f32_e32 v107, v107, v84
	s_nop 0
	v_add_f32_e32 v106, v106, v178
	v_add_f32_e32 v107, v107, v85
	s_nop 0
	v_add_f32_e32 v106, v106, v179
	v_add_f32_e32 v107, v107, v86
	s_nop 0
	v_add_f32_e32 v106, v106, v180
	v_add_f32_e32 v107, v107, v87
	s_nop 0
	v_add_f32_e32 v106, v106, v181
	v_add_f32_e32 v107, v107, v88
	s_nop 0
	v_add_f32_e32 v106, v106, v192
	v_add_f32_e32 v107, v107, v89
	s_nop 0
	v_add_f32_e32 v106, v106, v107
	v_mov_b32_e32 v107, v106
	s_nop 1
	v_permlane32_swap_b32_e32 v106, v107
	v_add_f32_e32 v106, v106, v107
	v_add_f32_e32 v149, v1, v106
	v_cvt_pk_bf16_f32 v106, v151, v153
	v_cvt_pk_bf16_f32 v107, v155, v157
	s_nop 0
	v_mfma_f32_32x32x16_bf16 v[90:105], v[124:127], v[140:143], v[90:105]
	v_cvt_pk_bf16_f32 v110, v175, v176
	v_cvt_pk_bf16_f32 v111, v177, v178
	v_cvt_pk_bf16_f32 v112, v179, v180
	v_cvt_pk_bf16_f32 v113, v181, v192
	v_cvt_pk_bf16_f32 v116, v193, v194
	v_cvt_pk_bf16_f32 v117, v195, v196
	v_cvt_pk_bf16_f32 v118, v197, v198
	v_mfma_f32_32x32x16_bf16 v[66:81], v[170:173], v[140:143], v[66:81]
	v_cvt_pk_bf16_f32 v119, v199, v200
	v_cvt_pk_bf16_f32 v120, v82, v83
	v_cvt_pk_bf16_f32 v121, v84, v85
	v_cvt_pk_bf16_f32 v122, v86, v87
	v_cvt_pk_bf16_f32 v123, v88, v89
	ds_read_b64_tr_b16 v[82:83], v184 offset:0
	ds_read_b64_tr_b16 v[84:85], v184 offset:0x800
	ds_read_b64_tr_b16 v[86:87], v184 offset:0x1000
	ds_read_b64_tr_b16 v[88:89], v184 offset:0x1800
	ds_read_b64_tr_b16 v[124:125], v184 offset:0x2000
	ds_read_b64_tr_b16 v[126:127], v184 offset:0x2800
	ds_read_b64_tr_b16 v[170:171], v184 offset:0x3000
	ds_read_b64_tr_b16 v[172:173], v184 offset:0x3800
	ds_read_b64_tr_b16 v[174:175], v184 offset:0x200
	ds_read_b64_tr_b16 v[176:177], v184 offset:0xa00
	ds_read_b64_tr_b16 v[178:179], v184 offset:0x1200
	ds_read_b64_tr_b16 v[180:181], v184 offset:0x1a00
	ds_read_b64_tr_b16 v[192:193], v184 offset:0x2200
	ds_read_b64_tr_b16 v[194:195], v184 offset:0x2a00
	ds_read_b64_tr_b16 v[196:197], v184 offset:0x3200
	ds_read_b64_tr_b16 v[198:199], v184 offset:0x3a00
	s_waitcnt lgkmcnt(8)
	s_nop 0
	v_mfma_f32_32x32x16_bf16 v[2:17], v[106:109], v[82:85], v[2:17]
	v_exp_f32_e32 v1, v91
	v_exp_f32_e32 v82, v92
	v_exp_f32_e32 v83, v93
	v_mfma_f32_32x32x16_bf16 v[2:17], v[110:113], v[86:89], v[2:17]
	v_exp_f32_e32 v88, v90
	v_mfma_f32_32x32x16_bf16 v[2:17], v[116:119], v[124:127], v[2:17]
	v_mfma_f32_32x32x16_bf16 v[2:17], v[120:123], v[170:173], v[2:17]
	ds_read_b64_tr_b16 v[90:91], v184 offset:0x400
	ds_read_b64_tr_b16 v[92:93], v184 offset:0xc00
	ds_read_b64_tr_b16 v[124:125], v184 offset:0x1400
	ds_read_b64_tr_b16 v[126:127], v184 offset:0x1c00
	ds_read_b64_tr_b16 v[170:171], v184 offset:0x2400
	ds_read_b64_tr_b16 v[172:173], v184 offset:0x2c00
	ds_read_b64_tr_b16 v[200:201], v184 offset:0x3400
	ds_read_b64_tr_b16 v[202:203], v184 offset:0x3c00
	s_waitcnt lgkmcnt(8)
	v_mfma_f32_32x32x16_bf16 v[18:33], v[106:109], v[174:177], v[18:33]
	v_exp_f32_e32 v84, v94
	v_exp_f32_e32 v85, v95
	v_exp_f32_e32 v86, v96
	v_exp_f32_e32 v87, v97
	v_mfma_f32_32x32x16_bf16 v[18:33], v[110:113], v[178:181], v[18:33]
	v_mfma_f32_32x32x16_bf16 v[18:33], v[116:119], v[192:195], v[18:33]
	v_mfma_f32_32x32x16_bf16 v[18:33], v[120:123], v[196:199], v[18:33]
	ds_read_b64_tr_b16 v[94:95], v184 offset:0x600
	ds_read_b64_tr_b16 v[96:97], v184 offset:0xe00
	ds_read_b64_tr_b16 v[174:175], v184 offset:0x1600
	ds_read_b64_tr_b16 v[176:177], v184 offset:0x1e00
	ds_read_b64_tr_b16 v[178:179], v184 offset:0x2600
	ds_read_b64_tr_b16 v[180:181], v184 offset:0x2e00
	ds_read_b64_tr_b16 v[192:193], v184 offset:0x3600
	ds_read_b64_tr_b16 v[194:195], v184 offset:0x3e00
	s_waitcnt lgkmcnt(8)
	v_mfma_f32_32x32x16_bf16 v[34:49], v[106:109], v[90:93], v[34:49]
	v_exp_f32_e32 v90, v98
	v_exp_f32_e32 v89, v99
	v_exp_f32_e32 v92, v100
	v_exp_f32_e32 v91, v101
	v_mfma_f32_32x32x16_bf16 v[34:49], v[110:113], v[124:127], v[34:49]
	v_mfma_f32_32x32x16_bf16 v[34:49], v[116:119], v[170:173], v[34:49]
	v_mfma_f32_32x32x16_bf16 v[34:49], v[120:123], v[200:203], v[34:49]
	s_waitcnt lgkmcnt(0)
	v_mfma_f32_32x32x16_bf16 v[50:65], v[106:109], v[94:97], v[50:65]
	v_exp_f32_e32 v94, v102
	v_exp_f32_e32 v93, v103
	v_exp_f32_e32 v95, v104
	v_exp_f32_e32 v151, v105
	v_mfma_f32_32x32x16_bf16 v[50:65], v[110:113], v[174:177], v[50:65]
	v_mfma_f32_32x32x16_bf16 v[50:65], v[116:119], v[178:181], v[50:65]
	v_mfma_f32_32x32x16_bf16 v[50:65], v[120:123], v[192:195], v[50:65]
	s_waitcnt vmcnt(0)
	s_and_b64 vcc, exec, s[4:5]
	s_waitcnt vmcnt(0)
	s_barrier
	s_cbranch_vccnz .LBB0_911
	v_readlane_b32 s36, v243, 63
	v_readlane_b32 s50, v242, 13
	v_readlane_b32 s51, v242, 14
	s_add_u32 s4, s50, s88
	v_mov_b32_e32 v96, s25
	v_mov_b32_e32 v97, v145
	s_addc_u32 s5, s51, s87
	s_add_i32 s92, s92, s91
	v_lshl_add_u64 v[170:171], v[114:115], 1, v[96:97]
	v_add_u32_e32 v96, s92, v182
	v_add_u32_e32 v97, s10, v166
	v_lshrrev_b32_e32 v98, 1, v96
	v_xor_b32_e32 v98, v98, v96
	v_and_b32_e32 v98, 4, v98
	v_lshl_or_b32 v98, v98, 1, v98
	v_xor_b32_e32 v96, v96, v98
	v_mul_lo_u32 v96, v96, s22
	v_and_b32_e32 v98, 0x60, v97
	v_or3_b32 v96, v169, v96, v98
	v_ashrrev_i32_e32 v97, 31, v96
	s_add_i32 s90, s90, s89
	v_lshlrev_b64 v[172:173], 1, v[96:97]
	v_add_u32_e32 v96, s90, v182
	v_lshrrev_b32_e32 v97, 1, v96
	v_xor_b32_e32 v97, v97, v96
	v_and_b32_e32 v97, 4, v97
	v_lshl_or_b32 v97, v97, 1, v97
	v_xor_b32_e32 v96, v96, v97
	v_mul_lo_u32 v96, v96, s22
	v_or3_b32 v96, v169, v96, v98
	v_ashrrev_i32_e32 v97, 31, v96
	v_lshlrev_b64 v[174:175], 1, v[96:97]
	v_or_b32_e32 v172, s24, v172
	v_or_b32_e32 v174, s24, v174
	s_mov_b32 s16, 6
	v_readlane_b32 s37, v242, 0
	v_readlane_b32 s38, v242, 1
	v_readlane_b32 s39, v242, 2
	v_readlane_b32 s40, v242, 3
	v_readlane_b32 s41, v242, 4
	v_readlane_b32 s42, v242, 5
	v_readlane_b32 s43, v242, 6
	v_readlane_b32 s44, v242, 7
	v_readlane_b32 s45, v242, 8
	v_readlane_b32 s46, v242, 9
	v_readlane_b32 s47, v242, 10
	v_readlane_b32 s48, v242, 11
	v_readlane_b32 s49, v242, 12
	v_exp_f32_e32 v222, v66
	v_exp_f32_e32 v223, v67
	v_exp_f32_e32 v224, v68
	v_exp_f32_e32 v225, v69
	v_exp_f32_e32 v226, v70
	v_exp_f32_e32 v227, v71
	v_exp_f32_e32 v228, v72
	v_exp_f32_e32 v229, v73
	v_exp_f32_e32 v230, v74
	v_exp_f32_e32 v231, v75
	v_exp_f32_e32 v232, v76
	v_exp_f32_e32 v233, v77
	v_exp_f32_e32 v234, v78
	v_exp_f32_e32 v235, v79
	v_exp_f32_e32 v236, v80
	v_exp_f32_e32 v237, v81
	s_branch .LBB0_907
.LBB0_906:
	v_lshl_add_u64 v[66:67], v[178:179], 0, s[12:13]
	s_mov_b32 m0, s35
	v_add_f32_e32 v1, v1, v70
	global_load_lds_dwordx4 v[66:67], off
	v_lshl_add_u64 v[66:67], v[176:177], 0, s[12:13]
	s_mov_b32 m0, s86
	global_load_lds_dwordx4 v[66:67], off
	ds_read_b128 v[66:69], v188 offset:40960
	ds_read_b128 v[70:73], v188 offset:45056
	ds_read_b128 v[82:85], v189 offset:40960
	ds_read_b128 v[86:89], v189 offset:45056
	ds_read_b128 v[90:93], v190 offset:40960
	ds_read_b128 v[176:179], v190 offset:45056
	ds_read_b128 v[192:195], v191 offset:40960
	ds_read_b128 v[196:199], v191 offset:45056
	v_add_f32_e32 v1, v149, v1
	s_waitcnt lgkmcnt(0)
	v_mfma_f32_32x32x16_bf16 v[112:127], v[66:69], v[128:131], 0
	v_mfma_f32_32x32x16_bf16 v[66:81], v[70:73], v[128:131], 0
	v_mfma_f32_32x32x16_bf16 v[66:81], v[86:89], v[132:135], v[66:81]
	v_mfma_f32_32x32x16_bf16 v[112:127], v[82:85], v[132:135], v[112:127]
	v_add_f32_e32 v86, v238, v239
	v_add_f32_e32 v87, v222, v223
	v_mfma_f32_32x32x16_bf16 v[66:81], v[176:179], v[136:139], v[66:81]
	v_add_f32_e32 v86, v86, v240
	v_add_f32_e32 v87, v87, v224
	v_cvt_pk_bf16_f32 v94, v238, v239
	v_add_f32_e32 v86, v86, v241
	v_add_f32_e32 v87, v87, v225
	v_cvt_pk_bf16_f32 v95, v240, v241
	v_add_f32_e32 v86, v86, v244
	v_add_f32_e32 v87, v87, v226
	v_cvt_pk_bf16_f32 v96, v244, v245
	v_add_f32_e32 v86, v86, v245
	v_add_f32_e32 v87, v87, v227
	v_cvt_pk_bf16_f32 v97, v246, v247
	v_add_f32_e32 v86, v86, v246
	v_add_f32_e32 v87, v87, v228
	s_nop 0
	v_add_f32_e32 v86, v86, v247
	v_add_f32_e32 v87, v87, v229
	v_add_f32_e32 v86, v86, v248
	v_add_f32_e32 v87, v87, v230
	v_mfma_f32_32x32x16_bf16 v[112:127], v[90:93], v[136:139], v[112:127]
	v_add_f32_e32 v86, v86, v249
	v_add_f32_e32 v87, v87, v231
	v_add_f32_e32 v86, v86, v250
	v_add_f32_e32 v87, v87, v232
	v_add_f32_e32 v86, v86, v251
	v_add_f32_e32 v87, v87, v233
	v_add_f32_e32 v86, v86, v252
	v_add_f32_e32 v87, v87, v234
	v_add_f32_e32 v86, v86, v253
	v_add_f32_e32 v87, v87, v235
	v_add_f32_e32 v86, v86, v254
	v_add_f32_e32 v87, v87, v236
	v_add_f32_e32 v86, v86, v255
	v_add_f32_e32 v87, v87, v237
	v_add_f32_e32 v86, v86, v87
	v_mov_b32_e32 v87, v86
	s_nop 1
	v_permlane32_swap_b32_e32 v86, v87
	v_add_f32_e32 v86, v86, v87
	v_add_f32_e32 v149, v1, v86
	v_mfma_f32_32x32x16_bf16 v[66:81], v[196:199], v[140:143], v[66:81]
	v_cvt_pk_bf16_f32 v98, v248, v249
	v_cvt_pk_bf16_f32 v99, v250, v251
	v_cvt_pk_bf16_f32 v100, v252, v253
	v_cvt_pk_bf16_f32 v101, v254, v255
	v_cvt_pk_bf16_f32 v102, v222, v223
	v_cvt_pk_bf16_f32 v103, v224, v225
	v_cvt_pk_bf16_f32 v104, v226, v227
	v_cvt_pk_bf16_f32 v105, v228, v229
	v_cvt_pk_bf16_f32 v106, v230, v231
	v_cvt_pk_bf16_f32 v107, v232, v233
	v_cvt_pk_bf16_f32 v108, v234, v235
	v_cvt_pk_bf16_f32 v109, v236, v237
	v_mfma_f32_32x32x16_bf16 v[112:127], v[192:195], v[140:143], v[112:127]
	ds_read_b64_tr_b16 v[82:83], v184 offset:0
	ds_read_b64_tr_b16 v[84:85], v184 offset:0x800
	ds_read_b64_tr_b16 v[86:87], v184 offset:0x1000
	ds_read_b64_tr_b16 v[88:89], v184 offset:0x1800
	ds_read_b64_tr_b16 v[90:91], v184 offset:0x2000
	ds_read_b64_tr_b16 v[92:93], v184 offset:0x2800
	ds_read_b64_tr_b16 v[176:177], v184 offset:0x3000
	ds_read_b64_tr_b16 v[178:179], v184 offset:0x3800
	ds_read_b64_tr_b16 v[192:193], v184 offset:0x200
	ds_read_b64_tr_b16 v[194:195], v184 offset:0xa00
	ds_read_b64_tr_b16 v[196:197], v184 offset:0x1200
	ds_read_b64_tr_b16 v[198:199], v184 offset:0x1a00
	ds_read_b64_tr_b16 v[200:201], v184 offset:0x2200
	ds_read_b64_tr_b16 v[202:203], v184 offset:0x2a00
	ds_read_b64_tr_b16 v[204:205], v184 offset:0x3200
	ds_read_b64_tr_b16 v[206:207], v184 offset:0x3a00
	s_waitcnt lgkmcnt(8)
	s_nop 0
	v_mfma_f32_32x32x16_bf16 v[2:17], v[94:97], v[82:85], v[2:17]
	v_exp_f32_e32 v222, v66
	s_nop 3
	v_exp_f32_e32 v1, v113
	v_exp_f32_e32 v82, v114
	v_exp_f32_e32 v83, v115
	v_mfma_f32_32x32x16_bf16 v[2:17], v[98:101], v[86:89], v[2:17]
	v_exp_f32_e32 v223, v67
	v_exp_f32_e32 v88, v112
	v_mfma_f32_32x32x16_bf16 v[2:17], v[102:105], v[90:93], v[2:17]
	v_exp_f32_e32 v224, v68
	v_mfma_f32_32x32x16_bf16 v[2:17], v[106:109], v[176:179], v[2:17]
	v_exp_f32_e32 v225, v69
	ds_read_b64_tr_b16 v[90:91], v184 offset:0x400
	ds_read_b64_tr_b16 v[92:93], v184 offset:0xc00
	ds_read_b64_tr_b16 v[110:111], v184 offset:0x1400
	ds_read_b64_tr_b16 v[112:113], v184 offset:0x1c00
	ds_read_b64_tr_b16 v[176:177], v184 offset:0x2400
	ds_read_b64_tr_b16 v[178:179], v184 offset:0x2c00
	ds_read_b64_tr_b16 v[208:209], v184 offset:0x3400
	ds_read_b64_tr_b16 v[210:211], v184 offset:0x3c00
	s_waitcnt lgkmcnt(8)
	v_mfma_f32_32x32x16_bf16 v[18:33], v[94:97], v[192:195], v[18:33]
	v_exp_f32_e32 v226, v70
	v_exp_f32_e32 v84, v116
	v_exp_f32_e32 v85, v117
	v_exp_f32_e32 v86, v118
	v_exp_f32_e32 v87, v119
	v_mfma_f32_32x32x16_bf16 v[18:33], v[98:101], v[196:199], v[18:33]
	v_exp_f32_e32 v227, v71
	v_mfma_f32_32x32x16_bf16 v[18:33], v[102:105], v[200:203], v[18:33]
	v_exp_f32_e32 v228, v72
	v_mfma_f32_32x32x16_bf16 v[18:33], v[106:109], v[204:207], v[18:33]
	v_exp_f32_e32 v229, v73
	ds_read_b64_tr_b16 v[114:115], v184 offset:0x600
	ds_read_b64_tr_b16 v[116:117], v184 offset:0xe00
	ds_read_b64_tr_b16 v[192:193], v184 offset:0x1600
	ds_read_b64_tr_b16 v[194:195], v184 offset:0x1e00
	ds_read_b64_tr_b16 v[196:197], v184 offset:0x2600
	ds_read_b64_tr_b16 v[198:199], v184 offset:0x2e00
	ds_read_b64_tr_b16 v[200:201], v184 offset:0x3600
	ds_read_b64_tr_b16 v[202:203], v184 offset:0x3e00
	s_waitcnt lgkmcnt(8)
	v_mfma_f32_32x32x16_bf16 v[34:49], v[94:97], v[90:93], v[34:49]
	v_exp_f32_e32 v230, v74
	v_exp_f32_e32 v90, v120
	v_exp_f32_e32 v89, v121
	v_exp_f32_e32 v92, v122
	v_exp_f32_e32 v91, v123
	v_mfma_f32_32x32x16_bf16 v[34:49], v[98:101], v[110:113], v[34:49]
	v_exp_f32_e32 v231, v75
	v_mfma_f32_32x32x16_bf16 v[34:49], v[102:105], v[176:179], v[34:49]
	v_exp_f32_e32 v232, v76
	v_mfma_f32_32x32x16_bf16 v[34:49], v[106:109], v[208:211], v[34:49]
	v_exp_f32_e32 v233, v77
	s_waitcnt lgkmcnt(0)
	v_mfma_f32_32x32x16_bf16 v[50:65], v[94:97], v[114:117], v[50:65]
	v_exp_f32_e32 v234, v78
	v_exp_f32_e32 v94, v124
	v_exp_f32_e32 v93, v125
	v_exp_f32_e32 v95, v126
	v_exp_f32_e32 v151, v127
	v_mfma_f32_32x32x16_bf16 v[50:65], v[98:101], v[192:195], v[50:65]
	v_exp_f32_e32 v235, v79
	v_mfma_f32_32x32x16_bf16 v[50:65], v[102:105], v[196:199], v[50:65]
	v_exp_f32_e32 v236, v80
	v_mfma_f32_32x32x16_bf16 v[50:65], v[106:109], v[200:203], v[50:65]
	v_exp_f32_e32 v237, v81
	s_waitcnt vmcnt(0)
	s_add_u32 s4, s4, 0x180000
	s_addc_u32 s5, s5, 0
	s_add_i32 s16, s16, 2
	s_and_b64 vcc, exec, s[0:1]
	s_waitcnt vmcnt(0)
	s_barrier
	s_cbranch_vccnz .LBB0_911

.LBB0_909:
	v_lshl_add_u64 v[178:179], s[4:5], 0, v[172:173]
	s_mov_b32 m0, s30
	v_lshl_add_u64 v[96:97], v[178:179], 0, s[8:9]
	v_lshl_add_u64 v[176:177], s[4:5], 0, v[174:175]
	global_load_lds_dwordx4 v[96:97], off
	v_lshl_add_u64 v[96:97], v[176:177], 0, s[8:9]
	s_mov_b32 m0, s33
	s_nop 0
	global_load_lds_dwordx4 v[96:97], off
	ds_read_b128 v[96:99], v188 offset:32768
	ds_read_b128 v[100:103], v188 offset:36864
	ds_read_b128 v[192:195], v189 offset:32768
	ds_read_b128 v[196:199], v189 offset:36864
	ds_read_b128 v[200:203], v190 offset:32768
	ds_read_b128 v[204:207], v190 offset:36864
	ds_read_b128 v[208:211], v191 offset:32768
	ds_read_b128 v[212:215], v191 offset:36864
	s_waitcnt lgkmcnt(0)
	v_mfma_f32_32x32x16_bf16 v[112:127], v[96:99], v[128:131], 0
	v_mfma_f32_32x32x16_bf16 v[96:111], v[100:103], v[128:131], 0
	v_mfma_f32_32x32x16_bf16 v[112:127], v[192:195], v[132:135], v[112:127]
	v_mfma_f32_32x32x16_bf16 v[96:111], v[196:199], v[132:135], v[96:111]
	v_add_f32_e32 v67, v88, v1
	v_cvt_pk_bf16_f32 v66, v88, v1
	v_add_f32_e32 v1, v222, v223
	v_add_f32_e32 v67, v67, v82
	v_mfma_f32_32x32x16_bf16 v[112:127], v[200:203], v[136:139], v[112:127]
	v_add_f32_e32 v1, v1, v224
	v_add_f32_e32 v67, v67, v83
	v_cvt_pk_bf16_f32 v68, v84, v85
	v_add_f32_e32 v1, v1, v225
	v_add_f32_e32 v67, v67, v84
	v_cvt_pk_bf16_f32 v69, v86, v87
	v_add_f32_e32 v1, v1, v226
	v_add_f32_e32 v67, v67, v85
	v_mfma_f32_32x32x16_bf16 v[96:111], v[204:207], v[136:139], v[96:111]
	v_add_f32_e32 v1, v1, v227
	v_add_f32_e32 v67, v67, v86
	v_add_f32_e32 v1, v1, v228
	v_add_f32_e32 v67, v67, v87
	v_add_f32_e32 v1, v1, v229
	v_add_f32_e32 v67, v67, v90
	v_add_f32_e32 v1, v1, v230
	v_add_f32_e32 v67, v67, v89
	v_add_f32_e32 v1, v1, v231
	v_add_f32_e32 v67, v67, v92
	v_add_f32_e32 v1, v1, v232
	v_add_f32_e32 v67, v67, v91
	v_add_f32_e32 v1, v1, v233
	v_add_f32_e32 v67, v67, v94
	v_add_f32_e32 v1, v1, v234
	v_add_f32_e32 v67, v67, v93
	v_add_f32_e32 v1, v1, v235
	v_add_f32_e32 v67, v67, v95
	v_add_f32_e32 v1, v1, v236
	v_add_f32_e32 v67, v67, v151
	v_add_f32_e32 v1, v1, v237
	v_add_f32_e32 v1, v67, v1
	v_mov_b32_e32 v70, v1
	s_nop 1
	v_permlane32_swap_b32_e32 v1, v70
	v_cvt_pk_bf16_f32 v67, v82, v83
	s_nop 1
	v_mfma_f32_32x32x16_bf16 v[112:127], v[208:211], v[140:143], v[112:127]
	v_cvt_pk_bf16_f32 v72, v90, v89
	v_cvt_pk_bf16_f32 v73, v92, v91
	v_cvt_pk_bf16_f32 v74, v94, v93
	v_cvt_pk_bf16_f32 v75, v95, v151
	v_cvt_pk_bf16_f32 v76, v222, v223
	v_cvt_pk_bf16_f32 v77, v224, v225
	v_cvt_pk_bf16_f32 v78, v226, v227
	v_mfma_f32_32x32x16_bf16 v[96:111], v[212:215], v[140:143], v[96:111]
	v_cvt_pk_bf16_f32 v79, v228, v229
	v_cvt_pk_bf16_f32 v80, v230, v231
	v_cvt_pk_bf16_f32 v81, v232, v233
	v_cvt_pk_bf16_f32 v82, v234, v235
	v_cvt_pk_bf16_f32 v83, v236, v237
	ds_read_b64_tr_b16 v[84:85], v185 offset:0
	ds_read_b64_tr_b16 v[86:87], v185 offset:0x800
	ds_read_b64_tr_b16 v[88:89], v185 offset:0x1000
	ds_read_b64_tr_b16 v[90:91], v185 offset:0x1800
	ds_read_b64_tr_b16 v[92:93], v185 offset:0x2000
	ds_read_b64_tr_b16 v[94:95], v185 offset:0x2800
	ds_read_b64_tr_b16 v[192:193], v185 offset:0x3000
	ds_read_b64_tr_b16 v[194:195], v185 offset:0x3800
	ds_read_b64_tr_b16 v[196:197], v185 offset:0x200
	ds_read_b64_tr_b16 v[198:199], v185 offset:0xa00
	ds_read_b64_tr_b16 v[200:201], v185 offset:0x1200
	ds_read_b64_tr_b16 v[202:203], v185 offset:0x1a00
	ds_read_b64_tr_b16 v[204:205], v185 offset:0x2200
	ds_read_b64_tr_b16 v[206:207], v185 offset:0x2a00
	ds_read_b64_tr_b16 v[208:209], v185 offset:0x3200
	ds_read_b64_tr_b16 v[210:211], v185 offset:0x3a00
	s_waitcnt lgkmcnt(8)
	s_nop 0
	v_mfma_f32_32x32x16_bf16 v[2:17], v[66:69], v[84:87], v[2:17]
	v_exp_f32_e32 v238, v112
	v_exp_f32_e32 v239, v113
	v_mfma_f32_32x32x16_bf16 v[2:17], v[72:75], v[88:91], v[2:17]
	v_exp_f32_e32 v240, v114
	v_exp_f32_e32 v241, v115
	v_mfma_f32_32x32x16_bf16 v[2:17], v[76:79], v[92:95], v[2:17]
	v_exp_f32_e32 v244, v116
	v_exp_f32_e32 v245, v117
	v_mfma_f32_32x32x16_bf16 v[2:17], v[80:83], v[192:195], v[2:17]
	v_exp_f32_e32 v246, v118
	v_exp_f32_e32 v247, v119
	ds_read_b64_tr_b16 v[84:85], v185 offset:0x400
	ds_read_b64_tr_b16 v[86:87], v185 offset:0xc00
	ds_read_b64_tr_b16 v[88:89], v185 offset:0x1400
	ds_read_b64_tr_b16 v[90:91], v185 offset:0x1c00
	ds_read_b64_tr_b16 v[92:93], v185 offset:0x2400
	ds_read_b64_tr_b16 v[94:95], v185 offset:0x2c00
	ds_read_b64_tr_b16 v[192:193], v185 offset:0x3400
	ds_read_b64_tr_b16 v[194:195], v185 offset:0x3c00
	s_waitcnt lgkmcnt(8)
	v_mfma_f32_32x32x16_bf16 v[18:33], v[66:69], v[196:199], v[18:33]
	v_exp_f32_e32 v248, v120
	v_exp_f32_e32 v249, v121
	v_mfma_f32_32x32x16_bf16 v[18:33], v[72:75], v[200:203], v[18:33]
	v_exp_f32_e32 v250, v122
	v_exp_f32_e32 v251, v123
	v_mfma_f32_32x32x16_bf16 v[18:33], v[76:79], v[204:207], v[18:33]
	v_exp_f32_e32 v252, v124
	v_exp_f32_e32 v253, v125
	v_mfma_f32_32x32x16_bf16 v[18:33], v[80:83], v[208:211], v[18:33]
	v_exp_f32_e32 v254, v126
	v_exp_f32_e32 v255, v127
	ds_read_b64_tr_b16 v[196:197], v185 offset:0x600
	ds_read_b64_tr_b16 v[198:199], v185 offset:0xe00
	ds_read_b64_tr_b16 v[200:201], v185 offset:0x1600
	ds_read_b64_tr_b16 v[202:203], v185 offset:0x1e00
	ds_read_b64_tr_b16 v[204:205], v185 offset:0x2600
	ds_read_b64_tr_b16 v[206:207], v185 offset:0x2e00
	ds_read_b64_tr_b16 v[208:209], v185 offset:0x3600
	ds_read_b64_tr_b16 v[210:211], v185 offset:0x3e00
	s_waitcnt lgkmcnt(8)
	v_mfma_f32_32x32x16_bf16 v[34:49], v[66:69], v[84:87], v[34:49]
	v_exp_f32_e32 v222, v96
	v_exp_f32_e32 v223, v97
	v_mfma_f32_32x32x16_bf16 v[34:49], v[72:75], v[88:91], v[34:49]
	v_exp_f32_e32 v224, v98
	v_exp_f32_e32 v225, v99
	v_mfma_f32_32x32x16_bf16 v[34:49], v[76:79], v[92:95], v[34:49]
	v_exp_f32_e32 v226, v100
	v_exp_f32_e32 v227, v101
	v_mfma_f32_32x32x16_bf16 v[34:49], v[80:83], v[192:195], v[34:49]
	v_exp_f32_e32 v228, v102
	v_exp_f32_e32 v229, v103
	s_waitcnt lgkmcnt(0)
	v_mfma_f32_32x32x16_bf16 v[50:65], v[66:69], v[196:199], v[50:65]
	v_exp_f32_e32 v230, v104
	v_exp_f32_e32 v231, v105
	v_mfma_f32_32x32x16_bf16 v[50:65], v[72:75], v[200:203], v[50:65]
	v_exp_f32_e32 v232, v106
	v_exp_f32_e32 v233, v107
	v_mfma_f32_32x32x16_bf16 v[50:65], v[76:79], v[204:207], v[50:65]
	v_exp_f32_e32 v234, v108
	v_exp_f32_e32 v235, v109
	v_mfma_f32_32x32x16_bf16 v[50:65], v[80:83], v[208:211], v[50:65]
	v_exp_f32_e32 v236, v110
	v_exp_f32_e32 v237, v111
	s_waitcnt vmcnt(0)
	s_cmp_ge_u32 s16, s11
	s_cselect_b64 s[0:1], -1, 0
	s_and_b64 vcc, exec, s[0:1]
	s_waitcnt vmcnt(0)
	s_barrier
	s_cbranch_vccnz .LBB0_906
	s_mov_b64 s[18:19], 0x15c81800
	v_lshl_add_u64 v[66:67], v[180:181], 0, s[18:19]
	s_mov_b32 m0, s31
	s_nop 0
	global_load_lds_dwordx4 v[66:67], off
	s_branch .LBB0_906
.LBB0_911:
	v_exp_f32_e32 v96, v66
	v_add_f32_e32 v66, 0, v88
	v_add_f32_e32 v66, v1, v66
	v_add_f32_e32 v66, v66, v82
	v_add_f32_e32 v66, v83, v66
	v_add_f32_e32 v66, v66, v84
	v_add_f32_e32 v66, v85, v66
	v_add_f32_e32 v66, v66, v86
	v_add_f32_e32 v66, v87, v66
	v_add_f32_e32 v66, v66, v90
	v_add_f32_e32 v66, v89, v66
	v_add_f32_e32 v66, v66, v92
	v_add_f32_e32 v66, v91, v66
	v_add_f32_e32 v66, v66, v94
	v_exp_f32_e32 v97, v67
	v_add_f32_e32 v66, v93, v66
	v_exp_f32_e32 v98, v68
	v_add_f32_e32 v66, v66, v95
	v_exp_f32_e32 v99, v69
	v_add_f32_e32 v66, v151, v66
	v_exp_f32_e32 v100, v70
	v_add_f32_e32 v66, v96, v66
	v_exp_f32_e32 v101, v71
	v_add_f32_e32 v66, v97, v66
	v_exp_f32_e32 v102, v72
	v_add_f32_e32 v66, v98, v66
	v_exp_f32_e32 v103, v73
	v_add_f32_e32 v66, v99, v66
	v_exp_f32_e32 v104, v74
	v_add_f32_e32 v66, v100, v66
	v_exp_f32_e32 v105, v75
	v_add_f32_e32 v66, v101, v66
	v_exp_f32_e32 v106, v76
	v_add_f32_e32 v66, v102, v66
	v_exp_f32_e32 v107, v77
	v_add_f32_e32 v66, v103, v66
	v_exp_f32_e32 v108, v78
	v_add_f32_e32 v66, v104, v66
	v_exp_f32_e32 v109, v79
	v_add_f32_e32 v66, v105, v66
	v_exp_f32_e32 v110, v80
	v_add_f32_e32 v66, v106, v66
	v_exp_f32_e32 v111, v81
	v_add_f32_e32 v66, v107, v66
	v_add_f32_e32 v66, v108, v66
	v_add_f32_e32 v66, v109, v66
	v_add_f32_e32 v66, v110, v66
	s_lshl_b32 s0, s10, 2
	v_add_f32_e32 v66, v111, v66
	v_readlane_b32 s44, v243, 63
	s_add_i32 s4, s0, 0
	v_mov_b32_e32 v67, v66
	v_readlane_b32 s45, v242, 0
	v_readlane_b32 s46, v242, 1
	v_readlane_b32 s47, v242, 2
	v_readlane_b32 s48, v242, 3
	v_readlane_b32 s49, v242, 4
	v_readlane_b32 s50, v242, 5
	v_readlane_b32 s51, v242, 6
	v_readlane_b32 s52, v242, 7
	v_readlane_b32 s53, v242, 8
	v_readlane_b32 s54, v242, 9
	v_readlane_b32 s55, v242, 10
	v_readlane_b32 s56, v242, 11
	v_readlane_b32 s57, v242, 12
	v_readlane_b32 s58, v242, 13
	v_readlane_b32 s59, v242, 14
	s_add_i32 s4, s4, 0x1e000
	v_permlane32_swap_b32_e32 v66, v67
	v_cvt_pk_bf16_f32 v68, v88, v1
	v_cvt_pk_bf16_f32 v69, v82, v83
	v_cvt_pk_bf16_f32 v70, v84, v85
	v_cvt_pk_bf16_f32 v71, v86, v87
	v_cvt_pk_bf16_f32 v72, v90, v89
	v_cvt_pk_bf16_f32 v73, v92, v91
	v_cvt_pk_bf16_f32 v74, v94, v93
	v_cvt_pk_bf16_f32 v75, v95, v151
	v_cvt_pk_bf16_f32 v76, v96, v97
	v_cvt_pk_bf16_f32 v77, v98, v99
	v_cvt_pk_bf16_f32 v78, v100, v101
	v_cvt_pk_bf16_f32 v79, v102, v103
	v_cvt_pk_bf16_f32 v80, v104, v105
	v_cvt_pk_bf16_f32 v81, v106, v107
	v_cvt_pk_bf16_f32 v82, v108, v109
	v_cvt_pk_bf16_f32 v83, v110, v111
	ds_read_b64_tr_b16 v[84:85], v185 offset:0
	ds_read_b64_tr_b16 v[86:87], v185 offset:0x800
	ds_read_b64_tr_b16 v[88:89], v185 offset:0x1000
	ds_read_b64_tr_b16 v[90:91], v185 offset:0x1800
	ds_read_b64_tr_b16 v[92:93], v185 offset:0x2000
	ds_read_b64_tr_b16 v[94:95], v185 offset:0x2800
	ds_read_b64_tr_b16 v[96:97], v185 offset:0x3000
	ds_read_b64_tr_b16 v[98:99], v185 offset:0x3800
	s_waitcnt lgkmcnt(0)
	s_nop 0
	v_mfma_f32_32x32x16_bf16 v[2:17], v[68:71], v[84:87], v[2:17]
	ds_read_b64_tr_b16 v[84:85], v185 offset:0x200
	ds_read_b64_tr_b16 v[86:87], v185 offset:0xa00
	v_mfma_f32_32x32x16_bf16 v[2:17], v[72:75], v[88:91], v[2:17]
	ds_read_b64_tr_b16 v[88:89], v185 offset:0x1200
	ds_read_b64_tr_b16 v[90:91], v185 offset:0x1a00
	v_mfma_f32_32x32x16_bf16 v[2:17], v[76:79], v[92:95], v[2:17]
	ds_read_b64_tr_b16 v[92:93], v185 offset:0x2200
	ds_read_b64_tr_b16 v[94:95], v185 offset:0x2a00
	ds_read_b64_tr_b16 v[100:101], v185 offset:0x3200
	ds_read_b64_tr_b16 v[102:103], v185 offset:0x3a00
	s_waitcnt lgkmcnt(0)
	v_mfma_f32_32x32x16_bf16 v[2:17], v[80:83], v[96:99], v[2:17]
	v_mfma_f32_32x32x16_bf16 v[18:33], v[68:71], v[84:87], v[18:33]
	ds_read_b64_tr_b16 v[84:85], v185 offset:0x400
	ds_read_b64_tr_b16 v[86:87], v185 offset:0xc00
	v_mfma_f32_32x32x16_bf16 v[18:33], v[72:75], v[88:91], v[18:33]
	ds_read_b64_tr_b16 v[88:89], v185 offset:0x1400
	ds_read_b64_tr_b16 v[90:91], v185 offset:0x1c00
	v_mfma_f32_32x32x16_bf16 v[18:33], v[76:79], v[92:95], v[18:33]
	ds_read_b64_tr_b16 v[92:93], v185 offset:0x2400
	ds_read_b64_tr_b16 v[94:95], v185 offset:0x2c00
	ds_read_b64_tr_b16 v[96:97], v185 offset:0x3400
	ds_read_b64_tr_b16 v[98:99], v185 offset:0x3c00
	s_waitcnt lgkmcnt(0)
	v_mfma_f32_32x32x16_bf16 v[18:33], v[80:83], v[100:103], v[18:33]
	v_mfma_f32_32x32x16_bf16 v[34:49], v[68:71], v[84:87], v[34:49]
	ds_read_b64_tr_b16 v[84:85], v185 offset:0x600
	ds_read_b64_tr_b16 v[86:87], v185 offset:0xe00
	v_mfma_f32_32x32x16_bf16 v[34:49], v[72:75], v[88:91], v[34:49]
	ds_read_b64_tr_b16 v[88:89], v185 offset:0x1600
	ds_read_b64_tr_b16 v[90:91], v185 offset:0x1e00
	v_mfma_f32_32x32x16_bf16 v[34:49], v[76:79], v[92:95], v[34:49]
	ds_read_b64_tr_b16 v[92:93], v185 offset:0x2600
	ds_read_b64_tr_b16 v[94:95], v185 offset:0x2e00
	ds_read_b64_tr_b16 v[100:101], v185 offset:0x3600
	ds_read_b64_tr_b16 v[102:103], v185 offset:0x3e00
	s_waitcnt lgkmcnt(0)
	v_mfma_f32_32x32x16_bf16 v[34:49], v[80:83], v[96:99], v[34:49]
	v_mfma_f32_32x32x16_bf16 v[50:65], v[68:71], v[84:87], v[50:65]
	s_barrier
	v_mfma_f32_32x32x16_bf16 v[50:65], v[72:75], v[88:91], v[50:65]
	v_mfma_f32_32x32x16_bf16 v[50:65], v[76:79], v[92:95], v[50:65]
	v_mfma_f32_32x32x16_bf16 v[50:65], v[80:83], v[100:103], v[50:65]
	s_and_saveexec_b64 s[0:1], s[2:3]
	s_cbranch_execz .LBB0_897
	v_add_f32_e32 v1, v66, v67
	v_add_f32_e32 v1, v149, v1
	v_lshl_add_u32 v66, v165, 2, s4
	ds_write_b32 v66, v1
	s_branch .LBB0_897

.LBB0_2311:
	s_ashr_i32 s14, s33, 9
	s_ashr_i32 s15, s14, 31
	s_lshl_b32 s0, s33, 8
	s_lshl_b64 s[8:9], s[14:15], 14
	s_and_b32 s0, s0, 0x3f00
	s_or_b32 s8, s8, s0
	s_lshl_b32 s0, s14, 8
	s_add_i32 s0, s0, 0x8000
	s_mul_i32 s4, s9, 0xc00
	s_mul_hi_u32 s12, s8, 0xc00
	s_bfe_u32 s36, s33, 0x30006
	s_ashr_i32 s1, s0, 31
	s_add_i32 s12, s12, s4
	s_mul_i32 s4, s8, 0xc00
	v_readlane_b32 s28, v242, 21
	v_readlane_b32 s29, v242, 22
	s_add_u32 s4, s28, s4
	s_addc_u32 s12, s29, s12
	s_mul_i32 s21, s36, 0x180
	s_add_u32 s28, s4, s21
	s_addc_u32 s29, s12, 0
	s_mul_i32 s12, s0, 0xc00
	s_mul_hi_i32 s4, s0, 0xc00
	s_add_u32 s12, s24, s12
	s_addc_u32 s4, s25, s4
	s_add_u32 s12, s12, s21
	s_addc_u32 s13, s4, 0
	s_mul_i32 s35, s14, 0x3000000
	s_mul_hi_i32 s4, s14, 0x3000000
	s_add_u32 s35, s24, s35
	s_addc_u32 s4, s25, s4
	s_add_u32 s38, s35, s21
	s_addc_u32 s39, s4, 0
	s_lshl_b64 s[0:1], s[0:1], 12
	s_add_u32 s0, s31, s0
	s_addc_u32 s1, s34, s1
	s_lshl_b32 s4, s36, 9
	s_add_u32 s0, s0, s4
	s_addc_u32 s1, s1, 0
	s_add_u32 s44, s0, 0x100
	s_addc_u32 s45, s1, 0
	s_lshl_b64 s[14:15], s[14:15], 26
	s_add_u32 s14, s31, s14
	s_addc_u32 s15, s34, s15
	s_add_u32 s4, s14, s4
	s_addc_u32 s14, s15, 0
	s_add_u32 s46, s4, 0x100
	v_readfirstlane_b32 s52, v0
	s_addc_u32 s47, s14, 0
	s_lshr_b32 s37, s52, 6
	s_lshl_b32 s35, s37, 5
	v_or_b32_e32 v4, s35, v165
	v_mov_b64_e32 v[2:3], s[28:29]
	v_mad_u64_u32 v[2:3], s[14:15], v4, s19, v[2:3]
	s_andn2_b32 s52, s52, 63
	v_lshl_add_u64 v[2:3], v[2:3], 0, v[148:149]
	global_load_dwordx4 v[142:145], v[2:3], off
	global_load_dwordx4 v[138:141], v[2:3], off offset:32
	global_load_dwordx4 v[134:137], v[2:3], off offset:64
	global_load_dwordx4 v[130:133], v[2:3], off offset:96
	global_load_dwordx4 v[126:129], v[2:3], off offset:128
	global_load_dwordx4 v[122:125], v[2:3], off offset:160
	global_load_dwordx4 v[118:121], v[2:3], off offset:192
	global_load_dwordx4 v[114:117], v[2:3], off offset:224
	global_load_dwordx4 v[110:113], v[2:3], off offset:256
	global_load_dwordx4 v[106:109], v[2:3], off offset:288
	global_load_dwordx4 v[102:105], v[2:3], off offset:320
	global_load_dwordx4 v[98:101], v[2:3], off offset:352
	v_or_b32_e32 v2, s52, v166
	v_mul_hi_i32 v3, v2, s20
	v_lshrrev_b32_e32 v4, 31, v3
	v_ashrrev_i32_e32 v3, 2, v3
	v_add_u32_e32 v3, v3, v4
	v_mul_lo_u32 v4, v3, 24
	v_sub_u32_e32 v4, v2, v4
	v_mul_lo_u32 v5, v3, s22
	v_lshrrev_b32_e32 v3, 1, v3
	v_bitop3_b32 v3, v3, v4, 7 bitop3:0x6c
	v_lshl_add_u32 v160, v3, 3, v5
	v_add_u32_e32 v3, 0x200, v2
	v_mul_hi_i32 v4, v3, s20
	v_lshrrev_b32_e32 v5, 31, v4
	v_ashrrev_i32_e32 v4, 2, v4
	v_add_u32_e32 v4, v4, v5
	v_mul_lo_u32 v5, v4, 24
	v_sub_u32_e32 v3, v3, v5
	v_mul_lo_u32 v5, v4, s22
	v_lshrrev_b32_e32 v4, 1, v4
	v_bitop3_b32 v3, v4, v3, 7 bitop3:0x6c
	v_lshl_add_u32 v162, v3, 3, v5
	v_add_u32_e32 v3, 0x400, v2
	v_mul_hi_i32 v4, v3, s20
	v_lshrrev_b32_e32 v5, 31, v4
	v_ashrrev_i32_e32 v4, 2, v4
	v_add_u32_e32 v4, v4, v5
	s_ashr_i32 s4, s52, 4
	v_mul_lo_u32 v5, v4, 24
	s_and_b32 s14, s4, 0x1ffff0
	s_lshr_b32 s4, s4, 1
	v_sub_u32_e32 v3, v3, v5
	v_mul_lo_u32 v5, v4, s22
	v_lshrrev_b32_e32 v4, 1, v4
	s_and_b32 s4, s4, 4
	v_bitop3_b32 v3, v4, v3, 7 bitop3:0x6c
	s_or_b32 s4, s14, s4
	v_lshl_add_u32 v168, v3, 3, v5
	v_or_b32_e32 v3, s4, v178
	v_lshrrev_b32_e32 v171, 1, v3
	v_xor_b32_e32 v171, v171, v3
	v_and_b32_e32 v171, 4, v171
	v_lshl_or_b32 v171, v171, 1, v171
	v_xor_b32_e32 v3, v3, v171
	s_add_i32 s4, s52, 0x200
	s_ashr_i32 s4, s4, 4
	s_and_b32 s14, s4, 0x1ffff0
	s_lshr_b32 s4, s4, 1
	s_and_b32 s4, s4, 4
	v_and_or_b32 v2, v2, s16, v177
	s_or_b32 s4, s14, s4
	v_lshl_or_b32 v170, v3, 11, v2
	v_or_b32_e32 v3, s4, v178
	v_lshrrev_b32_e32 v173, 1, v3
	v_xor_b32_e32 v173, v173, v3
	v_and_b32_e32 v173, 4, v173
	v_lshl_or_b32 v173, v173, 1, v173
	v_xor_b32_e32 v3, v3, v173
	s_lshl_b32 s4, s37, 10
	s_add_i32 s53, s4, 0
	v_ashrrev_i32_e32 v161, 31, v160
	v_lshl_or_b32 v172, v3, 11, v2
	s_add_i32 m0, s53, 0x8000
	v_lshl_add_u64 v[2:3], v[160:161], 1, s[12:13]
	v_ashrrev_i32_e32 v163, 31, v162
	global_load_lds_dwordx4 v[2:3], off
	v_lshl_add_u64 v[2:3], v[162:163], 1, s[12:13]
	s_add_i32 m0, s53, 0xa000
	v_ashrrev_i32_e32 v169, 31, v168
	global_load_lds_dwordx4 v[2:3], off
	v_lshl_add_u64 v[2:3], v[168:169], 1, s[12:13]
	s_add_i32 m0, s53, 0xc000
	v_ashrrev_i32_e32 v171, 31, v170
	global_load_lds_dwordx4 v[2:3], off
	v_lshl_add_u64 v[2:3], v[170:171], 1, s[0:1]
	v_lshl_add_u64 v[2:3], v[2:3], 0, s[6:7]
	s_mov_b32 m0, s53
	v_ashrrev_i32_e32 v173, 31, v172
	global_load_lds_dwordx4 v[2:3], off
	v_lshl_add_u64 v[2:3], v[172:173], 1, s[0:1]
	v_lshl_add_u64 v[2:3], v[2:3], 0, s[6:7]
	s_add_i32 m0, s53, 0x2000
	s_mov_b32 s4, -3
	global_load_lds_dwordx4 v[2:3], off
	s_waitcnt vmcnt(0)
	s_mov_b64 s[0:1], 64
	v_mov_b32_e32 v151, 0
	v_mov_b32_e32 v2, 0
	v_mov_b32_e32 v3, v147
	v_mov_b32_e32 v4, v147
	v_mov_b32_e32 v5, v147
	v_mov_b32_e32 v6, v147
	v_mov_b32_e32 v7, v147
	v_mov_b32_e32 v8, v147
	v_mov_b32_e32 v9, v147
	v_mov_b32_e32 v10, v147
	v_mov_b32_e32 v11, v147
	v_mov_b32_e32 v12, v147
	v_mov_b32_e32 v13, v147
	v_mov_b32_e32 v14, v147
	v_mov_b32_e32 v15, v147
	v_mov_b32_e32 v16, v147
	v_mov_b32_e32 v17, v147
	v_mov_b32_e32 v18, 0
	v_mov_b32_e32 v19, v147
	v_mov_b32_e32 v20, v147
	v_mov_b32_e32 v21, v147
	v_mov_b32_e32 v22, v147
	v_mov_b32_e32 v23, v147
	v_mov_b32_e32 v24, v147
	v_mov_b32_e32 v25, v147
	v_mov_b32_e32 v26, v147
	v_mov_b32_e32 v27, v147
	v_mov_b32_e32 v28, v147
	v_mov_b32_e32 v29, v147
	v_mov_b32_e32 v30, v147
	v_mov_b32_e32 v31, v147
	v_mov_b32_e32 v32, v147
	v_mov_b32_e32 v33, v147
	v_mov_b32_e32 v34, 0
	v_mov_b32_e32 v35, v147
	v_mov_b32_e32 v36, v147
	v_mov_b32_e32 v37, v147
	v_mov_b32_e32 v38, v147
	v_mov_b32_e32 v39, v147
	v_mov_b32_e32 v40, v147
	v_mov_b32_e32 v41, v147
	v_mov_b32_e32 v42, v147
	v_mov_b32_e32 v43, v147
	v_mov_b32_e32 v44, v147
	v_mov_b32_e32 v45, v147
	v_mov_b32_e32 v46, v147
	v_mov_b32_e32 v47, v147
	v_mov_b32_e32 v48, v147
	v_mov_b32_e32 v49, v147
	v_mov_b32_e32 v50, 0
	v_mov_b32_e32 v51, v147
	v_mov_b32_e32 v52, v147
	v_mov_b32_e32 v53, v147
	v_mov_b32_e32 v54, v147
	v_mov_b32_e32 v55, v147
	v_mov_b32_e32 v56, v147
	v_mov_b32_e32 v57, v147
	v_mov_b32_e32 v58, v147
	v_mov_b32_e32 v59, v147
	v_mov_b32_e32 v60, v147
	v_mov_b32_e32 v61, v147
	v_mov_b32_e32 v62, v147
	v_mov_b32_e32 v63, v147
	v_mov_b32_e32 v64, v147
	v_mov_b32_e32 v65, v147
	s_waitcnt vmcnt(0) lgkmcnt(0)
	s_barrier
.LBB0_2312:
	v_add_co_u32_e64 v66, s[14:15], s4, 3
	s_nop 0
	v_readfirstlane_b32 s21, v66
	s_and_b32 s21, s21, 1
	s_lshl_b64 s[28:29], s[4:5], 6
	s_and_b64 s[40:41], s[14:15], exec
	s_cselect_b32 s29, s1, s29
	s_cselect_b32 s28, s0, s28
	s_mul_i32 s42, s29, 0xc00
	s_mul_hi_u32 s43, s28, 0xc00
	s_cselect_b32 s41, s13, s39
	s_cselect_b32 s40, s12, s38
	s_add_i32 s43, s43, s42
	s_mul_i32 s42, s28, 0xc00
	s_add_u32 s40, s40, s42
	s_addc_u32 s41, s41, s43
	s_xor_b32 s42, s21, 1
	s_mulk_i32 s42, 0x6000
	s_add_i32 s42, s53, s42
	s_add_i32 m0, s42, 0x8000
	v_lshl_add_u64 v[66:67], v[160:161], 1, s[40:41]
	global_load_lds_dwordx4 v[66:67], off
	v_lshl_add_u64 v[66:67], v[162:163], 1, s[40:41]
	s_add_i32 m0, s42, 0xa000
	s_lshl_b64 s[28:29], s[28:29], 12
	global_load_lds_dwordx4 v[66:67], off
	s_add_i32 m0, s42, 0xc000
	s_and_b64 s[14:15], s[14:15], exec
	s_cselect_b32 s14, s44, s46
	s_cselect_b32 s15, s45, s47
	s_add_u32 s14, s14, s28
	s_addc_u32 s15, s15, s29
	s_lshl_b32 s28, s21, 14
	s_xor_b32 s29, s28, 0x4000
	v_lshl_add_u64 v[66:67], v[168:169], 1, s[40:41]
	s_add_i32 s29, s53, s29
	global_load_lds_dwordx4 v[66:67], off
	v_lshl_add_u64 v[66:67], v[170:171], 1, s[14:15]
	s_mov_b32 m0, s29
	s_mulk_i32 s21, 0x6000
	global_load_lds_dwordx4 v[66:67], off
	v_lshl_add_u64 v[66:67], v[172:173], 1, s[14:15]
	s_add_i32 m0, s29, 0x2000
	s_nop 0
	global_load_lds_dwordx4 v[66:67], off
	v_add_u32_e32 v74, s21, v182
	v_add_u32_e32 v75, v74, v181
	ds_read_b128 v[66:69], v75 offset:32768
	v_add_u32_e32 v76, v74, v183
	ds_read_b128 v[70:73], v76 offset:32768
	v_add_u32_e32 v153, v74, v184
	v_add_u32_e32 v155, v74, v185
	v_add_u32_e32 v157, v74, v186
	v_add_u32_e32 v159, v74, v187
	v_add_u32_e32 v209, v74, v188
	v_add_u32_e32 v218, v74, v189
	s_waitcnt lgkmcnt(0)
	v_mfma_f32_32x32x16_bf16 v[82:97], v[66:69], v[142:145], 0
	ds_read_b128 v[66:69], v153 offset:32768
	v_add_u32_e32 v219, v74, v190
	v_add_u32_e32 v220, v74, v191
	v_add_u32_e32 v221, v74, v192
	v_add_u32_e32 v222, v74, v193
	v_mfma_f32_32x32x16_bf16 v[82:97], v[70:73], v[138:141], v[82:97]
	ds_read_b128 v[70:73], v155 offset:32768
	s_waitcnt lgkmcnt(0)
	v_mfma_f32_32x32x16_bf16 v[82:97], v[66:69], v[134:137], v[82:97]
	ds_read_b128 v[66:69], v157 offset:32768
	v_mfma_f32_32x32x16_bf16 v[82:97], v[70:73], v[130:133], v[82:97]
	ds_read_b128 v[70:73], v159 offset:32768
	s_waitcnt lgkmcnt(0)
	v_mfma_f32_32x32x16_bf16 v[82:97], v[66:69], v[126:129], v[82:97]
	ds_read_b128 v[66:69], v209 offset:32768
	v_mfma_f32_32x32x16_bf16 v[82:97], v[70:73], v[122:125], v[82:97]
	ds_read_b128 v[70:73], v218 offset:32768
	s_waitcnt lgkmcnt(0)
	v_mfma_f32_32x32x16_bf16 v[82:97], v[66:69], v[118:121], v[82:97]
	ds_read_b128 v[66:69], v219 offset:32768
	v_mfma_f32_32x32x16_bf16 v[82:97], v[70:73], v[114:117], v[82:97]
	ds_read_b128 v[70:73], v220 offset:32768
	s_waitcnt lgkmcnt(0)
	v_mfma_f32_32x32x16_bf16 v[82:97], v[66:69], v[110:113], v[82:97]
	ds_read_b128 v[66:69], v221 offset:32768
	v_mfma_f32_32x32x16_bf16 v[82:97], v[70:73], v[106:109], v[82:97]
	ds_read_b128 v[70:73], v222 offset:32768
	s_waitcnt lgkmcnt(0)
	v_mfma_f32_32x32x16_bf16 v[82:97], v[66:69], v[102:105], v[82:97]
	v_mfma_f32_32x32x16_bf16 v[82:97], v[70:73], v[98:101], v[82:97]
	ds_read_b128 v[66:69], v75 offset:45056
	ds_read_b128 v[210:213], v76 offset:45056
	s_nop 9
	v_exp_f32_e32 v226, v86
	v_exp_f32_e32 v227, v87
	v_exp_f32_e32 v228, v88
	s_waitcnt lgkmcnt(0)
	v_mfma_f32_32x32x16_bf16 v[66:81], v[66:69], v[142:145], 0
	v_exp_f32_e32 v229, v89
	v_exp_f32_e32 v230, v90
	v_exp_f32_e32 v231, v91
	v_exp_f32_e32 v232, v92
	v_exp_f32_e32 v233, v93
	v_exp_f32_e32 v234, v94
	v_exp_f32_e32 v235, v95
	v_mfma_f32_32x32x16_bf16 v[66:81], v[210:213], v[138:141], v[66:81]
	ds_read_b128 v[210:213], v153 offset:45056
	ds_read_b128 v[214:217], v155 offset:45056
	v_exp_f32_e32 v155, v82
	v_exp_f32_e32 v236, v96
	v_exp_f32_e32 v237, v97
	v_cvt_pk_bf16_f32 v86, v230, v231
	v_cvt_pk_bf16_f32 v87, v232, v233
	v_cvt_pk_bf16_f32 v88, v234, v235
	s_waitcnt lgkmcnt(0)
	v_mfma_f32_32x32x16_bf16 v[66:81], v[210:213], v[134:137], v[66:81]
	v_cvt_pk_bf16_f32 v89, v236, v237
	v_add_u32_e32 v153, s28, v179
	v_mfma_f32_32x32x16_bf16 v[66:81], v[214:217], v[130:133], v[66:81]
	ds_read_b128 v[210:213], v157 offset:45056
	ds_read_b128 v[214:217], v159 offset:45056
	v_exp_f32_e32 v157, v83
	v_exp_f32_e32 v159, v84
	v_cvt_pk_bf16_f32 v84, v226, v227
	v_cvt_pk_bf16_f32 v82, v155, v157
	s_nop 1
	s_waitcnt lgkmcnt(0)
	v_mfma_f32_32x32x16_bf16 v[66:81], v[210:213], v[126:129], v[66:81]
	v_mfma_f32_32x32x16_bf16 v[66:81], v[214:217], v[122:125], v[66:81]
	ds_read_b128 v[210:213], v209 offset:45056
	ds_read_b128 v[214:217], v218 offset:45056
	v_exp_f32_e32 v209, v85
	v_cvt_pk_bf16_f32 v85, v228, v229
	v_cvt_pk_bf16_f32 v83, v159, v209
	s_nop 1
	s_waitcnt lgkmcnt(0)
	v_mfma_f32_32x32x16_bf16 v[66:81], v[210:213], v[118:121], v[66:81]
	ds_read_b128 v[210:213], v219 offset:45056
	v_mfma_f32_32x32x16_bf16 v[66:81], v[214:217], v[114:117], v[66:81]
	ds_read_b128 v[214:217], v220 offset:45056
	ds_read_b128 v[218:221], v221 offset:45056
	ds_read_b128 v[222:225], v222 offset:45056
	s_waitcnt lgkmcnt(0)
	v_mfma_f32_32x32x16_bf16 v[66:81], v[210:213], v[110:113], v[66:81]
	v_mfma_f32_32x32x16_bf16 v[66:81], v[214:217], v[106:109], v[66:81]
	v_mfma_f32_32x32x16_bf16 v[66:81], v[218:221], v[102:105], v[66:81]
	v_mfma_f32_32x32x16_bf16 v[66:81], v[222:225], v[98:101], v[66:81]
	ds_read_b64_tr_b16 v[90:91], v153 offset:0
	ds_read_b64_tr_b16 v[92:93], v153 offset:0x800
	ds_read_b64_tr_b16 v[94:95], v153 offset:0x1000
	ds_read_b64_tr_b16 v[96:97], v153 offset:0x1800
	ds_read_b64_tr_b16 v[210:211], v153 offset:0x200
	ds_read_b64_tr_b16 v[212:213], v153 offset:0xa00
	ds_read_b64_tr_b16 v[214:215], v153 offset:0x1200
	ds_read_b64_tr_b16 v[216:217], v153 offset:0x1a00
	s_waitcnt lgkmcnt(4)
	s_nop 0
	v_mfma_f32_32x32x16_bf16 v[2:17], v[82:85], v[90:93], v[2:17]
	s_nop 9
	v_exp_f32_e32 v218, v66
	v_exp_f32_e32 v219, v67
	v_exp_f32_e32 v220, v68
	v_exp_f32_e32 v221, v69
	v_mfma_f32_32x32x16_bf16 v[2:17], v[86:89], v[94:97], v[2:17]
	ds_read_b64_tr_b16 v[66:67], v153 offset:0x400
	ds_read_b64_tr_b16 v[68:69], v153 offset:0xc00
	ds_read_b64_tr_b16 v[90:91], v153 offset:0x1400
	ds_read_b64_tr_b16 v[92:93], v153 offset:0x1c00
	s_waitcnt lgkmcnt(4)
	v_mfma_f32_32x32x16_bf16 v[18:33], v[82:85], v[210:213], v[18:33]
	v_exp_f32_e32 v210, v70
	v_exp_f32_e32 v211, v71
	v_exp_f32_e32 v212, v72
	v_exp_f32_e32 v213, v73
	v_mfma_f32_32x32x16_bf16 v[18:33], v[86:89], v[214:217], v[18:33]
	ds_read_b64_tr_b16 v[70:71], v153 offset:0x600
	ds_read_b64_tr_b16 v[72:73], v153 offset:0xe00
	ds_read_b64_tr_b16 v[94:95], v153 offset:0x1600
	ds_read_b64_tr_b16 v[96:97], v153 offset:0x1e00
	s_waitcnt lgkmcnt(4)
	v_mfma_f32_32x32x16_bf16 v[34:49], v[82:85], v[66:69], v[34:49]
	v_exp_f32_e32 v214, v74
	v_exp_f32_e32 v215, v75
	v_exp_f32_e32 v216, v76
	v_exp_f32_e32 v217, v77
	v_mfma_f32_32x32x16_bf16 v[34:49], v[86:89], v[90:93], v[34:49]
	ds_read_b64_tr_b16 v[66:67], v153 offset:0x2000
	ds_read_b64_tr_b16 v[68:69], v153 offset:0x2800
	ds_read_b64_tr_b16 v[74:75], v153 offset:0x3000
	ds_read_b64_tr_b16 v[76:77], v153 offset:0x3800
	s_waitcnt lgkmcnt(4)
	v_exp_f32_e32 v90, v78
	v_mfma_f32_32x32x16_bf16 v[50:65], v[82:85], v[70:73], v[50:65]
	v_exp_f32_e32 v91, v79
	v_cvt_pk_bf16_f32 v72, v210, v211
	v_cvt_pk_bf16_f32 v73, v212, v213
	v_mfma_f32_32x32x16_bf16 v[50:65], v[86:89], v[94:97], v[50:65]
	v_exp_f32_e32 v92, v80
	v_exp_f32_e32 v248, v81
	v_cvt_pk_bf16_f32 v78, v214, v215
	v_cvt_pk_bf16_f32 v79, v216, v217
	v_cvt_pk_bf16_f32 v80, v90, v91
	v_cvt_pk_bf16_f32 v70, v218, v219
	v_cvt_pk_bf16_f32 v71, v220, v221
	v_cvt_pk_bf16_f32 v81, v92, v248
	s_nop 0
	ds_read_b64_tr_b16 v[82:83], v153 offset:0x2200
	ds_read_b64_tr_b16 v[84:85], v153 offset:0x2a00
	ds_read_b64_tr_b16 v[86:87], v153 offset:0x3200
	ds_read_b64_tr_b16 v[88:89], v153 offset:0x3a00
	s_waitcnt lgkmcnt(4)
	s_nop 0
	v_mfma_f32_32x32x16_bf16 v[2:17], v[70:73], v[66:69], v[2:17]
	v_add_f32_e32 v246, v155, v157
	v_add_f32_e32 v247, v218, v219
	v_add_f32_e32 v246, v246, v159
	v_add_f32_e32 v247, v247, v220
	v_mfma_f32_32x32x16_bf16 v[2:17], v[78:81], v[74:77], v[2:17]
	v_add_f32_e32 v246, v246, v209
	v_add_f32_e32 v247, v247, v221
	v_add_f32_e32 v246, v246, v226
	v_add_f32_e32 v247, v247, v210
	ds_read_b64_tr_b16 v[66:67], v153 offset:0x2400
	ds_read_b64_tr_b16 v[68:69], v153 offset:0x2c00
	ds_read_b64_tr_b16 v[74:75], v153 offset:0x3400
	ds_read_b64_tr_b16 v[76:77], v153 offset:0x3c00
	s_waitcnt lgkmcnt(4)
	v_mfma_f32_32x32x16_bf16 v[18:33], v[70:73], v[82:85], v[18:33]
	v_add_f32_e32 v246, v246, v227
	v_add_f32_e32 v247, v247, v211
	v_add_f32_e32 v246, v246, v228
	v_add_f32_e32 v247, v247, v212
	v_mfma_f32_32x32x16_bf16 v[18:33], v[78:81], v[86:89], v[18:33]
	v_add_f32_e32 v246, v246, v229
	v_add_f32_e32 v247, v247, v213
	v_add_f32_e32 v246, v246, v230
	v_add_f32_e32 v247, v247, v214
	ds_read_b64_tr_b16 v[82:83], v153 offset:0x2600
	ds_read_b64_tr_b16 v[84:85], v153 offset:0x2e00
	ds_read_b64_tr_b16 v[86:87], v153 offset:0x3600
	ds_read_b64_tr_b16 v[88:89], v153 offset:0x3e00
	s_waitcnt lgkmcnt(4)
	v_mfma_f32_32x32x16_bf16 v[34:49], v[70:73], v[66:69], v[34:49]
	v_add_f32_e32 v246, v246, v231
	v_add_f32_e32 v247, v247, v215
	v_add_f32_e32 v246, v246, v232
	v_add_f32_e32 v247, v247, v216
	v_mfma_f32_32x32x16_bf16 v[34:49], v[78:81], v[74:77], v[34:49]
	v_add_f32_e32 v246, v246, v233
	v_add_f32_e32 v247, v247, v217
	v_add_f32_e32 v246, v246, v234
	v_add_f32_e32 v247, v247, v90
	s_waitcnt lgkmcnt(0)
	v_mfma_f32_32x32x16_bf16 v[50:65], v[70:73], v[82:85], v[50:65]
	v_add_f32_e32 v246, v246, v235
	v_add_f32_e32 v247, v247, v91
	v_add_f32_e32 v246, v246, v236
	v_add_f32_e32 v247, v247, v92
	v_add_f32_e32 v246, v246, v237
	v_add_f32_e32 v247, v247, v248
	v_add_f32_e32 v246, v246, v247
	v_mov_b32_e32 v247, v246
	s_nop 1
	v_permlane32_swap_b32_e32 v246, v247
	v_add_f32_e32 v246, v246, v247
	v_add_f32_e32 v151, v151, v246
	s_waitcnt vmcnt(0)
	s_add_u32 s0, s0, 64
	s_addc_u32 s1, s1, 0
	s_add_i32 s4, s4, 1
	s_cmpk_eq_i32 s0, 0x4100
	s_waitcnt vmcnt(0)
	s_barrier
	v_mfma_f32_32x32x16_bf16 v[50:65], v[78:81], v[86:89], v[50:65]
	s_cbranch_scc0 .LBB0_2312
	s_lshl_b32 s0, s52, 2
	s_add_i32 s4, s0, 0
	s_add_i32 s4, s4, 0x1e000
	ds_read_b128 v[66:69], v196
	ds_read_b128 v[70:73], v197
	s_waitcnt lgkmcnt(1)
	v_mfma_f32_32x32x16_bf16 v[82:97], v[66:69], v[142:145], 0
	s_waitcnt lgkmcnt(0)
	v_mfma_f32_32x32x16_bf16 v[82:97], v[70:73], v[138:141], v[82:97]
	ds_read_b128 v[66:69], v198
	ds_read_b128 v[70:73], v199
	s_waitcnt lgkmcnt(1)
	v_mfma_f32_32x32x16_bf16 v[82:97], v[66:69], v[134:137], v[82:97]
	s_waitcnt lgkmcnt(0)
	v_mfma_f32_32x32x16_bf16 v[82:97], v[70:73], v[130:133], v[82:97]
	ds_read_b128 v[66:69], v200
	ds_read_b128 v[70:73], v201
	s_waitcnt lgkmcnt(1)
	v_mfma_f32_32x32x16_bf16 v[82:97], v[66:69], v[126:129], v[82:97]
	s_waitcnt lgkmcnt(0)
	v_mfma_f32_32x32x16_bf16 v[82:97], v[70:73], v[122:125], v[82:97]
	ds_read_b128 v[66:69], v202
	ds_read_b128 v[70:73], v203
	s_waitcnt lgkmcnt(1)
	v_mfma_f32_32x32x16_bf16 v[82:97], v[66:69], v[118:121], v[82:97]
	s_waitcnt lgkmcnt(0)
	v_mfma_f32_32x32x16_bf16 v[82:97], v[70:73], v[114:117], v[82:97]
	ds_read_b128 v[66:69], v204
	ds_read_b128 v[70:73], v205
	s_waitcnt lgkmcnt(1)
	v_mfma_f32_32x32x16_bf16 v[82:97], v[66:69], v[110:113], v[82:97]
	s_waitcnt lgkmcnt(0)
	v_mfma_f32_32x32x16_bf16 v[82:97], v[70:73], v[106:109], v[82:97]
	ds_read_b128 v[66:69], v206
	ds_read_b128 v[70:73], v207
	s_waitcnt lgkmcnt(1)
	v_mfma_f32_32x32x16_bf16 v[82:97], v[66:69], v[102:105], v[82:97]
	s_waitcnt lgkmcnt(0)
	v_mfma_f32_32x32x16_bf16 v[82:97], v[70:73], v[98:101], v[82:97]
	ds_read_b128 v[66:69], v196 offset:12288
	ds_read_b128 v[160:163], v197 offset:12288
	s_waitcnt lgkmcnt(1)
	v_mfma_f32_32x32x16_bf16 v[66:81], v[66:69], v[142:145], 0
	s_waitcnt lgkmcnt(0)
	v_mfma_f32_32x32x16_bf16 v[66:81], v[160:163], v[138:141], v[66:81]
	ds_read_b128 v[138:141], v198 offset:12288
	ds_read_b128 v[142:145], v199 offset:12288
	s_waitcnt lgkmcnt(1)
	v_mfma_f32_32x32x16_bf16 v[66:81], v[138:141], v[134:137], v[66:81]
	s_waitcnt lgkmcnt(0)
	v_mfma_f32_32x32x16_bf16 v[66:81], v[142:145], v[130:133], v[66:81]
	ds_read_b128 v[130:133], v200 offset:12288
	ds_read_b128 v[134:137], v201 offset:12288
	s_waitcnt lgkmcnt(1)
	v_mfma_f32_32x32x16_bf16 v[66:81], v[130:133], v[126:129], v[66:81]
	v_exp_f32_e32 v130, v82
	v_exp_f32_e32 v131, v83
	v_exp_f32_e32 v132, v84
	v_cvt_pk_bf16_f32 v82, v130, v131
	s_waitcnt lgkmcnt(0)
	v_mfma_f32_32x32x16_bf16 v[66:81], v[134:137], v[122:125], v[66:81]
	ds_read_b128 v[122:125], v202 offset:12288
	ds_read_b128 v[126:129], v203 offset:12288
	s_waitcnt lgkmcnt(1)
	v_mfma_f32_32x32x16_bf16 v[66:81], v[122:125], v[118:121], v[66:81]
	s_waitcnt lgkmcnt(0)
	v_mfma_f32_32x32x16_bf16 v[66:81], v[126:129], v[114:117], v[66:81]
	ds_read_b128 v[114:117], v204 offset:12288
	ds_read_b128 v[118:121], v205 offset:12288
	ds_read_b128 v[122:125], v206 offset:12288
	ds_read_b128 v[126:129], v207 offset:12288
	s_waitcnt lgkmcnt(3)
	v_mfma_f32_32x32x16_bf16 v[66:81], v[114:117], v[110:113], v[66:81]
	v_exp_f32_e32 v110, v85
	v_exp_f32_e32 v111, v86
	v_exp_f32_e32 v112, v87
	v_exp_f32_e32 v113, v88
	v_exp_f32_e32 v114, v89
	v_exp_f32_e32 v115, v90
	v_exp_f32_e32 v116, v91
	s_waitcnt lgkmcnt(2)
	v_mfma_f32_32x32x16_bf16 v[66:81], v[118:121], v[106:109], v[66:81]
	v_exp_f32_e32 v106, v92
	v_exp_f32_e32 v107, v93
	v_exp_f32_e32 v108, v94
	v_exp_f32_e32 v109, v95
	v_exp_f32_e32 v117, v96
	v_exp_f32_e32 v118, v97
	v_cvt_pk_bf16_f32 v83, v132, v110
	s_waitcnt lgkmcnt(1)
	v_mfma_f32_32x32x16_bf16 v[66:81], v[122:125], v[102:105], v[66:81]
	v_cvt_pk_bf16_f32 v84, v111, v112
	v_cvt_pk_bf16_f32 v85, v113, v114
	v_cvt_pk_bf16_f32 v86, v115, v116
	v_cvt_pk_bf16_f32 v87, v106, v107
	v_cvt_pk_bf16_f32 v88, v108, v109
	v_cvt_pk_bf16_f32 v89, v117, v118
	s_waitcnt lgkmcnt(0)
	v_mfma_f32_32x32x16_bf16 v[66:81], v[126:129], v[98:101], v[66:81]
	ds_read_b64_tr_b16 v[90:91], v208 offset:0
	ds_read_b64_tr_b16 v[92:93], v208 offset:0x800
	ds_read_b64_tr_b16 v[94:95], v208 offset:0x1000
	ds_read_b64_tr_b16 v[96:97], v208 offset:0x1800
	ds_read_b64_tr_b16 v[98:99], v208 offset:0x200
	ds_read_b64_tr_b16 v[100:101], v208 offset:0xa00
	ds_read_b64_tr_b16 v[102:103], v208 offset:0x1200
	ds_read_b64_tr_b16 v[104:105], v208 offset:0x1a00
	s_waitcnt lgkmcnt(4)
	s_nop 0
	v_mfma_f32_32x32x16_bf16 v[2:17], v[82:85], v[90:93], v[2:17]
	s_nop 6
	v_exp_f32_e32 v119, v66
	v_exp_f32_e32 v120, v67
	v_exp_f32_e32 v121, v68
	v_exp_f32_e32 v122, v69
	v_mfma_f32_32x32x16_bf16 v[2:17], v[86:89], v[94:97], v[2:17]
	ds_read_b64_tr_b16 v[66:67], v208 offset:0x400
	ds_read_b64_tr_b16 v[68:69], v208 offset:0xc00
	ds_read_b64_tr_b16 v[90:91], v208 offset:0x1400
	ds_read_b64_tr_b16 v[92:93], v208 offset:0x1c00
	s_waitcnt lgkmcnt(4)
	v_mfma_f32_32x32x16_bf16 v[18:33], v[82:85], v[98:101], v[18:33]
	v_exp_f32_e32 v98, v70
	v_exp_f32_e32 v99, v71
	v_exp_f32_e32 v100, v72
	v_exp_f32_e32 v101, v73
	v_mfma_f32_32x32x16_bf16 v[18:33], v[86:89], v[102:105], v[18:33]
	ds_read_b64_tr_b16 v[70:71], v208 offset:0x600
	ds_read_b64_tr_b16 v[72:73], v208 offset:0xe00
	ds_read_b64_tr_b16 v[94:95], v208 offset:0x1600
	ds_read_b64_tr_b16 v[96:97], v208 offset:0x1e00
	s_waitcnt lgkmcnt(4)
	v_mfma_f32_32x32x16_bf16 v[34:49], v[82:85], v[66:69], v[34:49]
	v_exp_f32_e32 v102, v74
	v_exp_f32_e32 v103, v75
	v_exp_f32_e32 v104, v76
	v_exp_f32_e32 v105, v77
	v_mfma_f32_32x32x16_bf16 v[34:49], v[86:89], v[90:93], v[34:49]
	ds_read_b64_tr_b16 v[74:75], v208 offset:0x2000
	ds_read_b64_tr_b16 v[76:77], v208 offset:0x2800
	ds_read_b64_tr_b16 v[90:91], v208 offset:0x3000
	ds_read_b64_tr_b16 v[92:93], v208 offset:0x3800
	s_waitcnt lgkmcnt(4)
	v_add_f32_e32 v66, v130, v131
	v_add_f32_e32 v67, v119, v120
	v_mfma_f32_32x32x16_bf16 v[50:65], v[82:85], v[70:73], v[50:65]
	v_add_f32_e32 v66, v66, v132
	v_add_f32_e32 v67, v67, v121
	v_exp_f32_e32 v123, v78
	v_add_f32_e32 v66, v66, v110
	v_add_f32_e32 v67, v67, v122
	v_exp_f32_e32 v124, v79
	v_add_f32_e32 v66, v66, v111
	v_add_f32_e32 v67, v67, v98
	v_mfma_f32_32x32x16_bf16 v[50:65], v[86:89], v[94:97], v[50:65]
	v_add_f32_e32 v66, v66, v112
	v_add_f32_e32 v67, v67, v99
	v_exp_f32_e32 v125, v80
	v_add_f32_e32 v66, v66, v113
	v_add_f32_e32 v67, v67, v100
	v_exp_f32_e32 v81, v81
	v_add_f32_e32 v66, v66, v114
	v_add_f32_e32 v67, v67, v101
	v_cvt_pk_bf16_f32 v68, v119, v120
	v_add_f32_e32 v66, v66, v115
	v_add_f32_e32 v67, v67, v102
	v_cvt_pk_bf16_f32 v69, v121, v122
	v_add_f32_e32 v66, v66, v116
	v_add_f32_e32 v67, v67, v103
	v_cvt_pk_bf16_f32 v70, v98, v99
	v_add_f32_e32 v66, v66, v106
	v_add_f32_e32 v67, v67, v104
	v_cvt_pk_bf16_f32 v71, v100, v101
	v_add_f32_e32 v66, v66, v107
	v_add_f32_e32 v67, v67, v105
	v_cvt_pk_bf16_f32 v78, v102, v103
	v_add_f32_e32 v66, v66, v108
	v_add_f32_e32 v67, v67, v123
	v_cvt_pk_bf16_f32 v79, v104, v105
	v_add_f32_e32 v66, v66, v109
	v_add_f32_e32 v67, v67, v124
	v_cvt_pk_bf16_f32 v80, v123, v124
	v_add_f32_e32 v66, v66, v117
	v_add_f32_e32 v67, v67, v125
	v_add_f32_e32 v66, v66, v118
	v_add_f32_e32 v67, v67, v81
	v_cvt_pk_bf16_f32 v81, v125, v81
	v_add_f32_e32 v66, v66, v67
	v_mov_b32_e32 v67, v66
	s_nop 1
	v_permlane32_swap_b32_e32 v66, v67
	ds_read_b64_tr_b16 v[82:83], v208 offset:0x2200
	ds_read_b64_tr_b16 v[84:85], v208 offset:0x2a00
	ds_read_b64_tr_b16 v[86:87], v208 offset:0x3200
	ds_read_b64_tr_b16 v[88:89], v208 offset:0x3a00
	s_waitcnt lgkmcnt(4)
	v_mfma_f32_32x32x16_bf16 v[2:17], v[68:71], v[74:77], v[2:17]
	s_nop 0
	v_mfma_f32_32x32x16_bf16 v[2:17], v[78:81], v[90:93], v[2:17]
	ds_read_b64_tr_b16 v[72:73], v208 offset:0x2400
	ds_read_b64_tr_b16 v[74:75], v208 offset:0x2c00
	ds_read_b64_tr_b16 v[90:91], v208 offset:0x3400
	ds_read_b64_tr_b16 v[92:93], v208 offset:0x3c00
	s_waitcnt lgkmcnt(4)
	v_mfma_f32_32x32x16_bf16 v[18:33], v[68:71], v[82:85], v[18:33]
	v_mfma_f32_32x32x16_bf16 v[18:33], v[78:81], v[86:89], v[18:33]
	ds_read_b64_tr_b16 v[82:83], v208 offset:0x2600
	ds_read_b64_tr_b16 v[84:85], v208 offset:0x2e00
	ds_read_b64_tr_b16 v[86:87], v208 offset:0x3600
	ds_read_b64_tr_b16 v[88:89], v208 offset:0x3e00
	s_waitcnt lgkmcnt(4)
	v_mfma_f32_32x32x16_bf16 v[34:49], v[68:71], v[72:75], v[34:49]
	v_mfma_f32_32x32x16_bf16 v[34:49], v[78:81], v[90:93], v[34:49]
	s_waitcnt lgkmcnt(0)
	v_mfma_f32_32x32x16_bf16 v[50:65], v[68:71], v[82:85], v[50:65]
	s_waitcnt vmcnt(0)
	s_barrier
	v_mfma_f32_32x32x16_bf16 v[50:65], v[78:81], v[86:89], v[50:65]
	s_and_saveexec_b64 s[0:1], s[2:3]
	s_cbranch_execz .LBB0_2310
	v_add_f32_e32 v66, v66, v67
	v_lshl_add_u32 v68, v165, 2, s4
	v_add_f32_e32 v66, v151, v66
	ds_write_b32 v68, v66
	s_branch .LBB0_2310

.LBB0_2318:
	s_lshl_b32 s0, s30, 1
	s_and_b32 s24, s0, 0x700
	s_ashr_i32 s0, s30, 10
	s_ashr_i32 s1, s0, 31
	s_lshl_b64 s[46:47], s[0:1], 14
	s_lshl_b32 s1, s30, 8
	s_and_b32 s1, s1, 0x3f00
	s_or_b32 s46, s46, s1
	s_bfe_u32 s23, s30, 0x40006
	s_mul_i32 s4, s47, 0x3000
	s_mul_hi_u32 s21, s46, 0x3000
	s_lshl_b32 s52, s23, 7
	s_lshl_b32 s1, s0, 8
	s_add_i32 s21, s21, s4
	s_mul_i32 s4, s46, 0x3000
	v_readlane_b32 s40, v242, 17
	v_readlane_b32 s41, v242, 18
	s_add_u32 s4, s40, s4
	s_addc_u32 s21, s41, s21
	s_add_u32 s4, s4, s52
	s_addc_u32 s21, s21, 0
	s_add_u32 s28, s4, 0x1000
	s_addc_u32 s29, s21, 0
	s_mul_i32 s4, s0, 0x300000
	s_mul_hi_i32 s1, s1, 0x3000
	s_add_u32 s4, s40, s4
	s_addc_u32 s21, s41, s1
	s_add_u32 s34, s4, s52
	s_addc_u32 s35, s21, 0
	s_mul_i32 s58, s0, 0xc000000
	s_mul_hi_i32 s25, s0, 0xc000000
	s_add_u32 s0, s40, s58
	s_addc_u32 s1, s41, s25
	s_add_u32 s0, s0, s52
	s_addc_u32 s1, s1, 0
	s_and_b32 s31, s52, 0x700
	s_add_u32 s61, s4, s31
	s_addc_u32 s62, s21, 0
	s_add_u32 s40, s61, 0x18002000
	v_readfirstlane_b32 s33, v0
	s_addc_u32 s41, s62, 0
	s_lshr_b32 s31, s33, 6
	s_lshl_b32 s4, s31, 5
	v_or_b32_e32 v4, s4, v165
	v_mov_b64_e32 v[2:3], s[28:29]
	v_mad_u64_u32 v[2:3], s[28:29], v4, s20, v[2:3]
	v_lshl_add_u64 v[2:3], v[2:3], 0, v[132:133]
	global_load_dwordx4 v[114:117], v[2:3], off
	global_load_dwordx4 v[118:121], v[2:3], off offset:32
	global_load_dwordx4 v[122:125], v[2:3], off offset:64
	global_load_dwordx4 v[126:129], v[2:3], off offset:96
	s_andn2_b32 s33, s33, 63
	s_ashr_i32 s21, s33, 4
	s_and_b32 s28, s21, -16
	s_lshr_b32 s21, s21, 1
	s_and_b32 s21, s21, 4
	v_or_b32_e32 v2, s33, v166
	s_or_b32 s60, s28, s21
	s_add_i32 s21, s33, 0x200
	v_ashrrev_i32_e32 v3, 31, v2
	s_ashr_i32 s21, s21, 4
	v_lshrrev_b32_e32 v3, 29, v3
	s_and_b32 s28, s21, -16
	s_lshr_b32 s21, s21, 1
	v_add_u32_e32 v3, v2, v3
	s_and_b32 s21, s21, 4
	v_ashrrev_i32_e32 v5, 3, v3
	v_and_b32_e32 v3, 0x1ffffff8, v3
	s_or_b32 s59, s28, s21
	v_sub_u32_e32 v3, v2, v3
	v_lshrrev_b32_e32 v4, 1, v5
	v_and_b32_e32 v137, 0x60, v2
	v_or_b32_e32 v2, s60, v163
	v_or_b32_e32 v6, s59, v163
	v_bitop3_b32 v3, v4, v3, 7 bitop3:0x6c
	v_or_b32_e32 v4, v137, v162
	v_lshrrev_b32_e32 v7, 1, v2
	v_xor_b32_e32 v7, v7, v2
	v_and_b32_e32 v7, 4, v7
	v_lshl_or_b32 v7, v7, 1, v7
	v_xor_b32_e32 v2, v2, v7
	v_lshrrev_b32_e32 v7, 1, v6
	v_xor_b32_e32 v7, v7, v6
	v_and_b32_e32 v7, 4, v7
	v_lshl_or_b32 v7, v7, 1, v7
	v_xor_b32_e32 v6, v6, v7
	v_mul_lo_u32 v2, v2, s22
	v_mul_lo_u32 v6, v6, s22
	v_mul_lo_u32 v5, v5, s22
	v_or_b32_e32 v2, v2, v4
	v_or_b32_e32 v4, v6, v4
	v_lshl_add_u32 v6, v3, 3, v5
	v_ashrrev_i32_e32 v7, 31, v6
	v_lshlrev_b64 v[150:151], 1, v[6:7]
	s_lshl_b32 s21, s31, 10
	v_lshl_add_u64 v[98:99], s[34:35], 0, v[150:151]
	s_add_i32 s34, s21, 0
	s_add_i32 s35, s34, 0x8000
	v_ashrrev_i32_e32 v3, 31, v2
	v_lshl_add_u64 v[6:7], v[98:99], 0, s[6:7]
	s_mov_b32 m0, s35
	v_lshlrev_b64 v[152:153], 1, v[2:3]
	v_ashrrev_i32_e32 v5, 31, v4
	global_load_lds_dwordx4 v[6:7], off
	v_lshl_add_u64 v[2:3], s[40:41], 0, v[152:153]
	s_mov_b32 m0, s34
	v_lshlrev_b64 v[154:155], 1, v[4:5]
	s_add_i32 s54, s34, 0x2000
	global_load_lds_dwordx4 v[2:3], off
	v_lshl_add_u64 v[2:3], s[40:41], 0, v[154:155]
	s_mov_b32 m0, s54
	s_add_i32 s55, s34, 0xa000
	global_load_lds_dwordx4 v[2:3], off
	v_lshl_add_u64 v[2:3], v[98:99], 0, s[8:9]
	s_mov_b32 m0, s55
	s_waitcnt vmcnt(0)
	s_waitcnt vmcnt(0) lgkmcnt(0)
	s_barrier
	global_load_lds_dwordx4 v[2:3], off
	ds_read_b128 v[2:5], v172 offset:32768
	ds_read_b128 v[18:21], v172 offset:36864
	s_waitcnt lgkmcnt(0)
	v_mfma_f32_32x32x16_bf16 v[2:17], v[2:5], v[114:117], 0
	ds_read_b128 v[22:25], v173 offset:32768
	ds_read_b128 v[34:37], v173 offset:36864
	s_add_u32 s28, s61, 0x180c2000
	v_lshl_add_u64 v[30:31], v[98:99], 0, s[12:13]
	s_mov_b32 m0, s35
	s_addc_u32 s29, s62, 0
	s_add_i32 s56, s34, 0x4000
	s_add_i32 s57, s34, 0x6000
	s_waitcnt lgkmcnt(0)
	v_mfma_f32_32x32x16_bf16 v[2:17], v[22:25], v[118:121], v[2:17]
	ds_read_b128 v[22:25], v174 offset:32768
	ds_read_b128 v[38:41], v174 offset:36864
	ds_read_b128 v[26:29], v175 offset:32768
	ds_read_b128 v[42:45], v175 offset:36864
	s_waitcnt vmcnt(0)
	s_waitcnt vmcnt(0) lgkmcnt(0)
	s_barrier
	global_load_lds_dwordx4 v[30:31], off
	v_mfma_f32_32x32x16_bf16 v[2:17], v[22:25], v[122:125], v[2:17]
	v_lshl_add_u64 v[22:23], s[28:29], 0, v[152:153]
	s_mov_b32 m0, s56
	s_mov_b32 s53, s5
	global_load_lds_dwordx4 v[22:23], off
	v_lshl_add_u64 v[22:23], s[28:29], 0, v[154:155]
	s_mov_b32 m0, s57
	v_mfma_f32_32x32x16_bf16 v[2:17], v[26:29], v[126:129], v[2:17]
	global_load_lds_dwordx4 v[22:23], off
	v_mfma_f32_32x32x16_bf16 v[18:33], v[18:21], v[114:117], 0
	s_nop 9
	v_exp_f32_e32 v54, v2
	v_exp_f32_e32 v55, v3
	v_exp_f32_e32 v56, v4
	v_exp_f32_e32 v57, v5
	v_exp_f32_e32 v58, v6
	v_exp_f32_e32 v59, v7
	v_exp_f32_e32 v60, v8
	v_mfma_f32_32x32x16_bf16 v[18:33], v[34:37], v[118:121], v[18:33]
	v_exp_f32_e32 v61, v9
	v_exp_f32_e32 v62, v10
	v_exp_f32_e32 v63, v11
	v_exp_f32_e32 v64, v12
	v_exp_f32_e32 v65, v13
	v_exp_f32_e32 v102, v14
	v_exp_f32_e32 v103, v15
	v_mfma_f32_32x32x16_bf16 v[18:33], v[38:41], v[122:125], v[18:33]
	v_exp_f32_e32 v104, v16
	v_exp_f32_e32 v105, v17
	ds_read_b128 v[2:5], v172 offset:40960
	ds_read_b128 v[6:9], v172 offset:45056
	ds_read_b128 v[10:13], v173 offset:40960
	ds_read_b128 v[14:17], v173 offset:45056
	ds_read_b128 v[34:37], v174 offset:40960
	ds_read_b128 v[38:41], v174 offset:45056
	ds_read_b128 v[46:49], v175 offset:40960
	ds_read_b128 v[50:53], v175 offset:45056
	v_mfma_f32_32x32x16_bf16 v[18:33], v[42:45], v[126:129], v[18:33]
	s_waitcnt lgkmcnt(0)
	v_mfma_f32_32x32x16_bf16 v[66:81], v[6:9], v[114:117], 0
	v_mfma_f32_32x32x16_bf16 v[82:97], v[2:5], v[114:117], 0
	s_nop 8
	v_exp_f32_e32 v2, v18
	v_exp_f32_e32 v3, v19
	v_exp_f32_e32 v4, v20
	v_exp_f32_e32 v5, v21
	v_exp_f32_e32 v18, v22
	v_exp_f32_e32 v19, v23
	v_exp_f32_e32 v20, v24
	v_exp_f32_e32 v21, v25
	v_mfma_f32_32x32x16_bf16 v[66:81], v[14:17], v[118:121], v[66:81]
	v_exp_f32_e32 v6, v26
	v_exp_f32_e32 v7, v27
	v_exp_f32_e32 v8, v28
	v_exp_f32_e32 v9, v29
	v_mfma_f32_32x32x16_bf16 v[82:97], v[10:13], v[118:121], v[82:97]
	v_exp_f32_e32 v10, v30
	v_exp_f32_e32 v11, v31
	v_exp_f32_e32 v12, v32
	v_exp_f32_e32 v13, v33
	v_add_f32_e32 v14, v54, v55
	v_add_f32_e32 v15, v2, v3
	v_mfma_f32_32x32x16_bf16 v[66:81], v[38:41], v[122:125], v[66:81]
	v_add_f32_e32 v14, v14, v56
	v_add_f32_e32 v15, v15, v4
	v_cvt_pk_bf16_f32 v54, v54, v55
	v_add_f32_e32 v14, v14, v57
	v_add_f32_e32 v15, v15, v5
	v_cvt_pk_bf16_f32 v55, v56, v57
	v_add_f32_e32 v14, v14, v58
	v_add_f32_e32 v15, v15, v18
	v_cvt_pk_bf16_f32 v56, v58, v59
	v_add_f32_e32 v14, v14, v59
	v_add_f32_e32 v15, v15, v19
	v_cvt_pk_bf16_f32 v57, v60, v61
	v_add_f32_e32 v14, v14, v60
	v_add_f32_e32 v15, v15, v20
	s_nop 0
	v_add_f32_e32 v14, v14, v61
	v_add_f32_e32 v15, v15, v21
	v_add_f32_e32 v14, v14, v62
	v_add_f32_e32 v15, v15, v6
	v_mfma_f32_32x32x16_bf16 v[82:97], v[34:37], v[122:125], v[82:97]
	v_add_f32_e32 v14, v14, v63
	v_add_f32_e32 v15, v15, v7
	s_nop 0
	v_add_f32_e32 v14, v14, v64
	v_add_f32_e32 v15, v15, v8
	s_nop 0
	v_add_f32_e32 v14, v14, v65
	v_add_f32_e32 v15, v15, v9
	s_nop 0
	v_add_f32_e32 v14, v14, v102
	v_add_f32_e32 v15, v15, v10
	s_nop 0
	v_add_f32_e32 v14, v14, v103
	v_add_f32_e32 v15, v15, v11
	s_nop 0
	v_add_f32_e32 v14, v14, v104
	v_add_f32_e32 v15, v15, v12
	s_nop 0
	v_add_f32_e32 v14, v14, v105
	v_add_f32_e32 v15, v15, v13
	s_nop 0
	v_add_f32_e32 v14, v14, v15
	v_mov_b32_e32 v15, v14
	s_nop 1
	v_permlane32_swap_b32_e32 v14, v15
	v_add_f32_e32 v14, v14, v15
	v_add_f32_e32 v135, 0, v14
	v_mfma_f32_32x32x16_bf16 v[66:81], v[50:53], v[126:129], v[66:81]
	v_cvt_pk_bf16_f32 v100, v62, v63
	v_cvt_pk_bf16_f32 v101, v64, v65
	v_cvt_pk_bf16_f32 v102, v102, v103
	v_cvt_pk_bf16_f32 v103, v104, v105
	v_cvt_pk_bf16_f32 v104, v2, v3
	v_cvt_pk_bf16_f32 v105, v4, v5
	v_cvt_pk_bf16_f32 v106, v18, v19
	v_cvt_pk_bf16_f32 v107, v20, v21
	v_cvt_pk_bf16_f32 v108, v6, v7
	v_cvt_pk_bf16_f32 v109, v8, v9
	v_cvt_pk_bf16_f32 v110, v10, v11
	v_cvt_pk_bf16_f32 v111, v12, v13
	v_mfma_f32_32x32x16_bf16 v[82:97], v[46:49], v[126:129], v[82:97]
	ds_read_b64_tr_b16 v[2:3], v168 offset:0
	ds_read_b64_tr_b16 v[4:5], v168 offset:0x800
	ds_read_b64_tr_b16 v[18:19], v168 offset:0x1000
	ds_read_b64_tr_b16 v[20:21], v168 offset:0x1800
	ds_read_b64_tr_b16 v[22:23], v168 offset:0x2000
	ds_read_b64_tr_b16 v[24:25], v168 offset:0x2800
	ds_read_b64_tr_b16 v[26:27], v168 offset:0x3000
	ds_read_b64_tr_b16 v[28:29], v168 offset:0x3800
	ds_read_b64_tr_b16 v[30:31], v168 offset:0x200
	ds_read_b64_tr_b16 v[32:33], v168 offset:0xa00
	ds_read_b64_tr_b16 v[34:35], v168 offset:0x1200
	ds_read_b64_tr_b16 v[36:37], v168 offset:0x1a00
	ds_read_b64_tr_b16 v[38:39], v168 offset:0x2200
	ds_read_b64_tr_b16 v[40:41], v168 offset:0x2a00
	ds_read_b64_tr_b16 v[42:43], v168 offset:0x3200
	ds_read_b64_tr_b16 v[44:45], v168 offset:0x3a00
	s_waitcnt lgkmcnt(8)
	s_nop 0
	v_mfma_f32_32x32x16_bf16 v[2:17], v[54:57], v[2:5], 0
	s_nop 3
	v_exp_f32_e32 v139, v82
	v_exp_f32_e32 v141, v83
	v_exp_f32_e32 v143, v84
	v_exp_f32_e32 v145, v85
	v_mfma_f32_32x32x16_bf16 v[2:17], v[100:103], v[18:21], v[2:17]
	v_mfma_f32_32x32x16_bf16 v[2:17], v[104:107], v[22:25], v[2:17]
	v_mfma_f32_32x32x16_bf16 v[2:17], v[108:111], v[26:29], v[2:17]
	ds_read_b64_tr_b16 v[46:47], v168 offset:0x400
	ds_read_b64_tr_b16 v[48:49], v168 offset:0xc00
	ds_read_b64_tr_b16 v[50:51], v168 offset:0x1400
	ds_read_b64_tr_b16 v[52:53], v168 offset:0x1c00
	ds_read_b64_tr_b16 v[58:59], v168 offset:0x2400
	ds_read_b64_tr_b16 v[60:61], v168 offset:0x2c00
	ds_read_b64_tr_b16 v[62:63], v168 offset:0x3400
	ds_read_b64_tr_b16 v[64:65], v168 offset:0x3c00
	s_waitcnt lgkmcnt(8)
	v_mfma_f32_32x32x16_bf16 v[18:33], v[54:57], v[30:33], 0
	v_exp_f32_e32 v147, v86
	v_exp_f32_e32 v149, v87
	v_exp_f32_e32 v196, v88
	v_exp_f32_e32 v197, v89
	v_mfma_f32_32x32x16_bf16 v[18:33], v[100:103], v[34:37], v[18:33]
	v_mfma_f32_32x32x16_bf16 v[18:33], v[104:107], v[38:41], v[18:33]
	v_mfma_f32_32x32x16_bf16 v[18:33], v[108:111], v[42:45], v[18:33]
	ds_read_b64_tr_b16 v[82:83], v168 offset:0x600
	ds_read_b64_tr_b16 v[84:85], v168 offset:0xe00
	ds_read_b64_tr_b16 v[86:87], v168 offset:0x1600
	ds_read_b64_tr_b16 v[88:89], v168 offset:0x1e00
	ds_read_b64_tr_b16 v[156:157], v168 offset:0x2600
	ds_read_b64_tr_b16 v[158:159], v168 offset:0x2e00
	ds_read_b64_tr_b16 v[176:177], v168 offset:0x3600
	ds_read_b64_tr_b16 v[178:179], v168 offset:0x3e00
	s_waitcnt lgkmcnt(8)
	v_mfma_f32_32x32x16_bf16 v[34:49], v[54:57], v[46:49], 0
	v_exp_f32_e32 v198, v90
	v_exp_f32_e32 v199, v91
	v_exp_f32_e32 v200, v92
	v_exp_f32_e32 v201, v93
	v_mfma_f32_32x32x16_bf16 v[34:49], v[100:103], v[50:53], v[34:49]
	v_mfma_f32_32x32x16_bf16 v[34:49], v[104:107], v[58:61], v[34:49]
	v_mfma_f32_32x32x16_bf16 v[34:49], v[108:111], v[62:65], v[34:49]
	s_waitcnt lgkmcnt(0)
	v_mfma_f32_32x32x16_bf16 v[50:65], v[54:57], v[82:85], 0
	v_exp_f32_e32 v202, v94
	v_exp_f32_e32 v203, v95
	v_exp_f32_e32 v204, v96
	v_exp_f32_e32 v205, v97
	v_mfma_f32_32x32x16_bf16 v[50:65], v[100:103], v[86:89], v[50:65]
	v_mfma_f32_32x32x16_bf16 v[50:65], v[104:107], v[156:159], v[50:65]
	v_mfma_f32_32x32x16_bf16 v[50:65], v[108:111], v[176:179], v[50:65]
	s_add_u32 s28, s61, 0x18182000
	s_mov_b32 m0, s55
	v_lshl_add_u64 v[82:83], v[98:99], 0, s[16:17]
	s_addc_u32 s29, s62, 0
	s_waitcnt vmcnt(0)
	s_waitcnt vmcnt(0)
	s_barrier
	global_load_lds_dwordx4 v[82:83], off
	v_lshl_add_u64 v[82:83], s[28:29], 0, v[152:153]
	s_mov_b32 m0, s34
	v_lshl_add_u64 v[90:91], s[0:1], 0, v[150:151]
	global_load_lds_dwordx4 v[82:83], off
	v_lshl_add_u64 v[82:83], s[28:29], 0, v[154:155]
	s_mov_b32 m0, s54
	v_lshl_add_u64 v[160:161], v[90:91], 0, s[14:15]
	global_load_lds_dwordx4 v[82:83], off
	ds_read_b128 v[82:85], v172 offset:32768
	ds_read_b128 v[86:89], v172 offset:36864
	ds_read_b128 v[156:159], v173 offset:32768
	ds_read_b128 v[176:179], v173 offset:36864
	ds_read_b128 v[180:183], v174 offset:32768
	ds_read_b128 v[184:187], v174 offset:36864
	ds_read_b128 v[188:191], v175 offset:32768
	ds_read_b128 v[192:195], v175 offset:36864
	s_waitcnt lgkmcnt(0)
	v_mfma_f32_32x32x16_bf16 v[98:113], v[82:85], v[114:117], 0
	v_exp_f32_e32 v206, v66
	v_exp_f32_e32 v207, v67
	v_exp_f32_e32 v208, v68
	v_exp_f32_e32 v209, v69
	v_exp_f32_e32 v210, v70
	v_exp_f32_e32 v211, v71
	v_exp_f32_e32 v212, v72
	v_exp_f32_e32 v213, v73
	v_mfma_f32_32x32x16_bf16 v[82:97], v[86:89], v[114:117], 0
	v_exp_f32_e32 v81, v81
	v_mfma_f32_32x32x16_bf16 v[98:113], v[156:159], v[118:121], v[98:113]
	v_exp_f32_e32 v157, v74
	v_exp_f32_e32 v159, v75
	v_exp_f32_e32 v214, v76
	v_exp_f32_e32 v215, v77
	v_exp_f32_e32 v216, v78
	v_exp_f32_e32 v217, v79
	v_exp_f32_e32 v218, v80
	v_mfma_f32_32x32x16_bf16 v[82:97], v[176:179], v[118:121], v[82:97]
	v_add_f32_e32 v66, v139, v141
	v_add_f32_e32 v67, v206, v207
	v_cvt_pk_bf16_f32 v68, v147, v149
	v_add_f32_e32 v66, v66, v143
	v_add_f32_e32 v67, v67, v208
	v_cvt_pk_bf16_f32 v69, v196, v197
	v_add_f32_e32 v66, v66, v145
	v_add_f32_e32 v67, v67, v209
	v_mfma_f32_32x32x16_bf16 v[98:113], v[180:183], v[122:125], v[98:113]
	v_add_f32_e32 v66, v66, v147
	v_add_f32_e32 v67, v67, v210
	s_nop 0
	v_add_f32_e32 v66, v66, v149
	v_add_f32_e32 v67, v67, v211
	s_nop 0
	v_add_f32_e32 v66, v66, v196
	v_add_f32_e32 v67, v67, v212
	v_mfma_f32_32x32x16_bf16 v[82:97], v[184:187], v[122:125], v[82:97]
	v_add_f32_e32 v66, v66, v197
	v_add_f32_e32 v67, v67, v213
	s_nop 0
	v_add_f32_e32 v66, v66, v198
	v_add_f32_e32 v67, v67, v157
	s_nop 0
	v_add_f32_e32 v66, v66, v199
	v_add_f32_e32 v67, v67, v159
	s_nop 0
	v_add_f32_e32 v66, v66, v200
	v_add_f32_e32 v67, v67, v214
	s_nop 0
	v_add_f32_e32 v66, v66, v201
	v_add_f32_e32 v67, v67, v215
	s_nop 0
	v_add_f32_e32 v66, v66, v202
	v_add_f32_e32 v67, v67, v216
	s_nop 0
	v_add_f32_e32 v66, v66, v203
	v_add_f32_e32 v67, v67, v217
	s_nop 0
	v_add_f32_e32 v66, v66, v204
	v_add_f32_e32 v67, v67, v218
	s_nop 0
	v_add_f32_e32 v66, v66, v205
	v_add_f32_e32 v67, v67, v81
	s_nop 0
	v_add_f32_e32 v156, v66, v67
	v_cvt_pk_bf16_f32 v66, v139, v141
	v_cvt_pk_bf16_f32 v67, v143, v145
	v_mov_b32_e32 v158, v156
	v_permlane32_swap_b32_e32 v156, v158
	v_cvt_pk_bf16_f32 v70, v198, v199
	v_cvt_pk_bf16_f32 v71, v200, v201
	v_cvt_pk_bf16_f32 v72, v202, v203
	v_cvt_pk_bf16_f32 v73, v204, v205
	v_cvt_pk_bf16_f32 v74, v206, v207
	v_cvt_pk_bf16_f32 v75, v208, v209
	v_cvt_pk_bf16_f32 v76, v210, v211
	v_cvt_pk_bf16_f32 v77, v212, v213
	v_cvt_pk_bf16_f32 v78, v157, v159
	v_cvt_pk_bf16_f32 v79, v214, v215
	v_cvt_pk_bf16_f32 v80, v216, v217
	v_cvt_pk_bf16_f32 v81, v218, v81
	v_mfma_f32_32x32x16_bf16 v[98:113], v[188:191], v[126:129], v[98:113]
	v_mfma_f32_32x32x16_bf16 v[82:97], v[192:195], v[126:129], v[82:97]
	ds_read_b64_tr_b16 v[176:177], v169 offset:0
	ds_read_b64_tr_b16 v[178:179], v169 offset:0x800
	ds_read_b64_tr_b16 v[180:181], v169 offset:0x1000
	ds_read_b64_tr_b16 v[182:183], v169 offset:0x1800
	ds_read_b64_tr_b16 v[184:185], v169 offset:0x2000
	ds_read_b64_tr_b16 v[186:187], v169 offset:0x2800
	ds_read_b64_tr_b16 v[188:189], v169 offset:0x3000
	ds_read_b64_tr_b16 v[190:191], v169 offset:0x3800
	ds_read_b64_tr_b16 v[192:193], v169 offset:0x200
	ds_read_b64_tr_b16 v[194:195], v169 offset:0xa00
	ds_read_b64_tr_b16 v[196:197], v169 offset:0x1200
	ds_read_b64_tr_b16 v[198:199], v169 offset:0x1a00
	ds_read_b64_tr_b16 v[200:201], v169 offset:0x2200
	ds_read_b64_tr_b16 v[202:203], v169 offset:0x2a00
	ds_read_b64_tr_b16 v[204:205], v169 offset:0x3200
	ds_read_b64_tr_b16 v[206:207], v169 offset:0x3a00
	s_waitcnt lgkmcnt(8)
	s_nop 0
	v_mfma_f32_32x32x16_bf16 v[2:17], v[66:69], v[176:179], v[2:17]
	s_nop 8
	v_exp_f32_e32 v139, v98
	v_exp_f32_e32 v141, v99
	v_exp_f32_e32 v143, v100
	v_exp_f32_e32 v145, v101
	v_mfma_f32_32x32x16_bf16 v[2:17], v[70:73], v[180:183], v[2:17]
	v_mfma_f32_32x32x16_bf16 v[2:17], v[74:77], v[184:187], v[2:17]
	v_mfma_f32_32x32x16_bf16 v[2:17], v[78:81], v[188:191], v[2:17]
	ds_read_b64_tr_b16 v[98:99], v169 offset:0x400
	ds_read_b64_tr_b16 v[100:101], v169 offset:0xc00
	ds_read_b64_tr_b16 v[176:177], v169 offset:0x1400
	ds_read_b64_tr_b16 v[178:179], v169 offset:0x1c00
	ds_read_b64_tr_b16 v[180:181], v169 offset:0x2400
	ds_read_b64_tr_b16 v[182:183], v169 offset:0x2c00
	ds_read_b64_tr_b16 v[184:185], v169 offset:0x3400
	ds_read_b64_tr_b16 v[186:187], v169 offset:0x3c00
	s_waitcnt lgkmcnt(8)
	v_mfma_f32_32x32x16_bf16 v[18:33], v[66:69], v[192:195], v[18:33]
	v_exp_f32_e32 v147, v102
	v_exp_f32_e32 v149, v103
	v_mfma_f32_32x32x16_bf16 v[18:33], v[70:73], v[196:199], v[18:33]
	v_mfma_f32_32x32x16_bf16 v[18:33], v[74:77], v[200:203], v[18:33]
	v_exp_f32_e32 v200, v104
	v_exp_f32_e32 v201, v105
	v_mfma_f32_32x32x16_bf16 v[18:33], v[78:81], v[204:207], v[18:33]
	ds_read_b64_tr_b16 v[102:103], v169 offset:0x600
	ds_read_b64_tr_b16 v[104:105], v169 offset:0xe00
	ds_read_b64_tr_b16 v[188:189], v169 offset:0x1600
	ds_read_b64_tr_b16 v[190:191], v169 offset:0x1e00
	ds_read_b64_tr_b16 v[192:193], v169 offset:0x2600
	ds_read_b64_tr_b16 v[194:195], v169 offset:0x2e00
	ds_read_b64_tr_b16 v[196:197], v169 offset:0x3600
	ds_read_b64_tr_b16 v[198:199], v169 offset:0x3e00
	s_waitcnt lgkmcnt(8)
	v_mfma_f32_32x32x16_bf16 v[34:49], v[66:69], v[98:101], v[34:49]
	v_exp_f32_e32 v202, v106
	v_exp_f32_e32 v203, v107
	v_exp_f32_e32 v204, v108
	v_exp_f32_e32 v205, v109
	v_mfma_f32_32x32x16_bf16 v[34:49], v[70:73], v[176:179], v[34:49]
	v_mfma_f32_32x32x16_bf16 v[34:49], v[74:77], v[180:183], v[34:49]
	v_mfma_f32_32x32x16_bf16 v[34:49], v[78:81], v[184:187], v[34:49]
	s_waitcnt lgkmcnt(0)
	v_mfma_f32_32x32x16_bf16 v[50:65], v[66:69], v[102:105], v[50:65]
	v_exp_f32_e32 v206, v110
	v_exp_f32_e32 v207, v111
	v_exp_f32_e32 v208, v112
	v_exp_f32_e32 v209, v113
	v_mfma_f32_32x32x16_bf16 v[50:65], v[70:73], v[188:191], v[50:65]
	v_mfma_f32_32x32x16_bf16 v[50:65], v[74:77], v[192:195], v[50:65]
	v_mfma_f32_32x32x16_bf16 v[50:65], v[78:81], v[196:199], v[50:65]
	s_add_u32 s0, s61, 0x18242000
	s_mov_b32 m0, s35
	s_addc_u32 s1, s62, 0
	s_waitcnt vmcnt(0)
	s_waitcnt vmcnt(0)
	s_barrier
	global_load_lds_dwordx4 v[160:161], off
	v_lshl_add_u64 v[66:67], s[0:1], 0, v[152:153]
	s_mov_b32 m0, s56
	s_nop 0
	global_load_lds_dwordx4 v[66:67], off
	v_lshl_add_u64 v[66:67], s[0:1], 0, v[154:155]
	s_mov_b32 m0, s57
	s_nop 0
	global_load_lds_dwordx4 v[66:67], off
	ds_read_b128 v[66:69], v172 offset:40960
	ds_read_b128 v[70:73], v172 offset:45056
	ds_read_b128 v[152:155], v173 offset:40960
	ds_read_b128 v[176:179], v173 offset:45056
	ds_read_b128 v[180:183], v174 offset:40960
	ds_read_b128 v[184:187], v174 offset:45056
	ds_read_b128 v[188:191], v175 offset:40960
	ds_read_b128 v[192:195], v175 offset:45056
	s_waitcnt lgkmcnt(0)
	v_mfma_f32_32x32x16_bf16 v[98:113], v[66:69], v[114:117], 0
	v_exp_f32_e32 v160, v82
	v_exp_f32_e32 v161, v83
	v_exp_f32_e32 v196, v84
	v_exp_f32_e32 v197, v85
	v_exp_f32_e32 v198, v86
	v_exp_f32_e32 v199, v87
	v_exp_f32_e32 v210, v88
	v_mfma_f32_32x32x16_bf16 v[66:81], v[70:73], v[114:117], 0
	v_exp_f32_e32 v211, v89
	v_mfma_f32_32x32x16_bf16 v[66:81], v[176:179], v[118:121], v[66:81]
	v_exp_f32_e32 v212, v94
	v_exp_f32_e32 v213, v95
	v_exp_f32_e32 v214, v96
	v_exp_f32_e32 v97, v97
	v_mfma_f32_32x32x16_bf16 v[98:113], v[152:155], v[118:121], v[98:113]
	v_exp_f32_e32 v152, v90
	v_exp_f32_e32 v153, v91
	v_exp_f32_e32 v154, v92
	v_exp_f32_e32 v155, v93
	v_add_f32_e32 v82, v139, v141
	v_add_f32_e32 v83, v160, v161
	v_mfma_f32_32x32x16_bf16 v[66:81], v[184:187], v[122:125], v[66:81]
	v_add_f32_e32 v82, v82, v143
	v_add_f32_e32 v83, v83, v196
	v_cvt_pk_bf16_f32 v84, v147, v149
	v_add_f32_e32 v82, v82, v145
	v_add_f32_e32 v83, v83, v197
	v_cvt_pk_bf16_f32 v85, v200, v201
	v_add_f32_e32 v82, v82, v147
	v_add_f32_e32 v83, v83, v198
	v_mfma_f32_32x32x16_bf16 v[98:113], v[180:183], v[122:125], v[98:113]
	v_add_f32_e32 v82, v82, v149
	v_add_f32_e32 v83, v83, v199
	s_nop 0
	v_add_f32_e32 v82, v82, v200
	v_add_f32_e32 v83, v83, v210
	s_nop 0
	v_add_f32_e32 v82, v82, v201
	v_add_f32_e32 v83, v83, v211
	s_nop 0
	v_add_f32_e32 v82, v82, v202
	v_add_f32_e32 v83, v83, v152
	s_nop 0
	v_add_f32_e32 v82, v82, v203
	v_add_f32_e32 v83, v83, v153
	s_nop 0
	v_add_f32_e32 v82, v82, v204
	v_add_f32_e32 v83, v83, v154
	s_nop 0
	v_add_f32_e32 v82, v82, v205
	v_add_f32_e32 v83, v83, v155
	s_nop 0
	v_add_f32_e32 v82, v82, v206
	v_add_f32_e32 v83, v83, v212
	s_nop 0
	v_add_f32_e32 v82, v82, v207
	v_add_f32_e32 v83, v83, v213
	s_nop 0
	v_add_f32_e32 v82, v82, v208
	v_add_f32_e32 v83, v83, v214
	s_nop 0
	v_add_f32_e32 v82, v82, v209
	v_add_f32_e32 v83, v83, v97
	s_nop 0
	v_add_f32_e32 v157, v82, v83
	v_mov_b32_e32 v159, v157
	s_nop 1
	v_permlane32_swap_b32_e32 v157, v159
	v_add_f32_e64 v82, v156, v158
	v_add_f32_e64 v83, v157, v159
	v_add_f32_e32 v82, v135, v82
	v_add_f32_e32 v135, v82, v83
	v_cvt_pk_bf16_f32 v82, v139, v141
	v_cvt_pk_bf16_f32 v83, v143, v145
	s_nop 0
	v_mfma_f32_32x32x16_bf16 v[66:81], v[192:195], v[126:129], v[66:81]
	v_cvt_pk_bf16_f32 v86, v202, v203
	v_cvt_pk_bf16_f32 v87, v204, v205
	v_cvt_pk_bf16_f32 v88, v206, v207
	v_cvt_pk_bf16_f32 v89, v208, v209
	v_cvt_pk_bf16_f32 v90, v160, v161
	v_cvt_pk_bf16_f32 v91, v196, v197
	v_cvt_pk_bf16_f32 v92, v198, v199
	v_cvt_pk_bf16_f32 v93, v210, v211
	v_cvt_pk_bf16_f32 v94, v152, v153
	v_cvt_pk_bf16_f32 v95, v154, v155
	v_cvt_pk_bf16_f32 v96, v212, v213
	v_cvt_pk_bf16_f32 v97, v214, v97
	v_mfma_f32_32x32x16_bf16 v[98:113], v[188:191], v[126:129], v[98:113]
	ds_read_b64_tr_b16 v[152:153], v168 offset:0
	ds_read_b64_tr_b16 v[154:155], v168 offset:0x800
	ds_read_b64_tr_b16 v[156:157], v168 offset:0x1000
	ds_read_b64_tr_b16 v[158:159], v168 offset:0x1800
	ds_read_b64_tr_b16 v[176:177], v168 offset:0x2000
	ds_read_b64_tr_b16 v[178:179], v168 offset:0x2800
	ds_read_b64_tr_b16 v[180:181], v168 offset:0x3000
	ds_read_b64_tr_b16 v[182:183], v168 offset:0x3800
	ds_read_b64_tr_b16 v[184:185], v168 offset:0x200
	ds_read_b64_tr_b16 v[186:187], v168 offset:0xa00
	ds_read_b64_tr_b16 v[188:189], v168 offset:0x1200
	ds_read_b64_tr_b16 v[190:191], v168 offset:0x1a00
	ds_read_b64_tr_b16 v[192:193], v168 offset:0x2200
	ds_read_b64_tr_b16 v[194:195], v168 offset:0x2a00
	ds_read_b64_tr_b16 v[196:197], v168 offset:0x3200
	ds_read_b64_tr_b16 v[198:199], v168 offset:0x3a00
	s_waitcnt lgkmcnt(8)
	s_nop 0
	v_mfma_f32_32x32x16_bf16 v[2:17], v[82:85], v[152:155], v[2:17]
	s_nop 3
	v_exp_f32_e32 v139, v98
	v_exp_f32_e32 v141, v99
	v_exp_f32_e32 v143, v100
	v_exp_f32_e32 v145, v101
	v_mfma_f32_32x32x16_bf16 v[2:17], v[86:89], v[156:159], v[2:17]
	v_mfma_f32_32x32x16_bf16 v[2:17], v[90:93], v[176:179], v[2:17]
	v_mfma_f32_32x32x16_bf16 v[2:17], v[94:97], v[180:183], v[2:17]
	ds_read_b64_tr_b16 v[98:99], v168 offset:0x400
	ds_read_b64_tr_b16 v[100:101], v168 offset:0xc00
	ds_read_b64_tr_b16 v[152:153], v168 offset:0x1400
	ds_read_b64_tr_b16 v[154:155], v168 offset:0x1c00
	ds_read_b64_tr_b16 v[156:157], v168 offset:0x2400
	ds_read_b64_tr_b16 v[158:159], v168 offset:0x2c00
	ds_read_b64_tr_b16 v[200:201], v168 offset:0x3400
	ds_read_b64_tr_b16 v[202:203], v168 offset:0x3c00
	s_waitcnt lgkmcnt(8)
	v_mfma_f32_32x32x16_bf16 v[18:33], v[82:85], v[184:187], v[18:33]
	v_exp_f32_e32 v147, v102
	v_exp_f32_e32 v149, v103
	v_exp_f32_e32 v176, v104
	v_exp_f32_e32 v177, v105
	v_mfma_f32_32x32x16_bf16 v[18:33], v[86:89], v[188:191], v[18:33]
	v_mfma_f32_32x32x16_bf16 v[18:33], v[90:93], v[192:195], v[18:33]
	v_mfma_f32_32x32x16_bf16 v[18:33], v[94:97], v[196:199], v[18:33]
	ds_read_b64_tr_b16 v[102:103], v168 offset:0x600
	ds_read_b64_tr_b16 v[104:105], v168 offset:0xe00
	ds_read_b64_tr_b16 v[182:183], v168 offset:0x1600
	ds_read_b64_tr_b16 v[184:185], v168 offset:0x1e00
	ds_read_b64_tr_b16 v[186:187], v168 offset:0x2600
	ds_read_b64_tr_b16 v[188:189], v168 offset:0x2e00
	ds_read_b64_tr_b16 v[190:191], v168 offset:0x3600
	ds_read_b64_tr_b16 v[192:193], v168 offset:0x3e00
	s_waitcnt lgkmcnt(8)
	v_mfma_f32_32x32x16_bf16 v[34:49], v[82:85], v[98:101], v[34:49]
	v_exp_f32_e32 v178, v106
	v_exp_f32_e32 v179, v107
	v_exp_f32_e32 v180, v108
	v_exp_f32_e32 v181, v109
	v_mfma_f32_32x32x16_bf16 v[34:49], v[86:89], v[152:155], v[34:49]
	v_mfma_f32_32x32x16_bf16 v[34:49], v[90:93], v[156:159], v[34:49]
	v_mfma_f32_32x32x16_bf16 v[34:49], v[94:97], v[200:203], v[34:49]
	s_waitcnt lgkmcnt(0)
	v_mfma_f32_32x32x16_bf16 v[50:65], v[82:85], v[102:105], v[50:65]
	v_mfma_f32_32x32x16_bf16 v[50:65], v[86:89], v[182:185], v[50:65]
	v_exp_f32_e32 v182, v110
	v_exp_f32_e32 v183, v111
	v_exp_f32_e32 v184, v112
	v_exp_f32_e32 v185, v113
	v_mfma_f32_32x32x16_bf16 v[50:65], v[90:93], v[186:189], v[50:65]
	v_mfma_f32_32x32x16_bf16 v[50:65], v[94:97], v[190:193], v[50:65]
	v_add_u32_e32 v82, s60, v163
	v_lshrrev_b32_e32 v83, 1, v82
	v_xor_b32_e32 v83, v83, v82
	v_and_b32_e32 v83, 4, v83
	v_lshl_or_b32 v83, v83, 1, v83
	v_xor_b32_e32 v82, v82, v83
	v_mul_lo_u32 v82, v82, s22
	v_or3_b32 v82, v162, v82, v137
	v_ashrrev_i32_e32 v83, 31, v82
	v_lshlrev_b64 v[152:153], 1, v[82:83]
	v_add_u32_e32 v82, s59, v163
	v_lshrrev_b32_e32 v83, 1, v82
	v_xor_b32_e32 v83, v83, v82
	v_and_b32_e32 v83, 4, v83
	v_lshl_or_b32 v83, v83, 1, v83
	v_xor_b32_e32 v82, v82, v83
	v_mul_lo_u32 v82, v82, s22
	v_or3_b32 v82, v162, v82, v137
	s_waitcnt vmcnt(0)
	v_ashrrev_i32_e32 v83, 31, v82
	s_add_u32 s0, s90, s58
	v_lshlrev_b64 v[154:155], 1, v[82:83]
	v_lshl_add_u64 v[150:151], s[52:53], 0, v[150:151]
	s_addc_u32 s1, s91, s25
	v_or_b32_e32 v152, s24, v152
	v_or_b32_e32 v154, s24, v154
	s_mov_b32 s52, 4
	s_waitcnt vmcnt(0)
	s_barrier
	v_exp_f32_e32 v220, v66
	v_exp_f32_e32 v221, v67
	v_exp_f32_e32 v222, v68
	v_exp_f32_e32 v223, v69
	v_exp_f32_e32 v224, v70
	v_exp_f32_e32 v225, v71
	v_exp_f32_e32 v226, v72
	v_exp_f32_e32 v227, v73
	v_exp_f32_e32 v228, v74
	v_exp_f32_e32 v229, v75
	v_exp_f32_e32 v230, v76
	v_exp_f32_e32 v231, v77
	v_exp_f32_e32 v232, v78
	v_exp_f32_e32 v233, v79
	v_exp_f32_e32 v234, v80
	v_exp_f32_e32 v235, v81
	s_branch .LBB0_2320
.LBB0_2319:
	s_mov_b32 m0, s56
	v_lshl_add_u64 v[68:69], v[156:157], 0, s[44:45]
	global_load_lds_dwordx4 v[68:69], off
	v_lshl_add_u64 v[68:69], v[158:159], 0, s[44:45]
	s_mov_b32 m0, s57
	global_load_lds_dwordx4 v[68:69], off
	ds_read_b128 v[68:71], v172 offset:40960
	ds_read_b128 v[72:75], v172 offset:45056
	ds_read_b128 v[156:159], v173 offset:40960
	ds_read_b128 v[176:179], v173 offset:45056
	ds_read_b128 v[180:183], v174 offset:40960
	ds_read_b128 v[184:187], v174 offset:45056
	ds_read_b128 v[188:191], v175 offset:40960
	ds_read_b128 v[192:195], v175 offset:45056
	v_add_f32_e32 v66, v66, v67
	v_add_f32_e32 v135, v135, v66
	s_add_i32 s52, s52, 2
	s_waitcnt lgkmcnt(0)
	v_mfma_f32_32x32x16_bf16 v[98:113], v[68:71], v[114:117], 0
	v_mfma_f32_32x32x16_bf16 v[66:81], v[72:75], v[114:117], 0
	v_mfma_f32_32x32x16_bf16 v[66:81], v[176:179], v[118:121], v[66:81]
	v_mfma_f32_32x32x16_bf16 v[98:113], v[156:159], v[118:121], v[98:113]
	v_add_f32_e32 v82, v236, v237
	v_add_f32_e32 v83, v220, v221
	v_mfma_f32_32x32x16_bf16 v[66:81], v[184:187], v[122:125], v[66:81]
	v_add_f32_e32 v82, v82, v238
	v_add_f32_e32 v83, v83, v222
	v_cvt_pk_bf16_f32 v84, v240, v241
	v_add_f32_e32 v82, v82, v239
	v_add_f32_e32 v83, v83, v223
	v_cvt_pk_bf16_f32 v85, v244, v245
	v_add_f32_e32 v82, v82, v240
	v_add_f32_e32 v83, v83, v224
	v_mfma_f32_32x32x16_bf16 v[98:113], v[180:183], v[122:125], v[98:113]
	v_add_f32_e32 v82, v82, v241
	v_add_f32_e32 v83, v83, v225
	v_add_f32_e32 v82, v82, v244
	v_add_f32_e32 v83, v83, v226
	v_add_f32_e32 v82, v82, v245
	v_add_f32_e32 v83, v83, v227
	v_add_f32_e32 v82, v82, v246
	v_add_f32_e32 v83, v83, v228
	v_add_f32_e32 v82, v82, v247
	v_add_f32_e32 v83, v83, v229
	v_add_f32_e32 v82, v82, v248
	v_add_f32_e32 v83, v83, v230
	v_add_f32_e32 v82, v82, v249
	v_add_f32_e32 v83, v83, v231
	v_add_f32_e32 v82, v82, v250
	v_add_f32_e32 v83, v83, v232
	v_add_f32_e32 v82, v82, v251
	v_add_f32_e32 v83, v83, v233
	v_add_f32_e32 v82, v82, v252
	v_add_f32_e32 v83, v83, v234
	v_add_f32_e32 v82, v82, v253
	v_add_f32_e32 v83, v83, v235
	v_add_f32_e32 v82, v82, v83
	v_mov_b32_e32 v83, v82
	s_nop 1
	v_permlane32_swap_b32_e32 v82, v83
	v_add_f32_e32 v82, v82, v83
	v_add_f32_e32 v135, v135, v82
	v_cvt_pk_bf16_f32 v82, v236, v237
	v_cvt_pk_bf16_f32 v83, v238, v239
	s_nop 0
	v_mfma_f32_32x32x16_bf16 v[66:81], v[192:195], v[126:129], v[66:81]
	v_cvt_pk_bf16_f32 v86, v246, v247
	v_cvt_pk_bf16_f32 v87, v248, v249
	v_cvt_pk_bf16_f32 v88, v250, v251
	v_cvt_pk_bf16_f32 v89, v252, v253
	v_cvt_pk_bf16_f32 v90, v220, v221
	v_cvt_pk_bf16_f32 v91, v222, v223
	v_cvt_pk_bf16_f32 v92, v224, v225
	v_cvt_pk_bf16_f32 v93, v226, v227
	v_cvt_pk_bf16_f32 v94, v228, v229
	v_cvt_pk_bf16_f32 v95, v230, v231
	v_cvt_pk_bf16_f32 v96, v232, v233
	v_cvt_pk_bf16_f32 v97, v234, v235
	v_mfma_f32_32x32x16_bf16 v[98:113], v[188:191], v[126:129], v[98:113]
	ds_read_b64_tr_b16 v[156:157], v168 offset:0
	ds_read_b64_tr_b16 v[158:159], v168 offset:0x800
	ds_read_b64_tr_b16 v[176:177], v168 offset:0x1000
	ds_read_b64_tr_b16 v[178:179], v168 offset:0x1800
	ds_read_b64_tr_b16 v[180:181], v168 offset:0x2000
	ds_read_b64_tr_b16 v[182:183], v168 offset:0x2800
	ds_read_b64_tr_b16 v[184:185], v168 offset:0x3000
	ds_read_b64_tr_b16 v[186:187], v168 offset:0x3800
	ds_read_b64_tr_b16 v[188:189], v168 offset:0x200
	ds_read_b64_tr_b16 v[190:191], v168 offset:0xa00
	ds_read_b64_tr_b16 v[192:193], v168 offset:0x1200
	ds_read_b64_tr_b16 v[194:195], v168 offset:0x1a00
	ds_read_b64_tr_b16 v[196:197], v168 offset:0x2200
	ds_read_b64_tr_b16 v[198:199], v168 offset:0x2a00
	ds_read_b64_tr_b16 v[200:201], v168 offset:0x3200
	ds_read_b64_tr_b16 v[202:203], v168 offset:0x3a00
	s_waitcnt lgkmcnt(8)
	s_nop 0
	v_mfma_f32_32x32x16_bf16 v[2:17], v[82:85], v[156:159], v[2:17]
	v_exp_f32_e32 v220, v66
	s_nop 3
	v_exp_f32_e32 v139, v98
	v_exp_f32_e32 v141, v99
	v_exp_f32_e32 v143, v100
	v_exp_f32_e32 v145, v101
	v_mfma_f32_32x32x16_bf16 v[2:17], v[86:89], v[176:179], v[2:17]
	v_exp_f32_e32 v221, v67
	v_mfma_f32_32x32x16_bf16 v[2:17], v[90:93], v[180:183], v[2:17]
	v_exp_f32_e32 v222, v68
	v_mfma_f32_32x32x16_bf16 v[2:17], v[94:97], v[184:187], v[2:17]
	v_exp_f32_e32 v223, v69
	ds_read_b64_tr_b16 v[98:99], v168 offset:0x400
	ds_read_b64_tr_b16 v[100:101], v168 offset:0xc00
	ds_read_b64_tr_b16 v[156:157], v168 offset:0x1400
	ds_read_b64_tr_b16 v[158:159], v168 offset:0x1c00
	ds_read_b64_tr_b16 v[178:179], v168 offset:0x2400
	ds_read_b64_tr_b16 v[180:181], v168 offset:0x2c00
	ds_read_b64_tr_b16 v[182:183], v168 offset:0x3400
	ds_read_b64_tr_b16 v[184:185], v168 offset:0x3c00
	s_waitcnt lgkmcnt(8)
	v_mfma_f32_32x32x16_bf16 v[18:33], v[82:85], v[188:191], v[18:33]
	v_exp_f32_e32 v224, v70
	v_exp_f32_e32 v147, v102
	v_exp_f32_e32 v149, v103
	v_exp_f32_e32 v176, v104
	v_exp_f32_e32 v177, v105
	v_mfma_f32_32x32x16_bf16 v[18:33], v[86:89], v[192:195], v[18:33]
	v_exp_f32_e32 v225, v71
	v_mfma_f32_32x32x16_bf16 v[18:33], v[90:93], v[196:199], v[18:33]
	v_exp_f32_e32 v226, v72
	v_mfma_f32_32x32x16_bf16 v[18:33], v[94:97], v[200:203], v[18:33]
	v_exp_f32_e32 v227, v73
	ds_read_b64_tr_b16 v[102:103], v168 offset:0x600
	ds_read_b64_tr_b16 v[104:105], v168 offset:0xe00
	ds_read_b64_tr_b16 v[186:187], v168 offset:0x1600
	ds_read_b64_tr_b16 v[188:189], v168 offset:0x1e00
	ds_read_b64_tr_b16 v[190:191], v168 offset:0x2600
	ds_read_b64_tr_b16 v[192:193], v168 offset:0x2e00
	ds_read_b64_tr_b16 v[194:195], v168 offset:0x3600
	ds_read_b64_tr_b16 v[196:197], v168 offset:0x3e00
	s_waitcnt lgkmcnt(8)
	v_mfma_f32_32x32x16_bf16 v[34:49], v[82:85], v[98:101], v[34:49]
	v_exp_f32_e32 v228, v74
	v_mfma_f32_32x32x16_bf16 v[34:49], v[86:89], v[156:159], v[34:49]
	v_exp_f32_e32 v229, v75
	v_mfma_f32_32x32x16_bf16 v[34:49], v[90:93], v[178:181], v[34:49]
	v_exp_f32_e32 v230, v76
	v_exp_f32_e32 v178, v106
	v_exp_f32_e32 v179, v107
	v_exp_f32_e32 v180, v108
	v_exp_f32_e32 v181, v109
	v_mfma_f32_32x32x16_bf16 v[34:49], v[94:97], v[182:185], v[34:49]
	v_exp_f32_e32 v231, v77
	s_waitcnt lgkmcnt(0)
	v_mfma_f32_32x32x16_bf16 v[50:65], v[82:85], v[102:105], v[50:65]
	v_exp_f32_e32 v232, v78
	v_exp_f32_e32 v182, v110
	v_exp_f32_e32 v183, v111
	v_exp_f32_e32 v184, v112
	v_exp_f32_e32 v185, v113
	v_mfma_f32_32x32x16_bf16 v[50:65], v[86:89], v[186:189], v[50:65]
	v_exp_f32_e32 v233, v79
	v_mfma_f32_32x32x16_bf16 v[50:65], v[90:93], v[190:193], v[50:65]
	v_exp_f32_e32 v234, v80
	v_mfma_f32_32x32x16_bf16 v[50:65], v[94:97], v[194:197], v[50:65]
	v_exp_f32_e32 v235, v81
	s_waitcnt vmcnt(0)
	s_add_u32 s0, s0, 0x180000
	s_addc_u32 s1, s1, 0
	s_and_b64 vcc, exec, s[24:25]
	s_waitcnt vmcnt(0)
	s_barrier
	s_cbranch_vccnz .LBB0_2322
.LBB0_2320:
	v_lshl_add_u64 v[160:161], s[0:1], 0, v[150:151]
	s_mov_b32 m0, s55
	v_lshl_add_u64 v[82:83], v[160:161], 0, s[18:19]
	v_lshl_add_u64 v[156:157], s[0:1], 0, v[152:153]
	global_load_lds_dwordx4 v[82:83], off
	v_lshl_add_u64 v[82:83], v[156:157], 0, s[36:37]
	s_mov_b32 m0, s34
	v_lshl_add_u64 v[158:159], s[0:1], 0, v[154:155]
	global_load_lds_dwordx4 v[82:83], off
	v_lshl_add_u64 v[82:83], v[158:159], 0, s[36:37]
	s_mov_b32 m0, s54
	s_nop 0
	global_load_lds_dwordx4 v[82:83], off
	ds_read_b128 v[82:85], v172 offset:32768
	ds_read_b128 v[86:89], v172 offset:36864
	ds_read_b128 v[186:189], v173 offset:32768
	ds_read_b128 v[190:193], v173 offset:36864
	ds_read_b128 v[194:197], v174 offset:32768
	ds_read_b128 v[198:201], v174 offset:36864
	ds_read_b128 v[202:205], v175 offset:32768
	ds_read_b128 v[206:209], v175 offset:36864
	s_waitcnt lgkmcnt(0)
	v_mfma_f32_32x32x16_bf16 v[98:113], v[82:85], v[114:117], 0
	v_mfma_f32_32x32x16_bf16 v[82:97], v[86:89], v[114:117], 0
	v_mfma_f32_32x32x16_bf16 v[98:113], v[186:189], v[118:121], v[98:113]
	v_mfma_f32_32x32x16_bf16 v[82:97], v[190:193], v[118:121], v[82:97]
	v_add_f32_e32 v66, v139, v141
	v_add_f32_e32 v67, v220, v221
	v_mfma_f32_32x32x16_bf16 v[98:113], v[194:197], v[122:125], v[98:113]
	v_add_f32_e32 v66, v66, v143
	v_add_f32_e32 v67, v67, v222
	v_cvt_pk_bf16_f32 v68, v139, v141
	v_add_f32_e32 v66, v66, v145
	v_add_f32_e32 v67, v67, v223
	v_cvt_pk_bf16_f32 v69, v143, v145
	v_add_f32_e32 v66, v66, v147
	v_add_f32_e32 v67, v67, v224
	v_mfma_f32_32x32x16_bf16 v[82:97], v[198:201], v[122:125], v[82:97]
	v_add_f32_e32 v66, v66, v149
	v_add_f32_e32 v67, v67, v225
	v_cvt_pk_bf16_f32 v70, v147, v149
	v_add_f32_e32 v66, v66, v176
	v_add_f32_e32 v67, v67, v226
	v_cvt_pk_bf16_f32 v71, v176, v177
	v_add_f32_e32 v66, v66, v177
	v_add_f32_e32 v67, v67, v227
	s_nop 0
	v_add_f32_e32 v66, v66, v178
	v_add_f32_e32 v67, v67, v228
	v_add_f32_e32 v66, v66, v179
	v_add_f32_e32 v67, v67, v229
	v_add_f32_e32 v66, v66, v180
	v_add_f32_e32 v67, v67, v230
	v_add_f32_e32 v66, v66, v181
	v_add_f32_e32 v67, v67, v231
	v_add_f32_e32 v66, v66, v182
	v_add_f32_e32 v67, v67, v232
	v_add_f32_e32 v66, v66, v183
	v_add_f32_e32 v67, v67, v233
	v_add_f32_e32 v66, v66, v184
	v_add_f32_e32 v67, v67, v234
	v_add_f32_e32 v66, v66, v185
	v_add_f32_e32 v67, v67, v235
	v_add_f32_e32 v66, v66, v67
	v_mov_b32_e32 v67, v66
	s_nop 1
	v_permlane32_swap_b32_e32 v66, v67
	v_mfma_f32_32x32x16_bf16 v[98:113], v[202:205], v[126:129], v[98:113]
	v_cvt_pk_bf16_f32 v72, v178, v179
	v_cvt_pk_bf16_f32 v73, v180, v181
	v_cvt_pk_bf16_f32 v74, v182, v183
	v_cvt_pk_bf16_f32 v75, v184, v185
	v_cvt_pk_bf16_f32 v76, v220, v221
	v_cvt_pk_bf16_f32 v77, v222, v223
	v_cvt_pk_bf16_f32 v78, v224, v225
	v_mfma_f32_32x32x16_bf16 v[82:97], v[206:209], v[126:129], v[82:97]
	v_cvt_pk_bf16_f32 v79, v226, v227
	v_cvt_pk_bf16_f32 v176, v228, v229
	v_cvt_pk_bf16_f32 v177, v230, v231
	v_cvt_pk_bf16_f32 v178, v232, v233
	v_cvt_pk_bf16_f32 v179, v234, v235
	ds_read_b64_tr_b16 v[180:181], v169 offset:0
	ds_read_b64_tr_b16 v[182:183], v169 offset:0x800
	ds_read_b64_tr_b16 v[184:185], v169 offset:0x1000
	ds_read_b64_tr_b16 v[186:187], v169 offset:0x1800
	ds_read_b64_tr_b16 v[188:189], v169 offset:0x2000
	ds_read_b64_tr_b16 v[190:191], v169 offset:0x2800
	ds_read_b64_tr_b16 v[192:193], v169 offset:0x3000
	ds_read_b64_tr_b16 v[194:195], v169 offset:0x3800
	ds_read_b64_tr_b16 v[196:197], v169 offset:0x200
	ds_read_b64_tr_b16 v[198:199], v169 offset:0xa00
	ds_read_b64_tr_b16 v[200:201], v169 offset:0x1200
	ds_read_b64_tr_b16 v[202:203], v169 offset:0x1a00
	ds_read_b64_tr_b16 v[204:205], v169 offset:0x2200
	ds_read_b64_tr_b16 v[206:207], v169 offset:0x2a00
	ds_read_b64_tr_b16 v[208:209], v169 offset:0x3200
	ds_read_b64_tr_b16 v[210:211], v169 offset:0x3a00
	s_waitcnt lgkmcnt(8)
	s_nop 0
	v_mfma_f32_32x32x16_bf16 v[2:17], v[68:71], v[180:183], v[2:17]
	v_exp_f32_e32 v236, v98
	v_exp_f32_e32 v237, v99
	v_mfma_f32_32x32x16_bf16 v[2:17], v[72:75], v[184:187], v[2:17]
	v_exp_f32_e32 v238, v100
	v_exp_f32_e32 v239, v101
	v_mfma_f32_32x32x16_bf16 v[2:17], v[76:79], v[188:191], v[2:17]
	v_exp_f32_e32 v240, v102
	v_exp_f32_e32 v241, v103
	v_mfma_f32_32x32x16_bf16 v[2:17], v[176:179], v[192:195], v[2:17]
	v_exp_f32_e32 v244, v104
	v_exp_f32_e32 v245, v105
	ds_read_b64_tr_b16 v[180:181], v169 offset:0x400
	ds_read_b64_tr_b16 v[182:183], v169 offset:0xc00
	ds_read_b64_tr_b16 v[184:185], v169 offset:0x1400
	ds_read_b64_tr_b16 v[186:187], v169 offset:0x1c00
	ds_read_b64_tr_b16 v[188:189], v169 offset:0x2400
	ds_read_b64_tr_b16 v[190:191], v169 offset:0x2c00
	ds_read_b64_tr_b16 v[192:193], v169 offset:0x3400
	ds_read_b64_tr_b16 v[194:195], v169 offset:0x3c00
	s_waitcnt lgkmcnt(8)
	v_mfma_f32_32x32x16_bf16 v[18:33], v[68:71], v[196:199], v[18:33]
	v_exp_f32_e32 v246, v106
	v_exp_f32_e32 v247, v107
	v_mfma_f32_32x32x16_bf16 v[18:33], v[72:75], v[200:203], v[18:33]
	v_exp_f32_e32 v248, v108
	v_exp_f32_e32 v249, v109
	v_mfma_f32_32x32x16_bf16 v[18:33], v[76:79], v[204:207], v[18:33]
	v_exp_f32_e32 v250, v110
	v_exp_f32_e32 v251, v111
	v_mfma_f32_32x32x16_bf16 v[18:33], v[176:179], v[208:211], v[18:33]
	v_exp_f32_e32 v252, v112
	v_exp_f32_e32 v253, v113
	ds_read_b64_tr_b16 v[196:197], v169 offset:0x600
	ds_read_b64_tr_b16 v[198:199], v169 offset:0xe00
	ds_read_b64_tr_b16 v[200:201], v169 offset:0x1600
	ds_read_b64_tr_b16 v[202:203], v169 offset:0x1e00
	ds_read_b64_tr_b16 v[204:205], v169 offset:0x2600
	ds_read_b64_tr_b16 v[206:207], v169 offset:0x2e00
	ds_read_b64_tr_b16 v[208:209], v169 offset:0x3600
	ds_read_b64_tr_b16 v[210:211], v169 offset:0x3e00
	s_waitcnt lgkmcnt(8)
	v_mfma_f32_32x32x16_bf16 v[34:49], v[68:71], v[180:183], v[34:49]
	v_exp_f32_e32 v220, v82
	v_exp_f32_e32 v221, v83
	v_mfma_f32_32x32x16_bf16 v[34:49], v[72:75], v[184:187], v[34:49]
	v_exp_f32_e32 v222, v84
	v_exp_f32_e32 v223, v85
	v_mfma_f32_32x32x16_bf16 v[34:49], v[76:79], v[188:191], v[34:49]
	v_exp_f32_e32 v224, v86
	v_exp_f32_e32 v225, v87
	v_mfma_f32_32x32x16_bf16 v[34:49], v[176:179], v[192:195], v[34:49]
	v_exp_f32_e32 v226, v88
	v_exp_f32_e32 v227, v89
	s_waitcnt lgkmcnt(0)
	v_mfma_f32_32x32x16_bf16 v[50:65], v[68:71], v[196:199], v[50:65]
	v_exp_f32_e32 v228, v90
	v_exp_f32_e32 v229, v91
	v_mfma_f32_32x32x16_bf16 v[50:65], v[72:75], v[200:203], v[50:65]
	v_exp_f32_e32 v230, v92
	v_exp_f32_e32 v231, v93
	v_mfma_f32_32x32x16_bf16 v[50:65], v[76:79], v[204:207], v[50:65]
	v_exp_f32_e32 v232, v94
	v_exp_f32_e32 v233, v95
	v_mfma_f32_32x32x16_bf16 v[50:65], v[176:179], v[208:211], v[50:65]
	v_exp_f32_e32 v234, v96
	v_exp_f32_e32 v235, v97
	s_waitcnt vmcnt(0)
	s_cmpk_gt_u32 s52, 0x101
	s_cselect_b64 s[24:25], -1, 0
	s_and_b64 vcc, exec, s[24:25]
	s_waitcnt vmcnt(0)
	s_barrier
	s_cbranch_vccnz .LBB0_2319
	v_lshl_add_u64 v[68:69], v[160:161], 0, s[38:39]
	s_mov_b32 m0, s35
	s_nop 0
	global_load_lds_dwordx4 v[68:69], off
	s_branch .LBB0_2319
.LBB0_2322:
	v_exp_f32_e32 v82, v66
	v_add_f32_e32 v66, 0, v139
	v_add_f32_e32 v66, v141, v66
	v_add_f32_e32 v66, v143, v66
	v_add_f32_e32 v66, v145, v66
	v_add_f32_e32 v66, v147, v66
	v_add_f32_e32 v66, v149, v66
	v_add_f32_e32 v66, v176, v66
	v_add_f32_e32 v66, v177, v66
	v_add_f32_e32 v66, v178, v66
	v_add_f32_e32 v66, v179, v66
	v_add_f32_e32 v66, v180, v66
	v_add_f32_e32 v66, v181, v66
	v_add_f32_e32 v66, v182, v66
	v_exp_f32_e32 v83, v67
	v_add_f32_e32 v66, v183, v66
	v_exp_f32_e32 v84, v68
	v_add_f32_e32 v66, v184, v66
	v_exp_f32_e32 v85, v69
	v_add_f32_e32 v66, v185, v66
	v_exp_f32_e32 v86, v70
	v_add_f32_e32 v66, v82, v66
	v_exp_f32_e32 v87, v71
	v_add_f32_e32 v66, v83, v66
	v_exp_f32_e32 v88, v72
	v_add_f32_e32 v66, v84, v66
	v_exp_f32_e32 v89, v73
	v_add_f32_e32 v66, v85, v66
	v_exp_f32_e32 v90, v74
	v_add_f32_e32 v66, v86, v66
	v_exp_f32_e32 v91, v75
	v_add_f32_e32 v66, v87, v66
	v_exp_f32_e32 v92, v76
	v_add_f32_e32 v66, v88, v66
	v_exp_f32_e32 v93, v77
	v_add_f32_e32 v66, v89, v66
	v_exp_f32_e32 v94, v78
	v_add_f32_e32 v66, v90, v66
	v_exp_f32_e32 v95, v79
	v_add_f32_e32 v66, v91, v66
	v_exp_f32_e32 v96, v80
	v_add_f32_e32 v66, v92, v66
	v_exp_f32_e32 v97, v81
	v_add_f32_e32 v66, v93, v66
	v_add_f32_e32 v66, v94, v66
	v_add_f32_e32 v66, v95, v66
	v_add_f32_e32 v66, v96, v66
	s_lshl_b32 s0, s33, 2
	v_add_f32_e32 v66, v97, v66
	s_add_i32 s24, s0, 0
	v_mov_b32_e32 v67, v66
	s_add_i32 s24, s24, 0x1e000
	s_nop 0
	v_permlane32_swap_b32_e32 v66, v67
	v_cvt_pk_bf16_f32 v68, v139, v141
	v_cvt_pk_bf16_f32 v69, v143, v145
	v_cvt_pk_bf16_f32 v70, v147, v149
	v_cvt_pk_bf16_f32 v71, v176, v177
	v_cvt_pk_bf16_f32 v72, v178, v179
	v_cvt_pk_bf16_f32 v73, v180, v181
	v_cvt_pk_bf16_f32 v74, v182, v183
	v_cvt_pk_bf16_f32 v75, v184, v185
	v_cvt_pk_bf16_f32 v76, v82, v83
	v_cvt_pk_bf16_f32 v77, v84, v85
	v_cvt_pk_bf16_f32 v78, v86, v87
	v_cvt_pk_bf16_f32 v79, v88, v89
	v_cvt_pk_bf16_f32 v80, v90, v91
	v_cvt_pk_bf16_f32 v81, v92, v93
	v_cvt_pk_bf16_f32 v82, v94, v95
	v_cvt_pk_bf16_f32 v83, v96, v97
	ds_read_b64_tr_b16 v[84:85], v169 offset:0
	ds_read_b64_tr_b16 v[86:87], v169 offset:0x800
	ds_read_b64_tr_b16 v[88:89], v169 offset:0x1000
	ds_read_b64_tr_b16 v[90:91], v169 offset:0x1800
	ds_read_b64_tr_b16 v[92:93], v169 offset:0x2000
	ds_read_b64_tr_b16 v[94:95], v169 offset:0x2800
	ds_read_b64_tr_b16 v[96:97], v169 offset:0x3000
	ds_read_b64_tr_b16 v[98:99], v169 offset:0x3800
	s_waitcnt lgkmcnt(0)
	s_nop 0
	v_mfma_f32_32x32x16_bf16 v[2:17], v[68:71], v[84:87], v[2:17]
	ds_read_b64_tr_b16 v[84:85], v169 offset:0x200
	ds_read_b64_tr_b16 v[86:87], v169 offset:0xa00
	v_mfma_f32_32x32x16_bf16 v[2:17], v[72:75], v[88:91], v[2:17]
	ds_read_b64_tr_b16 v[88:89], v169 offset:0x1200
	ds_read_b64_tr_b16 v[90:91], v169 offset:0x1a00
	v_mfma_f32_32x32x16_bf16 v[2:17], v[76:79], v[92:95], v[2:17]
	ds_read_b64_tr_b16 v[92:93], v169 offset:0x2200
	ds_read_b64_tr_b16 v[94:95], v169 offset:0x2a00
	ds_read_b64_tr_b16 v[100:101], v169 offset:0x3200
	ds_read_b64_tr_b16 v[102:103], v169 offset:0x3a00
	s_waitcnt lgkmcnt(0)
	v_mfma_f32_32x32x16_bf16 v[2:17], v[80:83], v[96:99], v[2:17]
	v_mfma_f32_32x32x16_bf16 v[18:33], v[68:71], v[84:87], v[18:33]
	ds_read_b64_tr_b16 v[84:85], v169 offset:0x400
	ds_read_b64_tr_b16 v[86:87], v169 offset:0xc00
	v_mfma_f32_32x32x16_bf16 v[18:33], v[72:75], v[88:91], v[18:33]
	ds_read_b64_tr_b16 v[88:89], v169 offset:0x1400
	ds_read_b64_tr_b16 v[90:91], v169 offset:0x1c00
	v_mfma_f32_32x32x16_bf16 v[18:33], v[76:79], v[92:95], v[18:33]
	ds_read_b64_tr_b16 v[92:93], v169 offset:0x2400
	ds_read_b64_tr_b16 v[94:95], v169 offset:0x2c00
	ds_read_b64_tr_b16 v[96:97], v169 offset:0x3400
	ds_read_b64_tr_b16 v[98:99], v169 offset:0x3c00
	s_waitcnt lgkmcnt(0)
	v_mfma_f32_32x32x16_bf16 v[18:33], v[80:83], v[100:103], v[18:33]
	v_mfma_f32_32x32x16_bf16 v[34:49], v[68:71], v[84:87], v[34:49]
	ds_read_b64_tr_b16 v[84:85], v169 offset:0x600
	ds_read_b64_tr_b16 v[86:87], v169 offset:0xe00
	v_mfma_f32_32x32x16_bf16 v[34:49], v[72:75], v[88:91], v[34:49]
	ds_read_b64_tr_b16 v[88:89], v169 offset:0x1600
	ds_read_b64_tr_b16 v[90:91], v169 offset:0x1e00
	v_mfma_f32_32x32x16_bf16 v[34:49], v[76:79], v[92:95], v[34:49]
	ds_read_b64_tr_b16 v[92:93], v169 offset:0x2600
	ds_read_b64_tr_b16 v[94:95], v169 offset:0x2e00
	ds_read_b64_tr_b16 v[100:101], v169 offset:0x3600
	ds_read_b64_tr_b16 v[102:103], v169 offset:0x3e00
	s_waitcnt lgkmcnt(0)
	v_mfma_f32_32x32x16_bf16 v[34:49], v[80:83], v[96:99], v[34:49]
	v_mfma_f32_32x32x16_bf16 v[50:65], v[68:71], v[84:87], v[50:65]
	s_barrier
	v_mfma_f32_32x32x16_bf16 v[50:65], v[72:75], v[88:91], v[50:65]
	v_mfma_f32_32x32x16_bf16 v[50:65], v[76:79], v[92:95], v[50:65]
	v_mfma_f32_32x32x16_bf16 v[50:65], v[80:83], v[100:103], v[50:65]
	s_and_saveexec_b64 s[0:1], s[2:3]
	s_cbranch_execz .LBB0_2317
	v_add_f32_e32 v66, v66, v67
	v_add_f32_e32 v66, v135, v66
	v_lshl_add_u32 v67, v165, 2, s24
	ds_write_b32 v67, v66
	s_branch .LBB0_2317
